# GEMM K-loops: mid-block s_setprio 0/1 toggle pair removed from every 32-MFMA compute segment
# baseline (speedup 1.0000x reference)
; #define PG8_STAGE(bufoff, gbase, voff) do { _Pragma("unroll") for (int _i = 0; _i < 2; ++_i) \
;         __builtin_amdgcn_global_load_lds((const unsigned*)((const char*)(gbase) + (voff)[_i]), (PG8_LAS unsigned*)(lds + (bufoff) + ldsw + _i * 8192), 16, 0, 0); } while (0)
; #define PG8_LDA(dst, b, h) do { _Pragma("unroll") for (int m = 0; m < 4; ++m) _Pragma("unroll") for (int k = 0; k < 2; ++k) dst[m][k] = *(const PG8_LAS bf16x8*)(lds + PG8_SA(b, h) + aoff + m * 2048 + k * 1024); } while (0)
; #define PG8_LDB(dst, b, h) do { _Pragma("unroll") for (int n = 0; n < 2; ++n) _Pragma("unroll") for (int k = 0; k < 2; ++k) dst[n][k] = *(const PG8_LAS bf16x8*)(lds + PG8_SB(b, h) + boff + n * 2048 + k * 1024); } while (0)
; #define PG8_MMA(ai, bj, At, Bt) do { __builtin_amdgcn_s_setprio(1); _Pragma("unroll") for (int m = 0; m < 4; ++m) _Pragma("unroll") for (int n = 0; n < 2; ++n) _Pragma("unroll") for (int k = 0; k < 2; ++k) \
;         acc[ai][bj][m][n] = __builtin_amdgcn_mfma_f32_16x16x32_bf16(Bt[n][k], At[m][k], acc[ai][bj][m][n], 0, 0, 0); __builtin_amdgcn_s_setprio(0); } while (0)
; #define PG8_WAIT_V(n) asm volatile("s_waitcnt vmcnt(" #n ")" ::: "memory")
; #define PG8_WAIT_L(n) asm volatile("s_waitcnt lgkmcnt(" #n ")" ::: "memory")
; #define PG8_BAR __builtin_amdgcn_s_barrier()
; #define PG8_SCHED __builtin_amdgcn_sched_barrier(0)
; template <class Epi, class Sched, bool ALIGN_EPI = false, bool SP2 = false>
; __device__ __forceinline__ void gemm_phase(PG8_LAS unsigned char* lds, const Gemm g, const Sched& S, const Epi& E) {
;     ...
;             PG8_LDB(B0, 0, 0); PG8_LDB(B1, 0, 1); PG8_SCHED; PG8_LDA(At, 0, 0); PG8_STAGE(PG8_SA(1, 1), a1 + hstep, voffA);
;             PG8_WAIT_V(8); PG8_WAIT_L(0); PG8_BAR; PG8_MMA(0, 0, At, B0); PG8_MMA(0, 1, At, B1); PG8_BAR; PG8_SCHED;
;             PG8_LDA(At, 0, 1); PG8_STAGE(PG8_SB(0, 0), b2, voffB); PG8_STAGE(PG8_SB(0, 1), b2 + hstep, voffB); PG8_STAGE(PG8_SA(0, 0), a2, voffA);
.LBB0_341:
	ds_read_b128 v[146:149], v159
	ds_read_b128 v[150:153], v159 offset:1024
	ds_read_b128 v[164:167], v159 offset:2048
	ds_read_b128 v[168:171], v159 offset:3072
	ds_read_b128 v[172:175], v160
	ds_read_b128 v[176:179], v160 offset:1024
	ds_read_b128 v[180:183], v160 offset:2048
	ds_read_b128 v[184:187], v160 offset:3072
	s_add_u32 s14, s10, 0xfff80080
	s_addc_u32 s15, s11, -1
	s_cmp_eq_u32 s48, 28
	s_cselect_b32 s87, s7, s15
	s_cselect_b32 s86, s9, s14
	s_cselect_b32 s15, s12, s47
	s_cselect_b32 s14, s45, s46
	v_lshl_add_u64 v[154:155], s[10:11], 0, v[136:137]
	s_add_i32 m0, s91, 0xc000
	ds_read_b128 v[188:191], v161
	ds_read_b128 v[192:195], v161 offset:1024
	ds_read_b128 v[196:199], v161 offset:2048
	ds_read_b128 v[200:203], v161 offset:3072
	ds_read_b128 v[204:207], v161 offset:4096
	ds_read_b128 v[208:211], v161 offset:5120
	ds_read_b128 v[212:215], v161 offset:6144
	ds_read_b128 v[216:219], v161 offset:7168
	global_load_lds_dwordx4 v[154:155], off
	v_lshl_add_u64 v[154:155], s[10:11], 0, v[138:139]
	s_add_i32 m0, s91, 0xe000
	s_nop 0
	global_load_lds_dwordx4 v[154:155], off
	s_waitcnt vmcnt(8)
	s_waitcnt lgkmcnt(0)
	s_barrier
	s_setprio 1
	s_waitcnt lgkmcnt(0)
	v_mfma_f32_16x16x32_bf16 v[124:127], v[146:149], v[188:191], v[124:127]
	v_mfma_f32_16x16x32_bf16 v[120:123], v[164:167], v[188:191], v[120:123]
	v_mfma_f32_16x16x32_bf16 v[108:111], v[146:149], v[196:199], v[108:111]
	v_mfma_f32_16x16x32_bf16 v[104:107], v[164:167], v[196:199], v[104:107]
	v_mfma_f32_16x16x32_bf16 v[92:95], v[146:149], v[204:207], v[92:95]
	v_mfma_f32_16x16x32_bf16 v[88:91], v[164:167], v[204:207], v[88:91]
	v_mfma_f32_16x16x32_bf16 v[76:79], v[146:149], v[212:215], v[76:79]
	v_mfma_f32_16x16x32_bf16 v[72:75], v[164:167], v[212:215], v[72:75]
	v_mfma_f32_16x16x32_bf16 v[124:127], v[150:153], v[192:195], v[124:127]
	v_mfma_f32_16x16x32_bf16 v[120:123], v[168:171], v[192:195], v[120:123]
	v_mfma_f32_16x16x32_bf16 v[108:111], v[150:153], v[200:203], v[108:111]
	v_mfma_f32_16x16x32_bf16 v[104:107], v[168:171], v[200:203], v[104:107]
	v_mfma_f32_16x16x32_bf16 v[92:95], v[150:153], v[208:211], v[92:95]
	v_mfma_f32_16x16x32_bf16 v[88:91], v[168:171], v[208:211], v[88:91]
	v_mfma_f32_16x16x32_bf16 v[76:79], v[150:153], v[216:219], v[76:79]
	v_mfma_f32_16x16x32_bf16 v[72:75], v[168:171], v[216:219], v[72:75]
	v_mfma_f32_16x16x32_bf16 v[116:119], v[172:175], v[188:191], v[116:119]
	v_mfma_f32_16x16x32_bf16 v[112:115], v[180:183], v[188:191], v[112:115]
	v_mfma_f32_16x16x32_bf16 v[100:103], v[172:175], v[196:199], v[100:103]
	v_mfma_f32_16x16x32_bf16 v[96:99], v[180:183], v[196:199], v[96:99]
	v_mfma_f32_16x16x32_bf16 v[84:87], v[172:175], v[204:207], v[84:87]
	v_mfma_f32_16x16x32_bf16 v[80:83], v[180:183], v[204:207], v[80:83]
	v_mfma_f32_16x16x32_bf16 v[68:71], v[172:175], v[212:215], v[68:71]
	v_mfma_f32_16x16x32_bf16 v[64:67], v[180:183], v[212:215], v[64:67]
	v_mfma_f32_16x16x32_bf16 v[116:119], v[176:179], v[192:195], v[116:119]
	v_mfma_f32_16x16x32_bf16 v[112:115], v[184:187], v[192:195], v[112:115]
	v_mfma_f32_16x16x32_bf16 v[100:103], v[176:179], v[200:203], v[100:103]
	v_mfma_f32_16x16x32_bf16 v[96:99], v[184:187], v[200:203], v[96:99]
	v_mfma_f32_16x16x32_bf16 v[84:87], v[176:179], v[208:211], v[84:87]
	v_mfma_f32_16x16x32_bf16 v[80:83], v[184:187], v[208:211], v[80:83]
	v_mfma_f32_16x16x32_bf16 v[68:71], v[176:179], v[216:219], v[68:71]
	v_mfma_f32_16x16x32_bf16 v[64:67], v[184:187], v[216:219], v[64:67]
	s_setprio 0
	s_barrier
	s_add_i32 s49, s42, s85
	v_lshl_add_u64 v[154:155], s[14:15], 0, v[130:131]
	s_mov_b32 m0, s49
	ds_read_b128 v[188:191], v161 offset:16384
	ds_read_b128 v[192:195], v161 offset:17408
	ds_read_b128 v[196:199], v161 offset:18432
	ds_read_b128 v[200:203], v161 offset:19456
	ds_read_b128 v[204:207], v161 offset:20480
	ds_read_b128 v[208:211], v161 offset:21504
	ds_read_b128 v[212:215], v161 offset:22528
	ds_read_b128 v[216:219], v161 offset:23552
	global_load_lds_dwordx4 v[154:155], off
	s_add_i32 m0, s49, 0x2000
	s_add_u32 s50, s14, 0x80000
	v_lshl_add_u64 v[220:221], s[14:15], 0, v[134:135]
	s_addc_u32 s51, s15, 0
	s_add_i32 s49, s43, s85
	global_load_lds_dwordx4 v[220:221], off
	v_lshl_add_u64 v[222:223], s[50:51], 0, v[130:131]
	s_mov_b32 m0, s49
	v_lshl_add_u64 v[224:225], s[86:87], 0, v[132:133]
	global_load_lds_dwordx4 v[222:223], off
	v_lshl_add_u64 v[222:223], s[50:51], 0, v[134:135]
	s_add_i32 m0, s49, 0x2000
	s_nop 0
	global_load_lds_dwordx4 v[222:223], off
	v_lshl_add_u64 v[222:223], s[86:87], 0, v[128:129]
	s_mov_b32 m0, s91
	s_nop 0
	global_load_lds_dwordx4 v[222:223], off
	s_mov_b32 m0, s93
	s_nop 0
	global_load_lds_dwordx4 v[224:225], off
	s_waitcnt vmcnt(8)
	s_waitcnt lgkmcnt(0)
	s_barrier
; #define PG8_STAGE(bufoff, gbase, voff) do { _Pragma("unroll") for (int _i = 0; _i < 2; ++_i) \
;         __builtin_amdgcn_global_load_lds((const unsigned*)((const char*)(gbase) + (voff)[_i]), (PG8_LAS unsigned*)(lds + (bufoff) + ldsw + _i * 8192), 16, 0, 0); } while (0)
; #define PG8_LDA(dst, b, h) do { _Pragma("unroll") for (int m = 0; m < 4; ++m) _Pragma("unroll") for (int k = 0; k < 2; ++k) dst[m][k] = *(const PG8_LAS bf16x8*)(lds + PG8_SA(b, h) + aoff + m * 2048 + k * 1024); } while (0)
; #define PG8_LDB(dst, b, h) do { _Pragma("unroll") for (int n = 0; n < 2; ++n) _Pragma("unroll") for (int k = 0; k < 2; ++k) dst[n][k] = *(const PG8_LAS bf16x8*)(lds + PG8_SB(b, h) + boff + n * 2048 + k * 1024); } while (0)
; #define PG8_MMA(ai, bj, At, Bt) do { __builtin_amdgcn_s_setprio(1); _Pragma("unroll") for (int m = 0; m < 4; ++m) _Pragma("unroll") for (int n = 0; n < 2; ++n) _Pragma("unroll") for (int k = 0; k < 2; ++k) \
;         acc[ai][bj][m][n] = __builtin_amdgcn_mfma_f32_16x16x32_bf16(Bt[n][k], At[m][k], acc[ai][bj][m][n], 0, 0, 0); __builtin_amdgcn_s_setprio(0); } while (0)
; #define PG8_WAIT_V(n) asm volatile("s_waitcnt vmcnt(" #n ")" ::: "memory")
; #define PG8_WAIT_L(n) asm volatile("s_waitcnt lgkmcnt(" #n ")" ::: "memory")
; #define PG8_BAR __builtin_amdgcn_s_barrier()
; #define PG8_SCHED __builtin_amdgcn_sched_barrier(0)
; template <class Epi, class Sched, bool ALIGN_EPI = false, bool SP2 = false>
; __device__ __forceinline__ void gemm_phase(PG8_LAS unsigned char* lds, const Gemm g, const Sched& S, const Epi& E) {
;     ...
;             PG8_LDA(At, 0, 1); PG8_STAGE(PG8_SB(0, 0), b2, voffB); PG8_STAGE(PG8_SB(0, 1), b2 + hstep, voffB); PG8_STAGE(PG8_SA(0, 0), a2, voffA);
;             PG8_WAIT_V(8); PG8_WAIT_L(0); PG8_BAR; PG8_MMA(1, 0, At, B0); PG8_MMA(1, 1, At, B1); PG8_BAR; PG8_SCHED;
;             PG8_LDB(B0, 1, 0); PG8_LDB(B1, 1, 1); PG8_SCHED; PG8_LDA(At, 1, 0); PG8_STAGE(PG8_SA(0, 1), a2 + hstep, voffA);
;             PG8_WAIT_V(8); PG8_WAIT_L(0); PG8_BAR; PG8_MMA(0, 0, At, B0); PG8_MMA(0, 1, At, B1); PG8_BAR; PG8_SCHED;
	s_setprio 1
	s_waitcnt lgkmcnt(0)
	v_mfma_f32_16x16x32_bf16 v[60:63], v[146:149], v[188:191], v[60:63]
	v_mfma_f32_16x16x32_bf16 v[56:59], v[164:167], v[188:191], v[56:59]
	v_mfma_f32_16x16x32_bf16 v[44:47], v[146:149], v[196:199], v[44:47]
	v_mfma_f32_16x16x32_bf16 v[40:43], v[164:167], v[196:199], v[40:43]
	v_mfma_f32_16x16x32_bf16 v[28:31], v[146:149], v[204:207], v[28:31]
	v_mfma_f32_16x16x32_bf16 v[24:27], v[164:167], v[204:207], v[24:27]
	v_mfma_f32_16x16x32_bf16 v[12:15], v[146:149], v[212:215], v[12:15]
	v_mfma_f32_16x16x32_bf16 v[8:11], v[164:167], v[212:215], v[8:11]
	v_mfma_f32_16x16x32_bf16 v[60:63], v[150:153], v[192:195], v[60:63]
	v_mfma_f32_16x16x32_bf16 v[56:59], v[168:171], v[192:195], v[56:59]
	v_mfma_f32_16x16x32_bf16 v[44:47], v[150:153], v[200:203], v[44:47]
	v_mfma_f32_16x16x32_bf16 v[40:43], v[168:171], v[200:203], v[40:43]
	v_mfma_f32_16x16x32_bf16 v[28:31], v[150:153], v[208:211], v[28:31]
	v_mfma_f32_16x16x32_bf16 v[24:27], v[168:171], v[208:211], v[24:27]
	v_mfma_f32_16x16x32_bf16 v[12:15], v[150:153], v[216:219], v[12:15]
	v_mfma_f32_16x16x32_bf16 v[8:11], v[168:171], v[216:219], v[8:11]
	v_mfma_f32_16x16x32_bf16 v[52:55], v[172:175], v[188:191], v[52:55]
	v_mfma_f32_16x16x32_bf16 v[48:51], v[180:183], v[188:191], v[48:51]
	v_mfma_f32_16x16x32_bf16 v[36:39], v[172:175], v[196:199], v[36:39]
	v_mfma_f32_16x16x32_bf16 v[32:35], v[180:183], v[196:199], v[32:35]
	v_mfma_f32_16x16x32_bf16 v[20:23], v[172:175], v[204:207], v[20:23]
	v_mfma_f32_16x16x32_bf16 v[16:19], v[180:183], v[204:207], v[16:19]
	v_mfma_f32_16x16x32_bf16 v[4:7], v[172:175], v[212:215], v[4:7]
	v_mfma_f32_16x16x32_bf16 v[0:3], v[180:183], v[212:215], v[0:3]
	v_mfma_f32_16x16x32_bf16 v[52:55], v[176:179], v[192:195], v[52:55]
	v_mfma_f32_16x16x32_bf16 v[48:51], v[184:187], v[192:195], v[48:51]
	v_mfma_f32_16x16x32_bf16 v[36:39], v[176:179], v[200:203], v[36:39]
	v_mfma_f32_16x16x32_bf16 v[32:35], v[184:187], v[200:203], v[32:35]
	v_mfma_f32_16x16x32_bf16 v[20:23], v[176:179], v[208:211], v[20:23]
	v_mfma_f32_16x16x32_bf16 v[16:19], v[184:187], v[208:211], v[16:19]
	v_mfma_f32_16x16x32_bf16 v[4:7], v[176:179], v[216:219], v[4:7]
	v_mfma_f32_16x16x32_bf16 v[0:3], v[184:187], v[216:219], v[0:3]
	s_setprio 0
	s_barrier
	s_add_i32 s49, 0, 0x18000
	v_add_u32_e32 v163, s49, v158
	s_add_i32 s69, 0, 0x1c000
	ds_read_b128 v[146:149], v163
	ds_read_b128 v[150:153], v163 offset:1024
	ds_read_b128 v[164:167], v163 offset:2048
	ds_read_b128 v[168:171], v163 offset:3072
	v_add_u32_e32 v163, s69, v158
	ds_read_b128 v[172:175], v163
	ds_read_b128 v[176:179], v163 offset:1024
	ds_read_b128 v[180:183], v163 offset:2048
	ds_read_b128 v[184:187], v163 offset:3072
	s_add_u32 s50, s86, 0x80000
	s_addc_u32 s51, s87, 0
	s_mov_b32 m0, s95
	v_lshl_add_u64 v[226:227], s[50:51], 0, v[128:129]
	ds_read_b128 v[188:191], v161 offset:32768
	ds_read_b128 v[192:195], v161 offset:33792
	ds_read_b128 v[196:199], v161 offset:34816
	ds_read_b128 v[200:203], v161 offset:35840
	ds_read_b128 v[204:207], v161 offset:36864
	ds_read_b128 v[208:211], v161 offset:37888
	ds_read_b128 v[212:215], v161 offset:38912
	ds_read_b128 v[216:219], v161 offset:39936
	global_load_lds_dwordx4 v[226:227], off
	v_lshl_add_u64 v[226:227], s[50:51], 0, v[132:133]
	s_mov_b32 m0, s97
	s_nop 0
	global_load_lds_dwordx4 v[226:227], off
	s_waitcnt vmcnt(8)
	s_waitcnt lgkmcnt(0)
	s_barrier
	s_setprio 1
	s_waitcnt lgkmcnt(0)
	v_mfma_f32_16x16x32_bf16 v[124:127], v[146:149], v[188:191], v[124:127]
	v_mfma_f32_16x16x32_bf16 v[120:123], v[164:167], v[188:191], v[120:123]
	v_mfma_f32_16x16x32_bf16 v[108:111], v[146:149], v[196:199], v[108:111]
	v_mfma_f32_16x16x32_bf16 v[104:107], v[164:167], v[196:199], v[104:107]
	v_mfma_f32_16x16x32_bf16 v[92:95], v[146:149], v[204:207], v[92:95]
	v_mfma_f32_16x16x32_bf16 v[88:91], v[164:167], v[204:207], v[88:91]
	v_mfma_f32_16x16x32_bf16 v[76:79], v[146:149], v[212:215], v[76:79]
	v_mfma_f32_16x16x32_bf16 v[72:75], v[164:167], v[212:215], v[72:75]
	v_mfma_f32_16x16x32_bf16 v[124:127], v[150:153], v[192:195], v[124:127]
	v_mfma_f32_16x16x32_bf16 v[120:123], v[168:171], v[192:195], v[120:123]
	v_mfma_f32_16x16x32_bf16 v[108:111], v[150:153], v[200:203], v[108:111]
	v_mfma_f32_16x16x32_bf16 v[104:107], v[168:171], v[200:203], v[104:107]
	v_mfma_f32_16x16x32_bf16 v[92:95], v[150:153], v[208:211], v[92:95]
	v_mfma_f32_16x16x32_bf16 v[88:91], v[168:171], v[208:211], v[88:91]
	v_mfma_f32_16x16x32_bf16 v[76:79], v[150:153], v[216:219], v[76:79]
	v_mfma_f32_16x16x32_bf16 v[72:75], v[168:171], v[216:219], v[72:75]
	v_mfma_f32_16x16x32_bf16 v[116:119], v[172:175], v[188:191], v[116:119]
	v_mfma_f32_16x16x32_bf16 v[112:115], v[180:183], v[188:191], v[112:115]
	v_mfma_f32_16x16x32_bf16 v[100:103], v[172:175], v[196:199], v[100:103]
	v_mfma_f32_16x16x32_bf16 v[96:99], v[180:183], v[196:199], v[96:99]
	v_mfma_f32_16x16x32_bf16 v[84:87], v[172:175], v[204:207], v[84:87]
	v_mfma_f32_16x16x32_bf16 v[80:83], v[180:183], v[204:207], v[80:83]
	v_mfma_f32_16x16x32_bf16 v[68:71], v[172:175], v[212:215], v[68:71]
	v_mfma_f32_16x16x32_bf16 v[64:67], v[180:183], v[212:215], v[64:67]
	v_mfma_f32_16x16x32_bf16 v[116:119], v[176:179], v[192:195], v[116:119]
	v_mfma_f32_16x16x32_bf16 v[112:115], v[184:187], v[192:195], v[112:115]
	v_mfma_f32_16x16x32_bf16 v[100:103], v[176:179], v[200:203], v[100:103]
	v_mfma_f32_16x16x32_bf16 v[96:99], v[184:187], v[200:203], v[96:99]
	v_mfma_f32_16x16x32_bf16 v[84:87], v[176:179], v[208:211], v[84:87]
	v_mfma_f32_16x16x32_bf16 v[80:83], v[184:187], v[208:211], v[80:83]
	v_mfma_f32_16x16x32_bf16 v[68:71], v[176:179], v[216:219], v[68:71]
	v_mfma_f32_16x16x32_bf16 v[64:67], v[184:187], v[216:219], v[64:67]
	s_setprio 0
	s_barrier
; #define PG8_STAGE(bufoff, gbase, voff) do { _Pragma("unroll") for (int _i = 0; _i < 2; ++_i) \
;         __builtin_amdgcn_global_load_lds((const unsigned*)((const char*)(gbase) + (voff)[_i]), (PG8_LAS unsigned*)(lds + (bufoff) + ldsw + _i * 8192), 16, 0, 0); } while (0)
; #define PG8_LDA(dst, b, h) do { _Pragma("unroll") for (int m = 0; m < 4; ++m) _Pragma("unroll") for (int k = 0; k < 2; ++k) dst[m][k] = *(const PG8_LAS bf16x8*)(lds + PG8_SA(b, h) + aoff + m * 2048 + k * 1024); } while (0)
; #define PG8_MMA(ai, bj, At, Bt) do { __builtin_amdgcn_s_setprio(1); _Pragma("unroll") for (int m = 0; m < 4; ++m) _Pragma("unroll") for (int n = 0; n < 2; ++n) _Pragma("unroll") for (int k = 0; k < 2; ++k) \
;         acc[ai][bj][m][n] = __builtin_amdgcn_mfma_f32_16x16x32_bf16(Bt[n][k], At[m][k], acc[ai][bj][m][n], 0, 0, 0); __builtin_amdgcn_s_setprio(0); } while (0)
; #define PG8_WAIT_V(n) asm volatile("s_waitcnt vmcnt(" #n ")" ::: "memory")
; #define PG8_WAIT_L(n) asm volatile("s_waitcnt lgkmcnt(" #n ")" ::: "memory")
; #define PG8_BAR __builtin_amdgcn_s_barrier()
; #define PG8_SCHED __builtin_amdgcn_sched_barrier(0)
; template <class Epi, class Sched, bool ALIGN_EPI = false, bool SP2 = false>
; __device__ __forceinline__ void gemm_phase(PG8_LAS unsigned char* lds, const Gemm g, const Sched& S, const Epi& E) {
;     ...
;             PG8_LDA(At, 1, 1); PG8_STAGE(PG8_SB(1, 0), b3, voffB); PG8_STAGE(PG8_SB(1, 1), b3 + hstep, voffB); PG8_STAGE(PG8_SA(1, 0), a3, voffA);
;             PG8_WAIT_V(8); PG8_WAIT_L(0); PG8_BAR; PG8_MMA(1, 0, At, B0); PG8_MMA(1, 1, At, B1); PG8_BAR; PG8_SCHED;
	s_add_i32 s49, s49, s85
	v_lshl_add_u64 v[154:155], v[154:155], 0, s[82:83]
	s_mov_b32 m0, s49
	ds_read_b128 v[188:191], v161 offset:49152
	ds_read_b128 v[192:195], v161 offset:50176
	ds_read_b128 v[196:199], v161 offset:51200
	ds_read_b128 v[200:203], v161 offset:52224
	ds_read_b128 v[204:207], v161 offset:53248
	ds_read_b128 v[208:211], v161 offset:54272
	ds_read_b128 v[212:215], v161 offset:55296
	ds_read_b128 v[216:219], v161 offset:56320
	global_load_lds_dwordx4 v[154:155], off
	s_add_i32 m0, s49, 0x2000
	s_add_u32 s14, s14, 0x80080
	v_lshl_add_u64 v[154:155], v[220:221], 0, s[82:83]
	s_addc_u32 s15, s15, 0
	s_add_i32 s49, s69, s85
	global_load_lds_dwordx4 v[154:155], off
	v_lshl_add_u64 v[154:155], s[14:15], 0, v[130:131]
	s_mov_b32 m0, s49
	s_nop 0
	global_load_lds_dwordx4 v[154:155], off
	v_lshl_add_u64 v[154:155], s[14:15], 0, v[134:135]
	s_add_i32 m0, s49, 0x2000
	s_nop 0
	global_load_lds_dwordx4 v[154:155], off
	v_lshl_add_u64 v[154:155], v[222:223], 0, s[82:83]
	s_mov_b32 m0, s39
	s_nop 0
	global_load_lds_dwordx4 v[154:155], off
	v_lshl_add_u64 v[154:155], v[224:225], 0, s[82:83]
	s_mov_b32 m0, s40
	s_nop 0
	global_load_lds_dwordx4 v[154:155], off
	s_waitcnt vmcnt(8)
	s_waitcnt lgkmcnt(0)
	s_barrier
	s_setprio 1
	s_waitcnt lgkmcnt(0)
	v_mfma_f32_16x16x32_bf16 v[60:63], v[146:149], v[188:191], v[60:63]
	v_mfma_f32_16x16x32_bf16 v[56:59], v[164:167], v[188:191], v[56:59]
	v_mfma_f32_16x16x32_bf16 v[44:47], v[146:149], v[196:199], v[44:47]
	v_mfma_f32_16x16x32_bf16 v[40:43], v[164:167], v[196:199], v[40:43]
	v_mfma_f32_16x16x32_bf16 v[28:31], v[146:149], v[204:207], v[28:31]
	v_mfma_f32_16x16x32_bf16 v[24:27], v[164:167], v[204:207], v[24:27]
	v_mfma_f32_16x16x32_bf16 v[12:15], v[146:149], v[212:215], v[12:15]
	v_mfma_f32_16x16x32_bf16 v[8:11], v[164:167], v[212:215], v[8:11]
	v_mfma_f32_16x16x32_bf16 v[60:63], v[150:153], v[192:195], v[60:63]
	v_mfma_f32_16x16x32_bf16 v[56:59], v[168:171], v[192:195], v[56:59]
	v_mfma_f32_16x16x32_bf16 v[44:47], v[150:153], v[200:203], v[44:47]
	v_mfma_f32_16x16x32_bf16 v[40:43], v[168:171], v[200:203], v[40:43]
	v_mfma_f32_16x16x32_bf16 v[28:31], v[150:153], v[208:211], v[28:31]
	v_mfma_f32_16x16x32_bf16 v[24:27], v[168:171], v[208:211], v[24:27]
	v_mfma_f32_16x16x32_bf16 v[12:15], v[150:153], v[216:219], v[12:15]
	v_mfma_f32_16x16x32_bf16 v[8:11], v[168:171], v[216:219], v[8:11]
	v_mfma_f32_16x16x32_bf16 v[52:55], v[172:175], v[188:191], v[52:55]
	v_mfma_f32_16x16x32_bf16 v[48:51], v[180:183], v[188:191], v[48:51]
	v_mfma_f32_16x16x32_bf16 v[36:39], v[172:175], v[196:199], v[36:39]
	v_mfma_f32_16x16x32_bf16 v[32:35], v[180:183], v[196:199], v[32:35]
	v_mfma_f32_16x16x32_bf16 v[20:23], v[172:175], v[204:207], v[20:23]
	v_mfma_f32_16x16x32_bf16 v[16:19], v[180:183], v[204:207], v[16:19]
	v_mfma_f32_16x16x32_bf16 v[4:7], v[172:175], v[212:215], v[4:7]
	v_mfma_f32_16x16x32_bf16 v[0:3], v[180:183], v[212:215], v[0:3]
	v_mfma_f32_16x16x32_bf16 v[52:55], v[176:179], v[192:195], v[52:55]
	v_mfma_f32_16x16x32_bf16 v[48:51], v[184:187], v[192:195], v[48:51]
	v_mfma_f32_16x16x32_bf16 v[36:39], v[176:179], v[200:203], v[36:39]
	v_mfma_f32_16x16x32_bf16 v[32:35], v[184:187], v[200:203], v[32:35]
	v_mfma_f32_16x16x32_bf16 v[20:23], v[176:179], v[208:211], v[20:23]
	v_mfma_f32_16x16x32_bf16 v[16:19], v[184:187], v[208:211], v[16:19]
	v_mfma_f32_16x16x32_bf16 v[4:7], v[176:179], v[216:219], v[4:7]
	v_mfma_f32_16x16x32_bf16 v[0:3], v[184:187], v[216:219], v[0:3]
	s_setprio 0
	s_barrier
	s_add_i32 s48, s48, 2
	s_add_u32 s10, s10, 0x100
	s_addc_u32 s11, s11, 0
	s_add_u32 s46, s46, 0x100
	s_addc_u32 s47, s47, 0
	s_cmp_gt_u32 s48, 29
	s_cbranch_scc0 .LBB0_341
	s_and_b64 vcc, exec, s[88:89]
	s_cbranch_vccz .LBB0_344
	s_barrier

; #define PG8_STAGE(bufoff, gbase, voff) do { _Pragma("unroll") for (int _i = 0; _i < 2; ++_i) \
;         __builtin_amdgcn_global_load_lds((const unsigned*)((const char*)(gbase) + (voff)[_i]), (PG8_LAS unsigned*)(lds + (bufoff) + ldsw + _i * 8192), 16, 0, 0); } while (0)
; #define PG8_LDA(dst, b, h) do { _Pragma("unroll") for (int m = 0; m < 4; ++m) _Pragma("unroll") for (int k = 0; k < 2; ++k) dst[m][k] = *(const PG8_LAS bf16x8*)(lds + PG8_SA(b, h) + aoff + m * 2048 + k * 1024); } while (0)
; #define PG8_LDB(dst, b, h) do { _Pragma("unroll") for (int n = 0; n < 2; ++n) _Pragma("unroll") for (int k = 0; k < 2; ++k) dst[n][k] = *(const PG8_LAS bf16x8*)(lds + PG8_SB(b, h) + boff + n * 2048 + k * 1024); } while (0)
; #define PG8_MMA(ai, bj, At, Bt) do { __builtin_amdgcn_s_setprio(1); _Pragma("unroll") for (int m = 0; m < 4; ++m) _Pragma("unroll") for (int n = 0; n < 2; ++n) _Pragma("unroll") for (int k = 0; k < 2; ++k) \
;         acc[ai][bj][m][n] = __builtin_amdgcn_mfma_f32_16x16x32_bf16(Bt[n][k], At[m][k], acc[ai][bj][m][n], 0, 0, 0); __builtin_amdgcn_s_setprio(0); } while (0)
; #define PG8_WAIT_V(n) asm volatile("s_waitcnt vmcnt(" #n ")" ::: "memory")
; #define PG8_WAIT_L(n) asm volatile("s_waitcnt lgkmcnt(" #n ")" ::: "memory")
; template <class Epi, class Sched, bool ALIGN_EPI = false, bool SP2 = false>
; __device__ __forceinline__ void gemm_phase(PG8_LAS unsigned char* lds, const Gemm g, const Sched& S, const Epi& E) {
;     ...
;             const bool last = (t == nt - 2);
;             const char* a1 = cA + (size_t)(t + 1) * kstep;
;             const char* a2 = last ? nA : cA + (size_t)(t + 2) * kstep; const char* b2 = last ? nB : cB + (size_t)(t + 2) * kstep;
;             const char* a3 = a2 + kstep; const char* b3 = b2 + kstep;
;             if (last && has_next) S.a_ready(nxt);
;             if constexpr (SP2) {
;             PG8_LDB(B0, 0, 0); PG8_LDB(B1, 0, 1); PG8_SCHED; PG8_LDA(At, 0, 0); PG8_STAGE(PG8_SA(1, 1), a1 + hstep, voffA);
;             PG8_WAIT_V(8); PG8_WAIT_L(0); PG8_BAR; PG8_MMA(0, 0, At, B0); PG8_MMA(0, 1, At, B1); PG8_BAR; PG8_SCHED;
;             PG8_LDA(At, 0, 1); PG8_STAGE(PG8_SB(0, 0), b2, voffB); PG8_STAGE(PG8_SB(0, 1), b2 + hstep, voffB); PG8_STAGE(PG8_SA(0, 0), a2, voffA);
;             PG8_WAIT_V(8); PG8_WAIT_L(0); PG8_BAR; PG8_MMA(1, 0, At, B0); PG8_MMA(1, 1, At, B1); PG8_BAR; PG8_SCHED;
.LBB0_919:
	ds_read_b128 v[128:131], v187
	ds_read_b128 v[132:135], v187 offset:1024
	ds_read_b128 v[154:157], v187 offset:2048
	ds_read_b128 v[158:161], v187 offset:3072
	ds_read_b128 v[162:165], v188
	ds_read_b128 v[166:169], v188 offset:1024
	ds_read_b128 v[170:173], v188 offset:2048
	ds_read_b128 v[174:177], v188 offset:3072
	s_add_i32 s46, s6, 2
	s_add_u32 s47, s0, 0x80
	s_addc_u32 s7, s1, 0
	s_cmp_eq_u32 s93, s6
	s_cselect_b32 s6, s16, s47
	s_cselect_b32 s7, s17, s7
	s_cselect_b32 s49, s19, s45
	s_cselect_b32 s48, s18, s44
	v_lshl_add_u64 v[182:183], s[0:1], 0, v[146:147]
	s_add_i32 m0, s85, 0xc000
	ds_read_b128 v[178:181], v189
	ds_read_b128 v[192:195], v189 offset:1024
	ds_read_b128 v[196:199], v189 offset:2048
	ds_read_b128 v[200:203], v189 offset:3072
	ds_read_b128 v[204:207], v189 offset:4096
	ds_read_b128 v[208:211], v189 offset:5120
	ds_read_b128 v[212:215], v189 offset:6144
	ds_read_b128 v[216:219], v189 offset:7168
	global_load_lds_dwordx4 v[182:183], off
	v_lshl_add_u64 v[182:183], s[0:1], 0, v[148:149]
	s_add_i32 m0, s85, 0xe000
	s_nop 0
	global_load_lds_dwordx4 v[182:183], off
	s_waitcnt vmcnt(8)
	s_waitcnt lgkmcnt(0)
	s_barrier
	s_setprio 1
	s_waitcnt lgkmcnt(0)
	v_mfma_f32_16x16x32_bf16 v[120:123], v[128:131], v[178:181], v[120:123]
	v_mfma_f32_16x16x32_bf16 v[124:127], v[154:157], v[178:181], v[124:127]
	v_mfma_f32_16x16x32_bf16 v[108:111], v[128:131], v[196:199], v[108:111]
	v_mfma_f32_16x16x32_bf16 v[104:107], v[154:157], v[196:199], v[104:107]
	v_mfma_f32_16x16x32_bf16 v[92:95], v[128:131], v[204:207], v[92:95]
	v_mfma_f32_16x16x32_bf16 v[88:91], v[154:157], v[204:207], v[88:91]
	v_mfma_f32_16x16x32_bf16 v[76:79], v[128:131], v[212:215], v[76:79]
	v_mfma_f32_16x16x32_bf16 v[72:75], v[154:157], v[212:215], v[72:75]
	v_mfma_f32_16x16x32_bf16 v[120:123], v[132:135], v[192:195], v[120:123]
	v_mfma_f32_16x16x32_bf16 v[124:127], v[158:161], v[192:195], v[124:127]
	v_mfma_f32_16x16x32_bf16 v[108:111], v[132:135], v[200:203], v[108:111]
	v_mfma_f32_16x16x32_bf16 v[104:107], v[158:161], v[200:203], v[104:107]
	v_mfma_f32_16x16x32_bf16 v[92:95], v[132:135], v[208:211], v[92:95]
	v_mfma_f32_16x16x32_bf16 v[88:91], v[158:161], v[208:211], v[88:91]
	v_mfma_f32_16x16x32_bf16 v[76:79], v[132:135], v[216:219], v[76:79]
	v_mfma_f32_16x16x32_bf16 v[72:75], v[158:161], v[216:219], v[72:75]
	v_mfma_f32_16x16x32_bf16 v[116:119], v[162:165], v[178:181], v[116:119]
	v_mfma_f32_16x16x32_bf16 v[112:115], v[170:173], v[178:181], v[112:115]
	v_mfma_f32_16x16x32_bf16 v[100:103], v[162:165], v[196:199], v[100:103]
	v_mfma_f32_16x16x32_bf16 v[96:99], v[170:173], v[196:199], v[96:99]
	v_mfma_f32_16x16x32_bf16 v[84:87], v[162:165], v[204:207], v[84:87]
	v_mfma_f32_16x16x32_bf16 v[80:83], v[170:173], v[204:207], v[80:83]
	v_mfma_f32_16x16x32_bf16 v[68:71], v[162:165], v[212:215], v[68:71]
	v_mfma_f32_16x16x32_bf16 v[64:67], v[170:173], v[212:215], v[64:67]
	v_mfma_f32_16x16x32_bf16 v[116:119], v[166:169], v[192:195], v[116:119]
	v_mfma_f32_16x16x32_bf16 v[112:115], v[174:177], v[192:195], v[112:115]
	v_mfma_f32_16x16x32_bf16 v[100:103], v[166:169], v[200:203], v[100:103]
	v_mfma_f32_16x16x32_bf16 v[96:99], v[174:177], v[200:203], v[96:99]
	v_mfma_f32_16x16x32_bf16 v[84:87], v[166:169], v[208:211], v[84:87]
	v_mfma_f32_16x16x32_bf16 v[80:83], v[174:177], v[208:211], v[80:83]
	v_mfma_f32_16x16x32_bf16 v[68:71], v[166:169], v[216:219], v[68:71]
	v_mfma_f32_16x16x32_bf16 v[64:67], v[174:177], v[216:219], v[64:67]
	s_setprio 0
	s_barrier
	s_add_i32 s47, s3, s84
	v_lshl_add_u64 v[182:183], s[48:49], 0, v[138:139]
	s_mov_b32 m0, s47
	ds_read_b128 v[178:181], v189 offset:16384
	ds_read_b128 v[192:195], v189 offset:17408
	ds_read_b128 v[196:199], v189 offset:18432
	ds_read_b128 v[200:203], v189 offset:19456
	ds_read_b128 v[204:207], v189 offset:20480
	ds_read_b128 v[208:211], v189 offset:21504
	ds_read_b128 v[212:215], v189 offset:22528
	ds_read_b128 v[216:219], v189 offset:23552
	global_load_lds_dwordx4 v[182:183], off
	s_add_i32 m0, s47, 0x2000
	v_lshl_add_u64 v[220:221], s[48:49], 0, v[142:143]
	s_add_u32 s48, s48, s10
	s_addc_u32 s49, s49, s11
	s_add_i32 s47, s8, s84
	global_load_lds_dwordx4 v[220:221], off
	v_lshl_add_u64 v[222:223], s[48:49], 0, v[138:139]
	s_mov_b32 m0, s47
	v_lshl_add_u64 v[224:225], s[48:49], 0, v[142:143]
	global_load_lds_dwordx4 v[222:223], off
	s_add_i32 m0, s47, 0x2000
	v_lshl_add_u64 v[226:227], s[6:7], 0, v[136:137]
	global_load_lds_dwordx4 v[224:225], off
	s_mov_b32 m0, s85
	v_lshl_add_u64 v[228:229], s[6:7], 0, v[140:141]
	global_load_lds_dwordx4 v[226:227], off
	s_mov_b32 m0, s86
	s_nop 0
	global_load_lds_dwordx4 v[228:229], off
	s_waitcnt vmcnt(8)
	s_waitcnt lgkmcnt(0)
	s_barrier
; #define PG8_STAGE(bufoff, gbase, voff) do { _Pragma("unroll") for (int _i = 0; _i < 2; ++_i) \
;         __builtin_amdgcn_global_load_lds((const unsigned*)((const char*)(gbase) + (voff)[_i]), (PG8_LAS unsigned*)(lds + (bufoff) + ldsw + _i * 8192), 16, 0, 0); } while (0)
; #define PG8_LDA(dst, b, h) do { _Pragma("unroll") for (int m = 0; m < 4; ++m) _Pragma("unroll") for (int k = 0; k < 2; ++k) dst[m][k] = *(const PG8_LAS bf16x8*)(lds + PG8_SA(b, h) + aoff + m * 2048 + k * 1024); } while (0)
; #define PG8_LDB(dst, b, h) do { _Pragma("unroll") for (int n = 0; n < 2; ++n) _Pragma("unroll") for (int k = 0; k < 2; ++k) dst[n][k] = *(const PG8_LAS bf16x8*)(lds + PG8_SB(b, h) + boff + n * 2048 + k * 1024); } while (0)
; #define PG8_MMA(ai, bj, At, Bt) do { __builtin_amdgcn_s_setprio(1); _Pragma("unroll") for (int m = 0; m < 4; ++m) _Pragma("unroll") for (int n = 0; n < 2; ++n) _Pragma("unroll") for (int k = 0; k < 2; ++k) \
;         acc[ai][bj][m][n] = __builtin_amdgcn_mfma_f32_16x16x32_bf16(Bt[n][k], At[m][k], acc[ai][bj][m][n], 0, 0, 0); __builtin_amdgcn_s_setprio(0); } while (0)
; #define PG8_WAIT_V(n) asm volatile("s_waitcnt vmcnt(" #n ")" ::: "memory")
; #define PG8_WAIT_L(n) asm volatile("s_waitcnt lgkmcnt(" #n ")" ::: "memory")
; #define PG8_BAR __builtin_amdgcn_s_barrier()
; #define PG8_SCHED __builtin_amdgcn_sched_barrier(0)
; template <class Epi, class Sched, bool ALIGN_EPI = false, bool SP2 = false>
; __device__ __forceinline__ void gemm_phase(PG8_LAS unsigned char* lds, const Gemm g, const Sched& S, const Epi& E) {
;     ...
;             PG8_WAIT_V(8); PG8_WAIT_L(0); PG8_BAR; PG8_MMA(1, 0, At, B0); PG8_MMA(1, 1, At, B1); PG8_BAR; PG8_SCHED;
;             PG8_LDB(B0, 1, 0); PG8_LDB(B1, 1, 1); PG8_SCHED; PG8_LDA(At, 1, 0); PG8_STAGE(PG8_SA(0, 1), a2 + hstep, voffA);
;             PG8_WAIT_V(8); PG8_WAIT_L(0); PG8_BAR; PG8_MMA(0, 0, At, B0); PG8_MMA(0, 1, At, B1); PG8_BAR; PG8_SCHED;
	s_setprio 1
	s_waitcnt lgkmcnt(0)
	v_mfma_f32_16x16x32_bf16 v[60:63], v[128:131], v[178:181], v[60:63]
	v_mfma_f32_16x16x32_bf16 v[56:59], v[154:157], v[178:181], v[56:59]
	v_mfma_f32_16x16x32_bf16 v[44:47], v[128:131], v[196:199], v[44:47]
	v_mfma_f32_16x16x32_bf16 v[40:43], v[154:157], v[196:199], v[40:43]
	v_mfma_f32_16x16x32_bf16 v[28:31], v[128:131], v[204:207], v[28:31]
	v_mfma_f32_16x16x32_bf16 v[24:27], v[154:157], v[204:207], v[24:27]
	v_mfma_f32_16x16x32_bf16 v[12:15], v[128:131], v[212:215], v[12:15]
	v_mfma_f32_16x16x32_bf16 v[8:11], v[154:157], v[212:215], v[8:11]
	v_mfma_f32_16x16x32_bf16 v[60:63], v[132:135], v[192:195], v[60:63]
	v_mfma_f32_16x16x32_bf16 v[56:59], v[158:161], v[192:195], v[56:59]
	v_mfma_f32_16x16x32_bf16 v[44:47], v[132:135], v[200:203], v[44:47]
	v_mfma_f32_16x16x32_bf16 v[40:43], v[158:161], v[200:203], v[40:43]
	v_mfma_f32_16x16x32_bf16 v[28:31], v[132:135], v[208:211], v[28:31]
	v_mfma_f32_16x16x32_bf16 v[24:27], v[158:161], v[208:211], v[24:27]
	v_mfma_f32_16x16x32_bf16 v[12:15], v[132:135], v[216:219], v[12:15]
	v_mfma_f32_16x16x32_bf16 v[8:11], v[158:161], v[216:219], v[8:11]
	v_mfma_f32_16x16x32_bf16 v[52:55], v[162:165], v[178:181], v[52:55]
	v_mfma_f32_16x16x32_bf16 v[48:51], v[170:173], v[178:181], v[48:51]
	v_mfma_f32_16x16x32_bf16 v[36:39], v[162:165], v[196:199], v[36:39]
	v_mfma_f32_16x16x32_bf16 v[32:35], v[170:173], v[196:199], v[32:35]
	v_mfma_f32_16x16x32_bf16 v[20:23], v[162:165], v[204:207], v[20:23]
	v_mfma_f32_16x16x32_bf16 v[16:19], v[170:173], v[204:207], v[16:19]
	v_mfma_f32_16x16x32_bf16 v[4:7], v[162:165], v[212:215], v[4:7]
	v_mfma_f32_16x16x32_bf16 v[0:3], v[170:173], v[212:215], v[0:3]
	v_mfma_f32_16x16x32_bf16 v[52:55], v[166:169], v[192:195], v[52:55]
	v_mfma_f32_16x16x32_bf16 v[48:51], v[174:177], v[192:195], v[48:51]
	v_mfma_f32_16x16x32_bf16 v[36:39], v[166:169], v[200:203], v[36:39]
	v_mfma_f32_16x16x32_bf16 v[32:35], v[174:177], v[200:203], v[32:35]
	v_mfma_f32_16x16x32_bf16 v[20:23], v[166:169], v[208:211], v[20:23]
	v_mfma_f32_16x16x32_bf16 v[16:19], v[174:177], v[208:211], v[16:19]
	v_mfma_f32_16x16x32_bf16 v[4:7], v[166:169], v[216:219], v[4:7]
	v_mfma_f32_16x16x32_bf16 v[0:3], v[174:177], v[216:219], v[0:3]
	s_setprio 0
	s_barrier
	s_add_i32 s47, 0, 0x18000
	s_add_i32 s48, 0, 0x1c000
	v_add_u32_e32 v158, s47, v186
	v_add_u32_e32 v174, s48, v186
	ds_read_b128 v[128:131], v158
	ds_read_b128 v[132:135], v158 offset:1024
	ds_read_b128 v[154:157], v158 offset:2048
	ds_read_b128 v[158:161], v158 offset:3072
	ds_read_b128 v[162:165], v174
	ds_read_b128 v[166:169], v174 offset:1024
	ds_read_b128 v[170:173], v174 offset:2048
	ds_read_b128 v[174:177], v174 offset:3072
	s_add_u32 s6, s6, s10
	s_addc_u32 s7, s7, s11
	s_mov_b32 m0, s87
	v_lshl_add_u64 v[230:231], s[6:7], 0, v[136:137]
	ds_read_b128 v[178:181], v189 offset:32768
	ds_read_b128 v[192:195], v189 offset:33792
	ds_read_b128 v[196:199], v189 offset:34816
	ds_read_b128 v[200:203], v189 offset:35840
	ds_read_b128 v[204:207], v189 offset:36864
	ds_read_b128 v[208:211], v189 offset:37888
	ds_read_b128 v[212:215], v189 offset:38912
	ds_read_b128 v[216:219], v189 offset:39936
	global_load_lds_dwordx4 v[230:231], off
	v_lshl_add_u64 v[230:231], s[6:7], 0, v[140:141]
	s_mov_b32 m0, s88
	s_nop 0
	global_load_lds_dwordx4 v[230:231], off
	s_waitcnt vmcnt(8)
	s_waitcnt lgkmcnt(0)
	s_barrier
	s_setprio 1
	s_waitcnt lgkmcnt(0)
	v_mfma_f32_16x16x32_bf16 v[120:123], v[128:131], v[178:181], v[120:123]
	v_mfma_f32_16x16x32_bf16 v[124:127], v[154:157], v[178:181], v[124:127]
	v_mfma_f32_16x16x32_bf16 v[108:111], v[128:131], v[196:199], v[108:111]
	v_mfma_f32_16x16x32_bf16 v[104:107], v[154:157], v[196:199], v[104:107]
	v_mfma_f32_16x16x32_bf16 v[92:95], v[128:131], v[204:207], v[92:95]
	v_mfma_f32_16x16x32_bf16 v[88:91], v[154:157], v[204:207], v[88:91]
	v_mfma_f32_16x16x32_bf16 v[76:79], v[128:131], v[212:215], v[76:79]
	v_mfma_f32_16x16x32_bf16 v[72:75], v[154:157], v[212:215], v[72:75]
	v_mfma_f32_16x16x32_bf16 v[120:123], v[132:135], v[192:195], v[120:123]
	v_mfma_f32_16x16x32_bf16 v[124:127], v[158:161], v[192:195], v[124:127]
	v_mfma_f32_16x16x32_bf16 v[108:111], v[132:135], v[200:203], v[108:111]
	v_mfma_f32_16x16x32_bf16 v[104:107], v[158:161], v[200:203], v[104:107]
	v_mfma_f32_16x16x32_bf16 v[92:95], v[132:135], v[208:211], v[92:95]
	v_mfma_f32_16x16x32_bf16 v[88:91], v[158:161], v[208:211], v[88:91]
	v_mfma_f32_16x16x32_bf16 v[76:79], v[132:135], v[216:219], v[76:79]
	v_mfma_f32_16x16x32_bf16 v[72:75], v[158:161], v[216:219], v[72:75]
	v_mfma_f32_16x16x32_bf16 v[116:119], v[162:165], v[178:181], v[116:119]
	v_mfma_f32_16x16x32_bf16 v[112:115], v[170:173], v[178:181], v[112:115]
	v_mfma_f32_16x16x32_bf16 v[100:103], v[162:165], v[196:199], v[100:103]
	v_mfma_f32_16x16x32_bf16 v[96:99], v[170:173], v[196:199], v[96:99]
	v_mfma_f32_16x16x32_bf16 v[84:87], v[162:165], v[204:207], v[84:87]
	v_mfma_f32_16x16x32_bf16 v[80:83], v[170:173], v[204:207], v[80:83]
	v_mfma_f32_16x16x32_bf16 v[68:71], v[162:165], v[212:215], v[68:71]
	v_mfma_f32_16x16x32_bf16 v[64:67], v[170:173], v[212:215], v[64:67]
	v_mfma_f32_16x16x32_bf16 v[116:119], v[166:169], v[192:195], v[116:119]
	v_mfma_f32_16x16x32_bf16 v[112:115], v[174:177], v[192:195], v[112:115]
	v_mfma_f32_16x16x32_bf16 v[100:103], v[166:169], v[200:203], v[100:103]
	v_mfma_f32_16x16x32_bf16 v[96:99], v[174:177], v[200:203], v[96:99]
	v_mfma_f32_16x16x32_bf16 v[84:87], v[166:169], v[208:211], v[84:87]
	v_mfma_f32_16x16x32_bf16 v[80:83], v[174:177], v[208:211], v[80:83]
	v_mfma_f32_16x16x32_bf16 v[68:71], v[166:169], v[216:219], v[68:71]
	v_mfma_f32_16x16x32_bf16 v[64:67], v[174:177], v[216:219], v[64:67]
	s_setprio 0
	s_barrier
; #define PG8_STAGE(bufoff, gbase, voff) do { _Pragma("unroll") for (int _i = 0; _i < 2; ++_i) \
;         __builtin_amdgcn_global_load_lds((const unsigned*)((const char*)(gbase) + (voff)[_i]), (PG8_LAS unsigned*)(lds + (bufoff) + ldsw + _i * 8192), 16, 0, 0); } while (0)
; #define PG8_LDA(dst, b, h) do { _Pragma("unroll") for (int m = 0; m < 4; ++m) _Pragma("unroll") for (int k = 0; k < 2; ++k) dst[m][k] = *(const PG8_LAS bf16x8*)(lds + PG8_SA(b, h) + aoff + m * 2048 + k * 1024); } while (0)
; #define PG8_MMA(ai, bj, At, Bt) do { __builtin_amdgcn_s_setprio(1); _Pragma("unroll") for (int m = 0; m < 4; ++m) _Pragma("unroll") for (int n = 0; n < 2; ++n) _Pragma("unroll") for (int k = 0; k < 2; ++k) \
;         acc[ai][bj][m][n] = __builtin_amdgcn_mfma_f32_16x16x32_bf16(Bt[n][k], At[m][k], acc[ai][bj][m][n], 0, 0, 0); __builtin_amdgcn_s_setprio(0); } while (0)
; #define PG8_WAIT_V(n) asm volatile("s_waitcnt vmcnt(" #n ")" ::: "memory")
; #define PG8_WAIT_L(n) asm volatile("s_waitcnt lgkmcnt(" #n ")" ::: "memory")
; #define PG8_BAR __builtin_amdgcn_s_barrier()
; #define PG8_SCHED __builtin_amdgcn_sched_barrier(0)
; template <class Epi, class Sched, bool ALIGN_EPI = false, bool SP2 = false>
; __device__ __forceinline__ void gemm_phase(PG8_LAS unsigned char* lds, const Gemm g, const Sched& S, const Epi& E) {
;     ...
;         for (int t = 0; t < nt; t += 2) {
;     ...
;             PG8_LDA(At, 1, 1); PG8_STAGE(PG8_SB(1, 0), b3, voffB); PG8_STAGE(PG8_SB(1, 1), b3 + hstep, voffB); PG8_STAGE(PG8_SA(1, 0), a3, voffA);
;             PG8_WAIT_V(8); PG8_WAIT_L(0); PG8_BAR; PG8_MMA(1, 0, At, B0); PG8_MMA(1, 1, At, B1); PG8_BAR; PG8_SCHED;
	s_add_i32 s6, s47, s84
	v_lshl_add_u64 v[182:183], v[182:183], 0, s[64:65]
	s_mov_b32 m0, s6
	ds_read_b128 v[178:181], v189 offset:49152
	ds_read_b128 v[192:195], v189 offset:50176
	ds_read_b128 v[196:199], v189 offset:51200
	ds_read_b128 v[200:203], v189 offset:52224
	ds_read_b128 v[204:207], v189 offset:53248
	ds_read_b128 v[208:211], v189 offset:54272
	ds_read_b128 v[212:215], v189 offset:55296
	ds_read_b128 v[216:219], v189 offset:56320
	global_load_lds_dwordx4 v[182:183], off
	v_lshl_add_u64 v[182:183], v[220:221], 0, s[64:65]
	s_add_i32 m0, s6, 0x2000
	s_add_i32 s6, s48, s84
	global_load_lds_dwordx4 v[182:183], off
	v_lshl_add_u64 v[182:183], v[222:223], 0, s[64:65]
	s_mov_b32 m0, s6
	s_nop 0
	global_load_lds_dwordx4 v[182:183], off
	v_lshl_add_u64 v[182:183], v[224:225], 0, s[64:65]
	s_add_i32 m0, s6, 0x2000
	s_nop 0
	global_load_lds_dwordx4 v[182:183], off
	v_lshl_add_u64 v[182:183], v[226:227], 0, s[64:65]
	s_mov_b32 m0, s96
	s_nop 0
	global_load_lds_dwordx4 v[182:183], off
	v_lshl_add_u64 v[182:183], v[228:229], 0, s[64:65]
	s_mov_b32 m0, s97
	s_nop 0
	global_load_lds_dwordx4 v[182:183], off
	s_waitcnt vmcnt(8)
	s_waitcnt lgkmcnt(0)
	s_barrier
	s_setprio 1
	s_waitcnt lgkmcnt(0)
	v_mfma_f32_16x16x32_bf16 v[60:63], v[128:131], v[178:181], v[60:63]
	v_mfma_f32_16x16x32_bf16 v[56:59], v[154:157], v[178:181], v[56:59]
	v_mfma_f32_16x16x32_bf16 v[44:47], v[128:131], v[196:199], v[44:47]
	v_mfma_f32_16x16x32_bf16 v[40:43], v[154:157], v[196:199], v[40:43]
	v_mfma_f32_16x16x32_bf16 v[28:31], v[128:131], v[204:207], v[28:31]
	v_mfma_f32_16x16x32_bf16 v[24:27], v[154:157], v[204:207], v[24:27]
	v_mfma_f32_16x16x32_bf16 v[12:15], v[128:131], v[212:215], v[12:15]
	v_mfma_f32_16x16x32_bf16 v[8:11], v[154:157], v[212:215], v[8:11]
	v_mfma_f32_16x16x32_bf16 v[60:63], v[132:135], v[192:195], v[60:63]
	v_mfma_f32_16x16x32_bf16 v[56:59], v[158:161], v[192:195], v[56:59]
	v_mfma_f32_16x16x32_bf16 v[44:47], v[132:135], v[200:203], v[44:47]
	v_mfma_f32_16x16x32_bf16 v[40:43], v[158:161], v[200:203], v[40:43]
	v_mfma_f32_16x16x32_bf16 v[28:31], v[132:135], v[208:211], v[28:31]
	v_mfma_f32_16x16x32_bf16 v[24:27], v[158:161], v[208:211], v[24:27]
	v_mfma_f32_16x16x32_bf16 v[12:15], v[132:135], v[216:219], v[12:15]
	v_mfma_f32_16x16x32_bf16 v[8:11], v[158:161], v[216:219], v[8:11]
	v_mfma_f32_16x16x32_bf16 v[52:55], v[162:165], v[178:181], v[52:55]
	v_mfma_f32_16x16x32_bf16 v[48:51], v[170:173], v[178:181], v[48:51]
	v_mfma_f32_16x16x32_bf16 v[36:39], v[162:165], v[196:199], v[36:39]
	v_mfma_f32_16x16x32_bf16 v[32:35], v[170:173], v[196:199], v[32:35]
	v_mfma_f32_16x16x32_bf16 v[20:23], v[162:165], v[204:207], v[20:23]
	v_mfma_f32_16x16x32_bf16 v[16:19], v[170:173], v[204:207], v[16:19]
	v_mfma_f32_16x16x32_bf16 v[4:7], v[162:165], v[212:215], v[4:7]
	v_mfma_f32_16x16x32_bf16 v[0:3], v[170:173], v[212:215], v[0:3]
	v_mfma_f32_16x16x32_bf16 v[52:55], v[166:169], v[192:195], v[52:55]
	v_mfma_f32_16x16x32_bf16 v[48:51], v[174:177], v[192:195], v[48:51]
	v_mfma_f32_16x16x32_bf16 v[36:39], v[166:169], v[200:203], v[36:39]
	v_mfma_f32_16x16x32_bf16 v[32:35], v[174:177], v[200:203], v[32:35]
	v_mfma_f32_16x16x32_bf16 v[20:23], v[166:169], v[208:211], v[20:23]
	v_mfma_f32_16x16x32_bf16 v[16:19], v[174:177], v[208:211], v[16:19]
	v_mfma_f32_16x16x32_bf16 v[4:7], v[166:169], v[216:219], v[4:7]
	v_mfma_f32_16x16x32_bf16 v[0:3], v[174:177], v[216:219], v[0:3]
	s_setprio 0
	s_barrier
	s_add_u32 s0, s0, 0x100
	s_addc_u32 s1, s1, 0
	s_add_u32 s44, s44, 0x100
	s_addc_u32 s45, s45, 0
	s_cmp_ge_i32 s46, s33
	s_mov_b32 s6, s46
	s_cbranch_scc0 .LBB0_919

; #define PG8_STAGE(bufoff, gbase, voff) do { _Pragma("unroll") for (int _i = 0; _i < 2; ++_i) \
;         __builtin_amdgcn_global_load_lds((const unsigned*)((const char*)(gbase) + (voff)[_i]), (PG8_LAS unsigned*)(lds + (bufoff) + ldsw + _i * 8192), 16, 0, 0); } while (0)
; #define PG8_LDA(dst, b, h) do { _Pragma("unroll") for (int m = 0; m < 4; ++m) _Pragma("unroll") for (int k = 0; k < 2; ++k) dst[m][k] = *(const PG8_LAS bf16x8*)(lds + PG8_SA(b, h) + aoff + m * 2048 + k * 1024); } while (0)
; #define PG8_LDB(dst, b, h) do { _Pragma("unroll") for (int n = 0; n < 2; ++n) _Pragma("unroll") for (int k = 0; k < 2; ++k) dst[n][k] = *(const PG8_LAS bf16x8*)(lds + PG8_SB(b, h) + boff + n * 2048 + k * 1024); } while (0)
; #define PG8_MMA(ai, bj, At, Bt) do { __builtin_amdgcn_s_setprio(1); _Pragma("unroll") for (int m = 0; m < 4; ++m) _Pragma("unroll") for (int n = 0; n < 2; ++n) _Pragma("unroll") for (int k = 0; k < 2; ++k) \
;         acc[ai][bj][m][n] = __builtin_amdgcn_mfma_f32_16x16x32_bf16(Bt[n][k], At[m][k], acc[ai][bj][m][n], 0, 0, 0); __builtin_amdgcn_s_setprio(0); } while (0)
; #define PG8_WAIT_V(n) asm volatile("s_waitcnt vmcnt(" #n ")" ::: "memory")
; #define PG8_WAIT_L(n) asm volatile("s_waitcnt lgkmcnt(" #n ")" ::: "memory")
; template <class Epi, class Sched, bool ALIGN_EPI = false, bool SP2 = false>
; __device__ __forceinline__ void gemm_phase(PG8_LAS unsigned char* lds, const Gemm g, const Sched& S, const Epi& E) {
;     ...
;             const bool last = (t == nt - 2);
;             const char* a1 = cA + (size_t)(t + 1) * kstep;
;             const char* a2 = last ? nA : cA + (size_t)(t + 2) * kstep; const char* b2 = last ? nB : cB + (size_t)(t + 2) * kstep;
;             const char* a3 = a2 + kstep; const char* b3 = b2 + kstep;
;             if (last && has_next) S.a_ready(nxt);
;             if constexpr (SP2) {
;             PG8_LDB(B0, 0, 0); PG8_LDB(B1, 0, 1); PG8_SCHED; PG8_LDA(At, 0, 0); PG8_STAGE(PG8_SA(1, 1), a1 + hstep, voffA);
;             PG8_WAIT_V(8); PG8_WAIT_L(0); PG8_BAR; PG8_MMA(0, 0, At, B0); PG8_MMA(0, 1, At, B1); PG8_BAR; PG8_SCHED;
;             PG8_LDA(At, 0, 1); PG8_STAGE(PG8_SB(0, 0), b2, voffB); PG8_STAGE(PG8_SB(0, 1), b2 + hstep, voffB); PG8_STAGE(PG8_SA(0, 0), a2, voffA);
;             PG8_WAIT_V(8); PG8_WAIT_L(0); PG8_BAR; PG8_MMA(1, 0, At, B0); PG8_MMA(1, 1, At, B1); PG8_BAR; PG8_SCHED;
.LBB0_1440:
	ds_read_b128 v[146:149], v164
	ds_read_b128 v[168:171], v164 offset:1024
	ds_read_b128 v[172:175], v164 offset:2048
	ds_read_b128 v[176:179], v164 offset:3072
	ds_read_b128 v[180:183], v165
	ds_read_b128 v[184:187], v165 offset:1024
	ds_read_b128 v[188:191], v165 offset:2048
	ds_read_b128 v[192:195], v165 offset:3072
	s_add_u32 s56, s54, 0xfff80080
	s_addc_u32 s57, s55, -1
	s_cmp_eq_u32 s87, 28
	s_cselect_b32 s59, s47, s57
	s_cselect_b32 s58, s83, s56
	s_cselect_b32 s57, s45, s86
	s_cselect_b32 s56, s84, s85
	v_lshl_add_u64 v[228:229], s[54:55], 0, v[136:137]
	s_add_i32 m0, s65, 0xc000
	ds_read_b128 v[196:199], v166
	ds_read_b128 v[200:203], v166 offset:1024
	ds_read_b128 v[204:207], v166 offset:2048
	ds_read_b128 v[208:211], v166 offset:3072
	ds_read_b128 v[212:215], v166 offset:4096
	ds_read_b128 v[216:219], v166 offset:5120
	ds_read_b128 v[220:223], v166 offset:6144
	ds_read_b128 v[224:227], v166 offset:7168
	global_load_lds_dwordx4 v[228:229], off
	v_lshl_add_u64 v[228:229], s[54:55], 0, v[138:139]
	s_add_i32 m0, s65, 0xe000
	s_nop 0
	global_load_lds_dwordx4 v[228:229], off
	s_waitcnt vmcnt(8)
	s_waitcnt lgkmcnt(0)
	s_barrier
	s_setprio 1
	s_waitcnt lgkmcnt(0)
	v_mfma_f32_16x16x32_bf16 v[124:127], v[146:149], v[196:199], v[124:127]
	v_mfma_f32_16x16x32_bf16 v[120:123], v[172:175], v[196:199], v[120:123]
	v_mfma_f32_16x16x32_bf16 v[108:111], v[146:149], v[204:207], v[108:111]
	v_mfma_f32_16x16x32_bf16 v[104:107], v[172:175], v[204:207], v[104:107]
	v_mfma_f32_16x16x32_bf16 v[92:95], v[146:149], v[212:215], v[92:95]
	v_mfma_f32_16x16x32_bf16 v[88:91], v[172:175], v[212:215], v[88:91]
	v_mfma_f32_16x16x32_bf16 v[76:79], v[146:149], v[220:223], v[76:79]
	v_mfma_f32_16x16x32_bf16 v[72:75], v[172:175], v[220:223], v[72:75]
	v_mfma_f32_16x16x32_bf16 v[124:127], v[168:171], v[200:203], v[124:127]
	v_mfma_f32_16x16x32_bf16 v[120:123], v[176:179], v[200:203], v[120:123]
	v_mfma_f32_16x16x32_bf16 v[108:111], v[168:171], v[208:211], v[108:111]
	v_mfma_f32_16x16x32_bf16 v[104:107], v[176:179], v[208:211], v[104:107]
	v_mfma_f32_16x16x32_bf16 v[92:95], v[168:171], v[216:219], v[92:95]
	v_mfma_f32_16x16x32_bf16 v[88:91], v[176:179], v[216:219], v[88:91]
	v_mfma_f32_16x16x32_bf16 v[76:79], v[168:171], v[224:227], v[76:79]
	v_mfma_f32_16x16x32_bf16 v[72:75], v[176:179], v[224:227], v[72:75]
	v_mfma_f32_16x16x32_bf16 v[116:119], v[180:183], v[196:199], v[116:119]
	v_mfma_f32_16x16x32_bf16 v[112:115], v[188:191], v[196:199], v[112:115]
	v_mfma_f32_16x16x32_bf16 v[100:103], v[180:183], v[204:207], v[100:103]
	v_mfma_f32_16x16x32_bf16 v[96:99], v[188:191], v[204:207], v[96:99]
	v_mfma_f32_16x16x32_bf16 v[84:87], v[180:183], v[212:215], v[84:87]
	v_mfma_f32_16x16x32_bf16 v[80:83], v[188:191], v[212:215], v[80:83]
	v_mfma_f32_16x16x32_bf16 v[68:71], v[180:183], v[220:223], v[68:71]
	v_mfma_f32_16x16x32_bf16 v[64:67], v[188:191], v[220:223], v[64:67]
	v_mfma_f32_16x16x32_bf16 v[116:119], v[184:187], v[200:203], v[116:119]
	v_mfma_f32_16x16x32_bf16 v[112:115], v[192:195], v[200:203], v[112:115]
	v_mfma_f32_16x16x32_bf16 v[100:103], v[184:187], v[208:211], v[100:103]
	v_mfma_f32_16x16x32_bf16 v[96:99], v[192:195], v[208:211], v[96:99]
	v_mfma_f32_16x16x32_bf16 v[84:87], v[184:187], v[216:219], v[84:87]
	v_mfma_f32_16x16x32_bf16 v[80:83], v[192:195], v[216:219], v[80:83]
	v_mfma_f32_16x16x32_bf16 v[68:71], v[184:187], v[224:227], v[68:71]
	v_mfma_f32_16x16x32_bf16 v[64:67], v[192:195], v[224:227], v[64:67]
	s_setprio 0
	s_barrier
	s_add_i32 s88, s74, s64
	v_lshl_add_u64 v[228:229], s[56:57], 0, v[130:131]
	s_mov_b32 m0, s88
	ds_read_b128 v[196:199], v166 offset:16384
	ds_read_b128 v[200:203], v166 offset:17408
	ds_read_b128 v[204:207], v166 offset:18432
	ds_read_b128 v[208:211], v166 offset:19456
	ds_read_b128 v[212:215], v166 offset:20480
	ds_read_b128 v[216:219], v166 offset:21504
	ds_read_b128 v[220:223], v166 offset:22528
	ds_read_b128 v[224:227], v166 offset:23552
	global_load_lds_dwordx4 v[228:229], off
	s_add_i32 m0, s88, 0x2000
	s_add_u32 s88, s56, 0x80000
	v_lshl_add_u64 v[230:231], s[56:57], 0, v[134:135]
	s_addc_u32 s89, s57, 0
	s_add_i32 s90, s75, s64
	global_load_lds_dwordx4 v[230:231], off
	v_lshl_add_u64 v[232:233], s[88:89], 0, v[130:131]
	s_mov_b32 m0, s90
	v_lshl_add_u64 v[234:235], s[58:59], 0, v[132:133]
	global_load_lds_dwordx4 v[232:233], off
	v_lshl_add_u64 v[232:233], s[88:89], 0, v[134:135]
	s_add_i32 m0, s90, 0x2000
	s_nop 0
	global_load_lds_dwordx4 v[232:233], off
	v_lshl_add_u64 v[232:233], s[58:59], 0, v[128:129]
	s_mov_b32 m0, s65
	s_nop 0
	global_load_lds_dwordx4 v[232:233], off
	s_mov_b32 m0, s66
	s_nop 0
	global_load_lds_dwordx4 v[234:235], off
	s_waitcnt vmcnt(8)
	s_waitcnt lgkmcnt(0)
	s_barrier
; #define PG8_STAGE(bufoff, gbase, voff) do { _Pragma("unroll") for (int _i = 0; _i < 2; ++_i) \
;         __builtin_amdgcn_global_load_lds((const unsigned*)((const char*)(gbase) + (voff)[_i]), (PG8_LAS unsigned*)(lds + (bufoff) + ldsw + _i * 8192), 16, 0, 0); } while (0)
; #define PG8_LDA(dst, b, h) do { _Pragma("unroll") for (int m = 0; m < 4; ++m) _Pragma("unroll") for (int k = 0; k < 2; ++k) dst[m][k] = *(const PG8_LAS bf16x8*)(lds + PG8_SA(b, h) + aoff + m * 2048 + k * 1024); } while (0)
; #define PG8_LDB(dst, b, h) do { _Pragma("unroll") for (int n = 0; n < 2; ++n) _Pragma("unroll") for (int k = 0; k < 2; ++k) dst[n][k] = *(const PG8_LAS bf16x8*)(lds + PG8_SB(b, h) + boff + n * 2048 + k * 1024); } while (0)
; #define PG8_MMA(ai, bj, At, Bt) do { __builtin_amdgcn_s_setprio(1); _Pragma("unroll") for (int m = 0; m < 4; ++m) _Pragma("unroll") for (int n = 0; n < 2; ++n) _Pragma("unroll") for (int k = 0; k < 2; ++k) \
;         acc[ai][bj][m][n] = __builtin_amdgcn_mfma_f32_16x16x32_bf16(Bt[n][k], At[m][k], acc[ai][bj][m][n], 0, 0, 0); __builtin_amdgcn_s_setprio(0); } while (0)
; #define PG8_WAIT_V(n) asm volatile("s_waitcnt vmcnt(" #n ")" ::: "memory")
; #define PG8_WAIT_L(n) asm volatile("s_waitcnt lgkmcnt(" #n ")" ::: "memory")
; #define PG8_BAR __builtin_amdgcn_s_barrier()
; #define PG8_SCHED __builtin_amdgcn_sched_barrier(0)
; template <class Epi, class Sched, bool ALIGN_EPI = false, bool SP2 = false>
; __device__ __forceinline__ void gemm_phase(PG8_LAS unsigned char* lds, const Gemm g, const Sched& S, const Epi& E) {
;     ...
;             PG8_WAIT_V(8); PG8_WAIT_L(0); PG8_BAR; PG8_MMA(1, 0, At, B0); PG8_MMA(1, 1, At, B1); PG8_BAR; PG8_SCHED;
;             PG8_LDB(B0, 1, 0); PG8_LDB(B1, 1, 1); PG8_SCHED; PG8_LDA(At, 1, 0); PG8_STAGE(PG8_SA(0, 1), a2 + hstep, voffA);
;             PG8_WAIT_V(8); PG8_WAIT_L(0); PG8_BAR; PG8_MMA(0, 0, At, B0); PG8_MMA(0, 1, At, B1); PG8_BAR; PG8_SCHED;
	s_setprio 1
	s_waitcnt lgkmcnt(0)
	v_mfma_f32_16x16x32_bf16 v[60:63], v[146:149], v[196:199], v[60:63]
	v_mfma_f32_16x16x32_bf16 v[56:59], v[172:175], v[196:199], v[56:59]
	v_mfma_f32_16x16x32_bf16 v[44:47], v[146:149], v[204:207], v[44:47]
	v_mfma_f32_16x16x32_bf16 v[40:43], v[172:175], v[204:207], v[40:43]
	v_mfma_f32_16x16x32_bf16 v[28:31], v[146:149], v[212:215], v[28:31]
	v_mfma_f32_16x16x32_bf16 v[24:27], v[172:175], v[212:215], v[24:27]
	v_mfma_f32_16x16x32_bf16 v[12:15], v[146:149], v[220:223], v[12:15]
	v_mfma_f32_16x16x32_bf16 v[8:11], v[172:175], v[220:223], v[8:11]
	v_mfma_f32_16x16x32_bf16 v[60:63], v[168:171], v[200:203], v[60:63]
	v_mfma_f32_16x16x32_bf16 v[56:59], v[176:179], v[200:203], v[56:59]
	v_mfma_f32_16x16x32_bf16 v[44:47], v[168:171], v[208:211], v[44:47]
	v_mfma_f32_16x16x32_bf16 v[40:43], v[176:179], v[208:211], v[40:43]
	v_mfma_f32_16x16x32_bf16 v[28:31], v[168:171], v[216:219], v[28:31]
	v_mfma_f32_16x16x32_bf16 v[24:27], v[176:179], v[216:219], v[24:27]
	v_mfma_f32_16x16x32_bf16 v[12:15], v[168:171], v[224:227], v[12:15]
	v_mfma_f32_16x16x32_bf16 v[8:11], v[176:179], v[224:227], v[8:11]
	v_mfma_f32_16x16x32_bf16 v[52:55], v[180:183], v[196:199], v[52:55]
	v_mfma_f32_16x16x32_bf16 v[48:51], v[188:191], v[196:199], v[48:51]
	v_mfma_f32_16x16x32_bf16 v[36:39], v[180:183], v[204:207], v[36:39]
	v_mfma_f32_16x16x32_bf16 v[32:35], v[188:191], v[204:207], v[32:35]
	v_mfma_f32_16x16x32_bf16 v[20:23], v[180:183], v[212:215], v[20:23]
	v_mfma_f32_16x16x32_bf16 v[16:19], v[188:191], v[212:215], v[16:19]
	v_mfma_f32_16x16x32_bf16 v[4:7], v[180:183], v[220:223], v[4:7]
	v_mfma_f32_16x16x32_bf16 v[0:3], v[188:191], v[220:223], v[0:3]
	v_mfma_f32_16x16x32_bf16 v[52:55], v[184:187], v[200:203], v[52:55]
	v_mfma_f32_16x16x32_bf16 v[48:51], v[192:195], v[200:203], v[48:51]
	v_mfma_f32_16x16x32_bf16 v[36:39], v[184:187], v[208:211], v[36:39]
	v_mfma_f32_16x16x32_bf16 v[32:35], v[192:195], v[208:211], v[32:35]
	v_mfma_f32_16x16x32_bf16 v[20:23], v[184:187], v[216:219], v[20:23]
	v_mfma_f32_16x16x32_bf16 v[16:19], v[192:195], v[216:219], v[16:19]
	v_mfma_f32_16x16x32_bf16 v[4:7], v[184:187], v[224:227], v[4:7]
	v_mfma_f32_16x16x32_bf16 v[0:3], v[192:195], v[224:227], v[0:3]
	s_setprio 0
	s_barrier
	s_add_i32 s88, 0, 0x18000
	v_add_u32_e32 v167, s88, v163
	s_add_i32 s89, 0, 0x1c000
	ds_read_b128 v[146:149], v167
	ds_read_b128 v[168:171], v167 offset:1024
	ds_read_b128 v[172:175], v167 offset:2048
	ds_read_b128 v[176:179], v167 offset:3072
	v_add_u32_e32 v167, s89, v163
	ds_read_b128 v[180:183], v167
	ds_read_b128 v[184:187], v167 offset:1024
	ds_read_b128 v[188:191], v167 offset:2048
	ds_read_b128 v[192:195], v167 offset:3072
	s_add_u32 s58, s58, 0x80000
	s_addc_u32 s59, s59, 0
	s_mov_b32 m0, s67
	v_lshl_add_u64 v[236:237], s[58:59], 0, v[128:129]
	ds_read_b128 v[196:199], v166 offset:32768
	ds_read_b128 v[200:203], v166 offset:33792
	ds_read_b128 v[204:207], v166 offset:34816
	ds_read_b128 v[208:211], v166 offset:35840
	ds_read_b128 v[212:215], v166 offset:36864
	ds_read_b128 v[216:219], v166 offset:37888
	ds_read_b128 v[220:223], v166 offset:38912
	ds_read_b128 v[224:227], v166 offset:39936
	global_load_lds_dwordx4 v[236:237], off
	v_lshl_add_u64 v[236:237], s[58:59], 0, v[132:133]
	s_mov_b32 m0, s68
	s_nop 0
	global_load_lds_dwordx4 v[236:237], off
	s_waitcnt vmcnt(8)
	s_waitcnt lgkmcnt(0)
	s_barrier
	s_setprio 1
	s_waitcnt lgkmcnt(0)
	v_mfma_f32_16x16x32_bf16 v[124:127], v[146:149], v[196:199], v[124:127]
	v_mfma_f32_16x16x32_bf16 v[120:123], v[172:175], v[196:199], v[120:123]
	v_mfma_f32_16x16x32_bf16 v[108:111], v[146:149], v[204:207], v[108:111]
	v_mfma_f32_16x16x32_bf16 v[104:107], v[172:175], v[204:207], v[104:107]
	v_mfma_f32_16x16x32_bf16 v[92:95], v[146:149], v[212:215], v[92:95]
	v_mfma_f32_16x16x32_bf16 v[88:91], v[172:175], v[212:215], v[88:91]
	v_mfma_f32_16x16x32_bf16 v[76:79], v[146:149], v[220:223], v[76:79]
	v_mfma_f32_16x16x32_bf16 v[72:75], v[172:175], v[220:223], v[72:75]
	v_mfma_f32_16x16x32_bf16 v[124:127], v[168:171], v[200:203], v[124:127]
	v_mfma_f32_16x16x32_bf16 v[120:123], v[176:179], v[200:203], v[120:123]
	v_mfma_f32_16x16x32_bf16 v[108:111], v[168:171], v[208:211], v[108:111]
	v_mfma_f32_16x16x32_bf16 v[104:107], v[176:179], v[208:211], v[104:107]
	v_mfma_f32_16x16x32_bf16 v[92:95], v[168:171], v[216:219], v[92:95]
	v_mfma_f32_16x16x32_bf16 v[88:91], v[176:179], v[216:219], v[88:91]
	v_mfma_f32_16x16x32_bf16 v[76:79], v[168:171], v[224:227], v[76:79]
	v_mfma_f32_16x16x32_bf16 v[72:75], v[176:179], v[224:227], v[72:75]
	v_mfma_f32_16x16x32_bf16 v[116:119], v[180:183], v[196:199], v[116:119]
	v_mfma_f32_16x16x32_bf16 v[112:115], v[188:191], v[196:199], v[112:115]
	v_mfma_f32_16x16x32_bf16 v[100:103], v[180:183], v[204:207], v[100:103]
	v_mfma_f32_16x16x32_bf16 v[96:99], v[188:191], v[204:207], v[96:99]
	v_mfma_f32_16x16x32_bf16 v[84:87], v[180:183], v[212:215], v[84:87]
	v_mfma_f32_16x16x32_bf16 v[80:83], v[188:191], v[212:215], v[80:83]
	v_mfma_f32_16x16x32_bf16 v[68:71], v[180:183], v[220:223], v[68:71]
	v_mfma_f32_16x16x32_bf16 v[64:67], v[188:191], v[220:223], v[64:67]
	v_mfma_f32_16x16x32_bf16 v[116:119], v[184:187], v[200:203], v[116:119]
	v_mfma_f32_16x16x32_bf16 v[112:115], v[192:195], v[200:203], v[112:115]
	v_mfma_f32_16x16x32_bf16 v[100:103], v[184:187], v[208:211], v[100:103]
	v_mfma_f32_16x16x32_bf16 v[96:99], v[192:195], v[208:211], v[96:99]
	v_mfma_f32_16x16x32_bf16 v[84:87], v[184:187], v[216:219], v[84:87]
	v_mfma_f32_16x16x32_bf16 v[80:83], v[192:195], v[216:219], v[80:83]
	v_mfma_f32_16x16x32_bf16 v[68:71], v[184:187], v[224:227], v[68:71]
	v_mfma_f32_16x16x32_bf16 v[64:67], v[192:195], v[224:227], v[64:67]
	s_setprio 0
	s_barrier
; #define PG8_STAGE(bufoff, gbase, voff) do { _Pragma("unroll") for (int _i = 0; _i < 2; ++_i) \
;         __builtin_amdgcn_global_load_lds((const unsigned*)((const char*)(gbase) + (voff)[_i]), (PG8_LAS unsigned*)(lds + (bufoff) + ldsw + _i * 8192), 16, 0, 0); } while (0)
; #define PG8_LDA(dst, b, h) do { _Pragma("unroll") for (int m = 0; m < 4; ++m) _Pragma("unroll") for (int k = 0; k < 2; ++k) dst[m][k] = *(const PG8_LAS bf16x8*)(lds + PG8_SA(b, h) + aoff + m * 2048 + k * 1024); } while (0)
; #define PG8_MMA(ai, bj, At, Bt) do { __builtin_amdgcn_s_setprio(1); _Pragma("unroll") for (int m = 0; m < 4; ++m) _Pragma("unroll") for (int n = 0; n < 2; ++n) _Pragma("unroll") for (int k = 0; k < 2; ++k) \
;         acc[ai][bj][m][n] = __builtin_amdgcn_mfma_f32_16x16x32_bf16(Bt[n][k], At[m][k], acc[ai][bj][m][n], 0, 0, 0); __builtin_amdgcn_s_setprio(0); } while (0)
; #define PG8_WAIT_V(n) asm volatile("s_waitcnt vmcnt(" #n ")" ::: "memory")
; #define PG8_WAIT_L(n) asm volatile("s_waitcnt lgkmcnt(" #n ")" ::: "memory")
; #define PG8_BAR __builtin_amdgcn_s_barrier()
; #define PG8_SCHED __builtin_amdgcn_sched_barrier(0)
; template <class Epi, class Sched, bool ALIGN_EPI = false, bool SP2 = false>
; __device__ __forceinline__ void gemm_phase(PG8_LAS unsigned char* lds, const Gemm g, const Sched& S, const Epi& E) {
;     ...
;             PG8_LDA(At, 1, 1); PG8_STAGE(PG8_SB(1, 0), b3, voffB); PG8_STAGE(PG8_SB(1, 1), b3 + hstep, voffB); PG8_STAGE(PG8_SA(1, 0), a3, voffA);
;             PG8_WAIT_V(8); PG8_WAIT_L(0); PG8_BAR; PG8_MMA(1, 0, At, B0); PG8_MMA(1, 1, At, B1); PG8_BAR; PG8_SCHED;
;     ...
;         if constexpr (ALIGN_EPI) { if (wr == 0) PG8_BAR; }
	s_add_i32 s58, s88, s64
	v_lshl_add_u64 v[228:229], v[228:229], 0, s[12:13]
	s_mov_b32 m0, s58
	ds_read_b128 v[196:199], v166 offset:49152
	ds_read_b128 v[200:203], v166 offset:50176
	ds_read_b128 v[204:207], v166 offset:51200
	ds_read_b128 v[208:211], v166 offset:52224
	ds_read_b128 v[212:215], v166 offset:53248
	ds_read_b128 v[216:219], v166 offset:54272
	ds_read_b128 v[220:223], v166 offset:55296
	ds_read_b128 v[224:227], v166 offset:56320
	global_load_lds_dwordx4 v[228:229], off
	s_add_i32 m0, s58, 0x2000
	s_add_u32 s56, s56, 0x80080
	v_lshl_add_u64 v[228:229], v[230:231], 0, s[12:13]
	s_addc_u32 s57, s57, 0
	s_add_i32 s58, s89, s64
	global_load_lds_dwordx4 v[228:229], off
	v_lshl_add_u64 v[228:229], s[56:57], 0, v[130:131]
	s_mov_b32 m0, s58
	s_nop 0
	global_load_lds_dwordx4 v[228:229], off
	v_lshl_add_u64 v[228:229], s[56:57], 0, v[134:135]
	s_add_i32 m0, s58, 0x2000
	s_nop 0
	global_load_lds_dwordx4 v[228:229], off
	v_lshl_add_u64 v[228:229], v[232:233], 0, s[12:13]
	s_mov_b32 m0, s71
	s_nop 0
	global_load_lds_dwordx4 v[228:229], off
	v_lshl_add_u64 v[228:229], v[234:235], 0, s[12:13]
	s_mov_b32 m0, s72
	s_nop 0
	global_load_lds_dwordx4 v[228:229], off
	s_waitcnt vmcnt(8)
	s_waitcnt lgkmcnt(0)
	s_barrier
	s_setprio 1
	s_waitcnt lgkmcnt(0)
	v_mfma_f32_16x16x32_bf16 v[60:63], v[146:149], v[196:199], v[60:63]
	v_mfma_f32_16x16x32_bf16 v[56:59], v[172:175], v[196:199], v[56:59]
	v_mfma_f32_16x16x32_bf16 v[44:47], v[146:149], v[204:207], v[44:47]
	v_mfma_f32_16x16x32_bf16 v[40:43], v[172:175], v[204:207], v[40:43]
	v_mfma_f32_16x16x32_bf16 v[28:31], v[146:149], v[212:215], v[28:31]
	v_mfma_f32_16x16x32_bf16 v[24:27], v[172:175], v[212:215], v[24:27]
	v_mfma_f32_16x16x32_bf16 v[12:15], v[146:149], v[220:223], v[12:15]
	v_mfma_f32_16x16x32_bf16 v[8:11], v[172:175], v[220:223], v[8:11]
	v_mfma_f32_16x16x32_bf16 v[60:63], v[168:171], v[200:203], v[60:63]
	v_mfma_f32_16x16x32_bf16 v[56:59], v[176:179], v[200:203], v[56:59]
	v_mfma_f32_16x16x32_bf16 v[44:47], v[168:171], v[208:211], v[44:47]
	v_mfma_f32_16x16x32_bf16 v[40:43], v[176:179], v[208:211], v[40:43]
	v_mfma_f32_16x16x32_bf16 v[28:31], v[168:171], v[216:219], v[28:31]
	v_mfma_f32_16x16x32_bf16 v[24:27], v[176:179], v[216:219], v[24:27]
	v_mfma_f32_16x16x32_bf16 v[12:15], v[168:171], v[224:227], v[12:15]
	v_mfma_f32_16x16x32_bf16 v[8:11], v[176:179], v[224:227], v[8:11]
	v_mfma_f32_16x16x32_bf16 v[52:55], v[180:183], v[196:199], v[52:55]
	v_mfma_f32_16x16x32_bf16 v[48:51], v[188:191], v[196:199], v[48:51]
	v_mfma_f32_16x16x32_bf16 v[36:39], v[180:183], v[204:207], v[36:39]
	v_mfma_f32_16x16x32_bf16 v[32:35], v[188:191], v[204:207], v[32:35]
	v_mfma_f32_16x16x32_bf16 v[20:23], v[180:183], v[212:215], v[20:23]
	v_mfma_f32_16x16x32_bf16 v[16:19], v[188:191], v[212:215], v[16:19]
	v_mfma_f32_16x16x32_bf16 v[4:7], v[180:183], v[220:223], v[4:7]
	v_mfma_f32_16x16x32_bf16 v[0:3], v[188:191], v[220:223], v[0:3]
	v_mfma_f32_16x16x32_bf16 v[52:55], v[184:187], v[200:203], v[52:55]
	v_mfma_f32_16x16x32_bf16 v[48:51], v[192:195], v[200:203], v[48:51]
	v_mfma_f32_16x16x32_bf16 v[36:39], v[184:187], v[208:211], v[36:39]
	v_mfma_f32_16x16x32_bf16 v[32:35], v[192:195], v[208:211], v[32:35]
	v_mfma_f32_16x16x32_bf16 v[20:23], v[184:187], v[216:219], v[20:23]
	v_mfma_f32_16x16x32_bf16 v[16:19], v[192:195], v[216:219], v[16:19]
	v_mfma_f32_16x16x32_bf16 v[4:7], v[184:187], v[224:227], v[4:7]
	v_mfma_f32_16x16x32_bf16 v[0:3], v[192:195], v[224:227], v[0:3]
	s_setprio 0
	s_barrier
	s_add_i32 s87, s87, 2
	s_add_u32 s54, s54, 0x100
	s_addc_u32 s55, s55, 0
	s_add_u32 s85, s85, 0x100
	s_addc_u32 s86, s86, 0
	s_cmp_gt_u32 s87, 29
	s_cbranch_scc0 .LBB0_1440
	s_and_b64 vcc, exec, s[14:15]
	s_cbranch_vccz .LBB0_1443
	s_barrier

; #define PG8_STAGE(bufoff, gbase, voff) do { _Pragma("unroll") for (int _i = 0; _i < 2; ++_i) \
;         __builtin_amdgcn_global_load_lds((const unsigned*)((const char*)(gbase) + (voff)[_i]), (PG8_LAS unsigned*)(lds + (bufoff) + ldsw + _i * 8192), 16, 0, 0); } while (0)
; #define PG8_LDA(dst, b, h) do { _Pragma("unroll") for (int m = 0; m < 4; ++m) _Pragma("unroll") for (int k = 0; k < 2; ++k) dst[m][k] = *(const PG8_LAS bf16x8*)(lds + PG8_SA(b, h) + aoff + m * 2048 + k * 1024); } while (0)
; #define PG8_LDB(dst, b, h) do { _Pragma("unroll") for (int n = 0; n < 2; ++n) _Pragma("unroll") for (int k = 0; k < 2; ++k) dst[n][k] = *(const PG8_LAS bf16x8*)(lds + PG8_SB(b, h) + boff + n * 2048 + k * 1024); } while (0)
; #define PG8_MMA(ai, bj, At, Bt) do { __builtin_amdgcn_s_setprio(1); _Pragma("unroll") for (int m = 0; m < 4; ++m) _Pragma("unroll") for (int n = 0; n < 2; ++n) _Pragma("unroll") for (int k = 0; k < 2; ++k) \
;         acc[ai][bj][m][n] = __builtin_amdgcn_mfma_f32_16x16x32_bf16(Bt[n][k], At[m][k], acc[ai][bj][m][n], 0, 0, 0); __builtin_amdgcn_s_setprio(0); } while (0)
; #define PG8_WAIT_V(n) asm volatile("s_waitcnt vmcnt(" #n ")" ::: "memory")
; #define PG8_WAIT_L(n) asm volatile("s_waitcnt lgkmcnt(" #n ")" ::: "memory")
; template <class Epi, class Sched, bool ALIGN_EPI = false, bool SP2 = false>
; __device__ __forceinline__ void gemm_phase(PG8_LAS unsigned char* lds, const Gemm g, const Sched& S, const Epi& E) {
;     ...
;             const bool last = (t == nt - 2);
;             const char* a1 = cA + (size_t)(t + 1) * kstep;
;             const char* a2 = last ? nA : cA + (size_t)(t + 2) * kstep; const char* b2 = last ? nB : cB + (size_t)(t + 2) * kstep;
;             const char* a3 = a2 + kstep; const char* b3 = b2 + kstep;
;             if (last && has_next) S.a_ready(nxt);
;             if constexpr (SP2) {
;             PG8_LDB(B0, 0, 0); PG8_LDB(B1, 0, 1); PG8_SCHED; PG8_LDA(At, 0, 0); PG8_STAGE(PG8_SA(1, 1), a1 + hstep, voffA);
;             PG8_WAIT_V(8); PG8_WAIT_L(0); PG8_BAR; PG8_MMA(0, 0, At, B0); PG8_MMA(0, 1, At, B1); PG8_BAR; PG8_SCHED;
;             PG8_LDA(At, 0, 1); PG8_STAGE(PG8_SB(0, 0), b2, voffB); PG8_STAGE(PG8_SB(0, 1), b2 + hstep, voffB); PG8_STAGE(PG8_SA(0, 0), a2, voffA);
;             PG8_WAIT_V(8); PG8_WAIT_L(0); PG8_BAR; PG8_MMA(1, 0, At, B0); PG8_MMA(1, 1, At, B1); PG8_BAR; PG8_SCHED;
.LBB0_1460:
	ds_read_b128 v[152:155], v147
	ds_read_b128 v[156:159], v147 offset:1024
	ds_read_b128 v[160:163], v147 offset:2048
	ds_read_b128 v[164:167], v147 offset:3072
	ds_read_b128 v[168:171], v148
	ds_read_b128 v[172:175], v148 offset:1024
	ds_read_b128 v[176:179], v148 offset:2048
	ds_read_b128 v[180:183], v148 offset:3072
	s_add_u32 s56, s54, 0xfffc0080
	s_addc_u32 s57, s55, -1
	s_cmp_eq_u32 s85, 12
	s_cselect_b32 s59, s47, s57
	s_cselect_b32 s58, s81, s56
	s_cselect_b32 s57, s45, s84
	s_cselect_b32 s56, s82, s83
	v_lshl_add_u64 v[216:217], s[54:55], 0, v[136:137]
	s_add_i32 m0, s43, 0xc000
	ds_read_b128 v[184:187], v149
	ds_read_b128 v[188:191], v149 offset:1024
	ds_read_b128 v[192:195], v149 offset:2048
	ds_read_b128 v[196:199], v149 offset:3072
	ds_read_b128 v[200:203], v149 offset:4096
	ds_read_b128 v[204:207], v149 offset:5120
	ds_read_b128 v[208:211], v149 offset:6144
	ds_read_b128 v[212:215], v149 offset:7168
	global_load_lds_dwordx4 v[216:217], off
	v_lshl_add_u64 v[216:217], s[54:55], 0, v[138:139]
	s_add_i32 m0, s43, 0xe000
	s_nop 0
	global_load_lds_dwordx4 v[216:217], off
	s_waitcnt vmcnt(8)
	s_waitcnt lgkmcnt(0)
	s_barrier
	s_setprio 1
	s_waitcnt lgkmcnt(0)
	v_mfma_f32_16x16x32_bf16 v[124:127], v[152:155], v[184:187], v[124:127]
	v_mfma_f32_16x16x32_bf16 v[120:123], v[160:163], v[184:187], v[120:123]
	v_mfma_f32_16x16x32_bf16 v[116:119], v[152:155], v[192:195], v[116:119]
	v_mfma_f32_16x16x32_bf16 v[112:115], v[160:163], v[192:195], v[112:115]
	v_mfma_f32_16x16x32_bf16 v[100:103], v[152:155], v[200:203], v[100:103]
	v_mfma_f32_16x16x32_bf16 v[96:99], v[160:163], v[200:203], v[96:99]
	v_mfma_f32_16x16x32_bf16 v[84:87], v[152:155], v[208:211], v[84:87]
	v_mfma_f32_16x16x32_bf16 v[80:83], v[160:163], v[208:211], v[80:83]
	v_mfma_f32_16x16x32_bf16 v[124:127], v[156:159], v[188:191], v[124:127]
	v_mfma_f32_16x16x32_bf16 v[120:123], v[164:167], v[188:191], v[120:123]
	v_mfma_f32_16x16x32_bf16 v[116:119], v[156:159], v[196:199], v[116:119]
	v_mfma_f32_16x16x32_bf16 v[112:115], v[164:167], v[196:199], v[112:115]
	v_mfma_f32_16x16x32_bf16 v[100:103], v[156:159], v[204:207], v[100:103]
	v_mfma_f32_16x16x32_bf16 v[96:99], v[164:167], v[204:207], v[96:99]
	v_mfma_f32_16x16x32_bf16 v[84:87], v[156:159], v[212:215], v[84:87]
	v_mfma_f32_16x16x32_bf16 v[80:83], v[164:167], v[212:215], v[80:83]
	v_mfma_f32_16x16x32_bf16 v[108:111], v[168:171], v[184:187], v[108:111]
	v_mfma_f32_16x16x32_bf16 v[104:107], v[176:179], v[184:187], v[104:107]
	v_mfma_f32_16x16x32_bf16 v[92:95], v[168:171], v[192:195], v[92:95]
	v_mfma_f32_16x16x32_bf16 v[88:91], v[176:179], v[192:195], v[88:91]
	v_mfma_f32_16x16x32_bf16 v[76:79], v[168:171], v[200:203], v[76:79]
	v_mfma_f32_16x16x32_bf16 v[72:75], v[176:179], v[200:203], v[72:75]
	v_mfma_f32_16x16x32_bf16 v[68:71], v[168:171], v[208:211], v[68:71]
	v_mfma_f32_16x16x32_bf16 v[64:67], v[176:179], v[208:211], v[64:67]
	v_mfma_f32_16x16x32_bf16 v[108:111], v[172:175], v[188:191], v[108:111]
	v_mfma_f32_16x16x32_bf16 v[104:107], v[180:183], v[188:191], v[104:107]
	v_mfma_f32_16x16x32_bf16 v[92:95], v[172:175], v[196:199], v[92:95]
	v_mfma_f32_16x16x32_bf16 v[88:91], v[180:183], v[196:199], v[88:91]
	v_mfma_f32_16x16x32_bf16 v[76:79], v[172:175], v[204:207], v[76:79]
	v_mfma_f32_16x16x32_bf16 v[72:75], v[180:183], v[204:207], v[72:75]
	v_mfma_f32_16x16x32_bf16 v[68:71], v[172:175], v[212:215], v[68:71]
	v_mfma_f32_16x16x32_bf16 v[64:67], v[180:183], v[212:215], v[64:67]
	s_setprio 0
	s_barrier
	s_add_i32 s86, s72, s60
	v_lshl_add_u64 v[216:217], s[56:57], 0, v[130:131]
	s_mov_b32 m0, s86
	ds_read_b128 v[184:187], v149 offset:16384
	ds_read_b128 v[188:191], v149 offset:17408
	ds_read_b128 v[192:195], v149 offset:18432
	ds_read_b128 v[196:199], v149 offset:19456
	ds_read_b128 v[200:203], v149 offset:20480
	ds_read_b128 v[204:207], v149 offset:21504
	ds_read_b128 v[208:211], v149 offset:22528
	ds_read_b128 v[212:215], v149 offset:23552
	global_load_lds_dwordx4 v[216:217], off
	s_add_i32 m0, s86, 0x2000
	s_add_u32 s86, s56, 0x40000
	v_lshl_add_u64 v[218:219], s[56:57], 0, v[134:135]
	s_addc_u32 s87, s57, 0
	s_add_i32 s88, s73, s60
	global_load_lds_dwordx4 v[218:219], off
	v_lshl_add_u64 v[220:221], s[86:87], 0, v[130:131]
	s_mov_b32 m0, s88
	v_lshl_add_u64 v[222:223], s[58:59], 0, v[132:133]
	global_load_lds_dwordx4 v[220:221], off
	v_lshl_add_u64 v[220:221], s[86:87], 0, v[134:135]
	s_add_i32 m0, s88, 0x2000
	s_nop 0
	global_load_lds_dwordx4 v[220:221], off
	v_lshl_add_u64 v[220:221], s[58:59], 0, v[128:129]
	s_mov_b32 m0, s43
	s_nop 0
	global_load_lds_dwordx4 v[220:221], off
	s_mov_b32 m0, s50
	s_nop 0
	global_load_lds_dwordx4 v[222:223], off
	s_waitcnt vmcnt(8)
	s_waitcnt lgkmcnt(0)
	s_barrier
; #define PG8_STAGE(bufoff, gbase, voff) do { _Pragma("unroll") for (int _i = 0; _i < 2; ++_i) \
;         __builtin_amdgcn_global_load_lds((const unsigned*)((const char*)(gbase) + (voff)[_i]), (PG8_LAS unsigned*)(lds + (bufoff) + ldsw + _i * 8192), 16, 0, 0); } while (0)
; #define PG8_LDA(dst, b, h) do { _Pragma("unroll") for (int m = 0; m < 4; ++m) _Pragma("unroll") for (int k = 0; k < 2; ++k) dst[m][k] = *(const PG8_LAS bf16x8*)(lds + PG8_SA(b, h) + aoff + m * 2048 + k * 1024); } while (0)
; #define PG8_LDB(dst, b, h) do { _Pragma("unroll") for (int n = 0; n < 2; ++n) _Pragma("unroll") for (int k = 0; k < 2; ++k) dst[n][k] = *(const PG8_LAS bf16x8*)(lds + PG8_SB(b, h) + boff + n * 2048 + k * 1024); } while (0)
; #define PG8_MMA(ai, bj, At, Bt) do { __builtin_amdgcn_s_setprio(1); _Pragma("unroll") for (int m = 0; m < 4; ++m) _Pragma("unroll") for (int n = 0; n < 2; ++n) _Pragma("unroll") for (int k = 0; k < 2; ++k) \
;         acc[ai][bj][m][n] = __builtin_amdgcn_mfma_f32_16x16x32_bf16(Bt[n][k], At[m][k], acc[ai][bj][m][n], 0, 0, 0); __builtin_amdgcn_s_setprio(0); } while (0)
; #define PG8_WAIT_V(n) asm volatile("s_waitcnt vmcnt(" #n ")" ::: "memory")
; #define PG8_WAIT_L(n) asm volatile("s_waitcnt lgkmcnt(" #n ")" ::: "memory")
; #define PG8_BAR __builtin_amdgcn_s_barrier()
; #define PG8_SCHED __builtin_amdgcn_sched_barrier(0)
; template <class Epi, class Sched, bool ALIGN_EPI = false, bool SP2 = false>
; __device__ __forceinline__ void gemm_phase(PG8_LAS unsigned char* lds, const Gemm g, const Sched& S, const Epi& E) {
;     ...
;             PG8_WAIT_V(8); PG8_WAIT_L(0); PG8_BAR; PG8_MMA(1, 0, At, B0); PG8_MMA(1, 1, At, B1); PG8_BAR; PG8_SCHED;
;             PG8_LDB(B0, 1, 0); PG8_LDB(B1, 1, 1); PG8_SCHED; PG8_LDA(At, 1, 0); PG8_STAGE(PG8_SA(0, 1), a2 + hstep, voffA);
;             PG8_WAIT_V(8); PG8_WAIT_L(0); PG8_BAR; PG8_MMA(0, 0, At, B0); PG8_MMA(0, 1, At, B1); PG8_BAR; PG8_SCHED;
	s_setprio 1
	s_waitcnt lgkmcnt(0)
	v_mfma_f32_16x16x32_bf16 v[60:63], v[152:155], v[184:187], v[60:63]
	v_mfma_f32_16x16x32_bf16 v[56:59], v[160:163], v[184:187], v[56:59]
	v_mfma_f32_16x16x32_bf16 v[52:55], v[152:155], v[192:195], v[52:55]
	v_mfma_f32_16x16x32_bf16 v[48:51], v[160:163], v[192:195], v[48:51]
	v_mfma_f32_16x16x32_bf16 v[36:39], v[152:155], v[200:203], v[36:39]
	v_mfma_f32_16x16x32_bf16 v[32:35], v[160:163], v[200:203], v[32:35]
	v_mfma_f32_16x16x32_bf16 v[20:23], v[152:155], v[208:211], v[20:23]
	v_mfma_f32_16x16x32_bf16 v[16:19], v[160:163], v[208:211], v[16:19]
	v_mfma_f32_16x16x32_bf16 v[60:63], v[156:159], v[188:191], v[60:63]
	v_mfma_f32_16x16x32_bf16 v[56:59], v[164:167], v[188:191], v[56:59]
	v_mfma_f32_16x16x32_bf16 v[52:55], v[156:159], v[196:199], v[52:55]
	v_mfma_f32_16x16x32_bf16 v[48:51], v[164:167], v[196:199], v[48:51]
	v_mfma_f32_16x16x32_bf16 v[36:39], v[156:159], v[204:207], v[36:39]
	v_mfma_f32_16x16x32_bf16 v[32:35], v[164:167], v[204:207], v[32:35]
	v_mfma_f32_16x16x32_bf16 v[20:23], v[156:159], v[212:215], v[20:23]
	v_mfma_f32_16x16x32_bf16 v[16:19], v[164:167], v[212:215], v[16:19]
	v_mfma_f32_16x16x32_bf16 v[44:47], v[168:171], v[184:187], v[44:47]
	v_mfma_f32_16x16x32_bf16 v[40:43], v[176:179], v[184:187], v[40:43]
	v_mfma_f32_16x16x32_bf16 v[28:31], v[168:171], v[192:195], v[28:31]
	v_mfma_f32_16x16x32_bf16 v[24:27], v[176:179], v[192:195], v[24:27]
	v_mfma_f32_16x16x32_bf16 v[12:15], v[168:171], v[200:203], v[12:15]
	v_mfma_f32_16x16x32_bf16 v[8:11], v[176:179], v[200:203], v[8:11]
	v_mfma_f32_16x16x32_bf16 v[4:7], v[168:171], v[208:211], v[4:7]
	v_mfma_f32_16x16x32_bf16 v[0:3], v[176:179], v[208:211], v[0:3]
	v_mfma_f32_16x16x32_bf16 v[44:47], v[172:175], v[188:191], v[44:47]
	v_mfma_f32_16x16x32_bf16 v[40:43], v[180:183], v[188:191], v[40:43]
	v_mfma_f32_16x16x32_bf16 v[28:31], v[172:175], v[196:199], v[28:31]
	v_mfma_f32_16x16x32_bf16 v[24:27], v[180:183], v[196:199], v[24:27]
	v_mfma_f32_16x16x32_bf16 v[12:15], v[172:175], v[204:207], v[12:15]
	v_mfma_f32_16x16x32_bf16 v[8:11], v[180:183], v[204:207], v[8:11]
	v_mfma_f32_16x16x32_bf16 v[4:7], v[172:175], v[212:215], v[4:7]
	v_mfma_f32_16x16x32_bf16 v[0:3], v[180:183], v[212:215], v[0:3]
	s_setprio 0
	s_barrier
	s_add_i32 s86, 0, 0x18000
	s_add_i32 s87, 0, 0x1c000
	v_add_u32_e32 v164, s86, v146
	v_add_u32_e32 v180, s87, v146
	ds_read_b128 v[152:155], v164
	ds_read_b128 v[156:159], v164 offset:1024
	ds_read_b128 v[160:163], v164 offset:2048
	ds_read_b128 v[164:167], v164 offset:3072
	ds_read_b128 v[168:171], v180
	ds_read_b128 v[172:175], v180 offset:1024
	ds_read_b128 v[176:179], v180 offset:2048
	ds_read_b128 v[180:183], v180 offset:3072
	s_add_u32 s58, s58, 0x40000
	s_addc_u32 s59, s59, 0
	s_mov_b32 m0, s51
	v_lshl_add_u64 v[224:225], s[58:59], 0, v[128:129]
	ds_read_b128 v[184:187], v149 offset:32768
	ds_read_b128 v[188:191], v149 offset:33792
	ds_read_b128 v[192:195], v149 offset:34816
	ds_read_b128 v[196:199], v149 offset:35840
	ds_read_b128 v[200:203], v149 offset:36864
	ds_read_b128 v[204:207], v149 offset:37888
	ds_read_b128 v[208:211], v149 offset:38912
	ds_read_b128 v[212:215], v149 offset:39936
	global_load_lds_dwordx4 v[224:225], off
	v_lshl_add_u64 v[224:225], s[58:59], 0, v[132:133]
	s_mov_b32 m0, s65
	s_nop 0
	global_load_lds_dwordx4 v[224:225], off
	s_waitcnt vmcnt(8)
	s_waitcnt lgkmcnt(0)
	s_barrier
	s_setprio 1
	s_waitcnt lgkmcnt(0)
	v_mfma_f32_16x16x32_bf16 v[124:127], v[152:155], v[184:187], v[124:127]
	v_mfma_f32_16x16x32_bf16 v[120:123], v[160:163], v[184:187], v[120:123]
	v_mfma_f32_16x16x32_bf16 v[116:119], v[152:155], v[192:195], v[116:119]
	v_mfma_f32_16x16x32_bf16 v[112:115], v[160:163], v[192:195], v[112:115]
	v_mfma_f32_16x16x32_bf16 v[100:103], v[152:155], v[200:203], v[100:103]
	v_mfma_f32_16x16x32_bf16 v[96:99], v[160:163], v[200:203], v[96:99]
	v_mfma_f32_16x16x32_bf16 v[84:87], v[152:155], v[208:211], v[84:87]
	v_mfma_f32_16x16x32_bf16 v[80:83], v[160:163], v[208:211], v[80:83]
	v_mfma_f32_16x16x32_bf16 v[124:127], v[156:159], v[188:191], v[124:127]
	v_mfma_f32_16x16x32_bf16 v[120:123], v[164:167], v[188:191], v[120:123]
	v_mfma_f32_16x16x32_bf16 v[116:119], v[156:159], v[196:199], v[116:119]
	v_mfma_f32_16x16x32_bf16 v[112:115], v[164:167], v[196:199], v[112:115]
	v_mfma_f32_16x16x32_bf16 v[100:103], v[156:159], v[204:207], v[100:103]
	v_mfma_f32_16x16x32_bf16 v[96:99], v[164:167], v[204:207], v[96:99]
	v_mfma_f32_16x16x32_bf16 v[84:87], v[156:159], v[212:215], v[84:87]
	v_mfma_f32_16x16x32_bf16 v[80:83], v[164:167], v[212:215], v[80:83]
	v_mfma_f32_16x16x32_bf16 v[108:111], v[168:171], v[184:187], v[108:111]
	v_mfma_f32_16x16x32_bf16 v[104:107], v[176:179], v[184:187], v[104:107]
	v_mfma_f32_16x16x32_bf16 v[92:95], v[168:171], v[192:195], v[92:95]
	v_mfma_f32_16x16x32_bf16 v[88:91], v[176:179], v[192:195], v[88:91]
	v_mfma_f32_16x16x32_bf16 v[76:79], v[168:171], v[200:203], v[76:79]
	v_mfma_f32_16x16x32_bf16 v[72:75], v[176:179], v[200:203], v[72:75]
	v_mfma_f32_16x16x32_bf16 v[68:71], v[168:171], v[208:211], v[68:71]
	v_mfma_f32_16x16x32_bf16 v[64:67], v[176:179], v[208:211], v[64:67]
	v_mfma_f32_16x16x32_bf16 v[108:111], v[172:175], v[188:191], v[108:111]
	v_mfma_f32_16x16x32_bf16 v[104:107], v[180:183], v[188:191], v[104:107]
	v_mfma_f32_16x16x32_bf16 v[92:95], v[172:175], v[196:199], v[92:95]
	v_mfma_f32_16x16x32_bf16 v[88:91], v[180:183], v[196:199], v[88:91]
	v_mfma_f32_16x16x32_bf16 v[76:79], v[172:175], v[204:207], v[76:79]
	v_mfma_f32_16x16x32_bf16 v[72:75], v[180:183], v[204:207], v[72:75]
	v_mfma_f32_16x16x32_bf16 v[68:71], v[172:175], v[212:215], v[68:71]
	v_mfma_f32_16x16x32_bf16 v[64:67], v[180:183], v[212:215], v[64:67]
	s_setprio 0
	s_barrier
; #define PG8_STAGE(bufoff, gbase, voff) do { _Pragma("unroll") for (int _i = 0; _i < 2; ++_i) \
;         __builtin_amdgcn_global_load_lds((const unsigned*)((const char*)(gbase) + (voff)[_i]), (PG8_LAS unsigned*)(lds + (bufoff) + ldsw + _i * 8192), 16, 0, 0); } while (0)
; #define PG8_LDA(dst, b, h) do { _Pragma("unroll") for (int m = 0; m < 4; ++m) _Pragma("unroll") for (int k = 0; k < 2; ++k) dst[m][k] = *(const PG8_LAS bf16x8*)(lds + PG8_SA(b, h) + aoff + m * 2048 + k * 1024); } while (0)
; #define PG8_MMA(ai, bj, At, Bt) do { __builtin_amdgcn_s_setprio(1); _Pragma("unroll") for (int m = 0; m < 4; ++m) _Pragma("unroll") for (int n = 0; n < 2; ++n) _Pragma("unroll") for (int k = 0; k < 2; ++k) \
;         acc[ai][bj][m][n] = __builtin_amdgcn_mfma_f32_16x16x32_bf16(Bt[n][k], At[m][k], acc[ai][bj][m][n], 0, 0, 0); __builtin_amdgcn_s_setprio(0); } while (0)
; #define PG8_WAIT_V(n) asm volatile("s_waitcnt vmcnt(" #n ")" ::: "memory")
; #define PG8_WAIT_L(n) asm volatile("s_waitcnt lgkmcnt(" #n ")" ::: "memory")
; #define PG8_BAR __builtin_amdgcn_s_barrier()
; #define PG8_SCHED __builtin_amdgcn_sched_barrier(0)
; template <class Epi, class Sched, bool ALIGN_EPI = false, bool SP2 = false>
; __device__ __forceinline__ void gemm_phase(PG8_LAS unsigned char* lds, const Gemm g, const Sched& S, const Epi& E) {
;     ...
;             PG8_LDA(At, 1, 1); PG8_STAGE(PG8_SB(1, 0), b3, voffB); PG8_STAGE(PG8_SB(1, 1), b3 + hstep, voffB); PG8_STAGE(PG8_SA(1, 0), a3, voffA);
;             PG8_WAIT_V(8); PG8_WAIT_L(0); PG8_BAR; PG8_MMA(1, 0, At, B0); PG8_MMA(1, 1, At, B1); PG8_BAR; PG8_SCHED;
;     ...
;         if constexpr (ALIGN_EPI) { if (wr == 0) PG8_BAR; }
	s_add_i32 s58, s86, s60
	v_lshl_add_u64 v[216:217], v[216:217], 0, s[10:11]
	s_mov_b32 m0, s58
	ds_read_b128 v[184:187], v149 offset:49152
	ds_read_b128 v[188:191], v149 offset:50176
	ds_read_b128 v[192:195], v149 offset:51200
	ds_read_b128 v[196:199], v149 offset:52224
	ds_read_b128 v[200:203], v149 offset:53248
	ds_read_b128 v[204:207], v149 offset:54272
	ds_read_b128 v[208:211], v149 offset:55296
	ds_read_b128 v[212:215], v149 offset:56320
	global_load_lds_dwordx4 v[216:217], off
	s_add_i32 m0, s58, 0x2000
	s_add_u32 s56, s56, 0x40080
	v_lshl_add_u64 v[216:217], v[218:219], 0, s[10:11]
	s_addc_u32 s57, s57, 0
	s_add_i32 s58, s87, s60
	global_load_lds_dwordx4 v[216:217], off
	v_lshl_add_u64 v[216:217], s[56:57], 0, v[130:131]
	s_mov_b32 m0, s58
	s_nop 0
	global_load_lds_dwordx4 v[216:217], off
	v_lshl_add_u64 v[216:217], s[56:57], 0, v[134:135]
	s_add_i32 m0, s58, 0x2000
	s_nop 0
	global_load_lds_dwordx4 v[216:217], off
	v_lshl_add_u64 v[216:217], v[220:221], 0, s[10:11]
	s_mov_b32 m0, s70
	s_nop 0
	global_load_lds_dwordx4 v[216:217], off
	v_lshl_add_u64 v[216:217], v[222:223], 0, s[10:11]
	s_mov_b32 m0, s71
	s_nop 0
	global_load_lds_dwordx4 v[216:217], off
	s_waitcnt vmcnt(8)
	s_waitcnt lgkmcnt(0)
	s_barrier
	s_setprio 1
	s_waitcnt lgkmcnt(0)
	v_mfma_f32_16x16x32_bf16 v[60:63], v[152:155], v[184:187], v[60:63]
	v_mfma_f32_16x16x32_bf16 v[56:59], v[160:163], v[184:187], v[56:59]
	v_mfma_f32_16x16x32_bf16 v[52:55], v[152:155], v[192:195], v[52:55]
	v_mfma_f32_16x16x32_bf16 v[48:51], v[160:163], v[192:195], v[48:51]
	v_mfma_f32_16x16x32_bf16 v[36:39], v[152:155], v[200:203], v[36:39]
	v_mfma_f32_16x16x32_bf16 v[32:35], v[160:163], v[200:203], v[32:35]
	v_mfma_f32_16x16x32_bf16 v[20:23], v[152:155], v[208:211], v[20:23]
	v_mfma_f32_16x16x32_bf16 v[16:19], v[160:163], v[208:211], v[16:19]
	v_mfma_f32_16x16x32_bf16 v[60:63], v[156:159], v[188:191], v[60:63]
	v_mfma_f32_16x16x32_bf16 v[56:59], v[164:167], v[188:191], v[56:59]
	v_mfma_f32_16x16x32_bf16 v[52:55], v[156:159], v[196:199], v[52:55]
	v_mfma_f32_16x16x32_bf16 v[48:51], v[164:167], v[196:199], v[48:51]
	v_mfma_f32_16x16x32_bf16 v[36:39], v[156:159], v[204:207], v[36:39]
	v_mfma_f32_16x16x32_bf16 v[32:35], v[164:167], v[204:207], v[32:35]
	v_mfma_f32_16x16x32_bf16 v[20:23], v[156:159], v[212:215], v[20:23]
	v_mfma_f32_16x16x32_bf16 v[16:19], v[164:167], v[212:215], v[16:19]
	v_mfma_f32_16x16x32_bf16 v[44:47], v[168:171], v[184:187], v[44:47]
	v_mfma_f32_16x16x32_bf16 v[40:43], v[176:179], v[184:187], v[40:43]
	v_mfma_f32_16x16x32_bf16 v[28:31], v[168:171], v[192:195], v[28:31]
	v_mfma_f32_16x16x32_bf16 v[24:27], v[176:179], v[192:195], v[24:27]
	v_mfma_f32_16x16x32_bf16 v[12:15], v[168:171], v[200:203], v[12:15]
	v_mfma_f32_16x16x32_bf16 v[8:11], v[176:179], v[200:203], v[8:11]
	v_mfma_f32_16x16x32_bf16 v[4:7], v[168:171], v[208:211], v[4:7]
	v_mfma_f32_16x16x32_bf16 v[0:3], v[176:179], v[208:211], v[0:3]
	v_mfma_f32_16x16x32_bf16 v[44:47], v[172:175], v[188:191], v[44:47]
	v_mfma_f32_16x16x32_bf16 v[40:43], v[180:183], v[188:191], v[40:43]
	v_mfma_f32_16x16x32_bf16 v[28:31], v[172:175], v[196:199], v[28:31]
	v_mfma_f32_16x16x32_bf16 v[24:27], v[180:183], v[196:199], v[24:27]
	v_mfma_f32_16x16x32_bf16 v[12:15], v[172:175], v[204:207], v[12:15]
	v_mfma_f32_16x16x32_bf16 v[8:11], v[180:183], v[204:207], v[8:11]
	v_mfma_f32_16x16x32_bf16 v[4:7], v[172:175], v[212:215], v[4:7]
	v_mfma_f32_16x16x32_bf16 v[0:3], v[180:183], v[212:215], v[0:3]
	s_setprio 0
	s_barrier
	s_add_i32 s85, s85, 2
	s_add_u32 s54, s54, 0x100
	s_addc_u32 s55, s55, 0
	s_add_u32 s83, s83, 0x100
	s_addc_u32 s84, s84, 0
	s_cmp_gt_u32 s85, 13
	s_cbranch_scc0 .LBB0_1460
	s_and_b64 vcc, exec, s[12:13]
	s_cbranch_vccz .LBB0_1463
	s_barrier

; #define PG8_STAGE(bufoff, gbase, voff) do { _Pragma("unroll") for (int _i = 0; _i < 2; ++_i) \
;         __builtin_amdgcn_global_load_lds((const unsigned*)((const char*)(gbase) + (voff)[_i]), (PG8_LAS unsigned*)(lds + (bufoff) + ldsw + _i * 8192), 16, 0, 0); } while (0)
; #define PG8_LDA(dst, b, h) do { _Pragma("unroll") for (int m = 0; m < 4; ++m) _Pragma("unroll") for (int k = 0; k < 2; ++k) dst[m][k] = *(const PG8_LAS bf16x8*)(lds + PG8_SA(b, h) + aoff + m * 2048 + k * 1024); } while (0)
; #define PG8_LDB(dst, b, h) do { _Pragma("unroll") for (int n = 0; n < 2; ++n) _Pragma("unroll") for (int k = 0; k < 2; ++k) dst[n][k] = *(const PG8_LAS bf16x8*)(lds + PG8_SB(b, h) + boff + n * 2048 + k * 1024); } while (0)
; #define PG8_MMA(ai, bj, At, Bt) do { __builtin_amdgcn_s_setprio(1); _Pragma("unroll") for (int m = 0; m < 4; ++m) _Pragma("unroll") for (int n = 0; n < 2; ++n) _Pragma("unroll") for (int k = 0; k < 2; ++k) \
;         acc[ai][bj][m][n] = __builtin_amdgcn_mfma_f32_16x16x32_bf16(Bt[n][k], At[m][k], acc[ai][bj][m][n], 0, 0, 0); __builtin_amdgcn_s_setprio(0); } while (0)
; #define PG8_WAIT_V(n) asm volatile("s_waitcnt vmcnt(" #n ")" ::: "memory")
; #define PG8_WAIT_L(n) asm volatile("s_waitcnt lgkmcnt(" #n ")" ::: "memory")
; template <class Epi, class Sched, bool ALIGN_EPI = false, bool SP2 = false>
; __device__ __forceinline__ void gemm_phase(PG8_LAS unsigned char* lds, const Gemm g, const Sched& S, const Epi& E) {
;     ...
;             const bool last = (t == nt - 2);
;             const char* a1 = cA + (size_t)(t + 1) * kstep;
;             const char* a2 = last ? nA : cA + (size_t)(t + 2) * kstep; const char* b2 = last ? nB : cB + (size_t)(t + 2) * kstep;
;             const char* a3 = a2 + kstep; const char* b3 = b2 + kstep;
;             if (last && has_next) S.a_ready(nxt);
;             if constexpr (SP2) {
;             PG8_LDB(B0, 0, 0); PG8_LDB(B1, 0, 1); PG8_SCHED; PG8_LDA(At, 0, 0); PG8_STAGE(PG8_SA(1, 1), a1 + hstep, voffA);
;             PG8_WAIT_V(8); PG8_WAIT_L(0); PG8_BAR; PG8_MMA(0, 0, At, B0); PG8_MMA(0, 1, At, B1); PG8_BAR; PG8_SCHED;
;             PG8_LDA(At, 0, 1); PG8_STAGE(PG8_SB(0, 0), b2, voffB); PG8_STAGE(PG8_SB(0, 1), b2 + hstep, voffB); PG8_STAGE(PG8_SA(0, 0), a2, voffA);
;             PG8_WAIT_V(8); PG8_WAIT_L(0); PG8_BAR; PG8_MMA(1, 0, At, B0); PG8_MMA(1, 1, At, B1); PG8_BAR; PG8_SCHED;
.LBB0_1535:
	ds_read_b128 v[146:149], v153
	ds_read_b128 v[156:159], v153 offset:1024
	ds_read_b128 v[160:163], v153 offset:2048
	ds_read_b128 v[164:167], v153 offset:3072
	ds_read_b128 v[168:171], v154
	ds_read_b128 v[172:175], v154 offset:1024
	ds_read_b128 v[176:179], v154 offset:2048
	ds_read_b128 v[180:183], v154 offset:3072
	s_add_u32 s44, s42, 0xfffc0080
	s_addc_u32 s45, s43, -1
	s_cmp_eq_u32 s70, 12
	s_cselect_b32 s47, s23, s45
	s_cselect_b32 s46, s66, s44
	s_cselect_b32 s45, s19, s69
	s_cselect_b32 s44, s67, s68
	v_lshl_add_u64 v[216:217], s[42:43], 0, v[136:137]
	s_add_i32 m0, s41, 0xc000
	ds_read_b128 v[184:187], v155
	ds_read_b128 v[188:191], v155 offset:1024
	ds_read_b128 v[192:195], v155 offset:2048
	ds_read_b128 v[196:199], v155 offset:3072
	ds_read_b128 v[200:203], v155 offset:4096
	ds_read_b128 v[204:207], v155 offset:5120
	ds_read_b128 v[208:211], v155 offset:6144
	ds_read_b128 v[212:215], v155 offset:7168
	global_load_lds_dwordx4 v[216:217], off
	v_lshl_add_u64 v[216:217], s[42:43], 0, v[138:139]
	s_add_i32 m0, s41, 0xe000
	s_nop 0
	global_load_lds_dwordx4 v[216:217], off
	s_waitcnt vmcnt(8)
	s_waitcnt lgkmcnt(0)
	s_barrier
	s_setprio 1
	s_waitcnt lgkmcnt(0)
	v_mfma_f32_16x16x32_bf16 v[124:127], v[146:149], v[184:187], v[124:127]
	v_mfma_f32_16x16x32_bf16 v[120:123], v[160:163], v[184:187], v[120:123]
	v_mfma_f32_16x16x32_bf16 v[108:111], v[146:149], v[192:195], v[108:111]
	v_mfma_f32_16x16x32_bf16 v[104:107], v[160:163], v[192:195], v[104:107]
	v_mfma_f32_16x16x32_bf16 v[92:95], v[146:149], v[200:203], v[92:95]
	v_mfma_f32_16x16x32_bf16 v[88:91], v[160:163], v[200:203], v[88:91]
	v_mfma_f32_16x16x32_bf16 v[76:79], v[146:149], v[208:211], v[76:79]
	v_mfma_f32_16x16x32_bf16 v[72:75], v[160:163], v[208:211], v[72:75]
	v_mfma_f32_16x16x32_bf16 v[124:127], v[156:159], v[188:191], v[124:127]
	v_mfma_f32_16x16x32_bf16 v[120:123], v[164:167], v[188:191], v[120:123]
	v_mfma_f32_16x16x32_bf16 v[108:111], v[156:159], v[196:199], v[108:111]
	v_mfma_f32_16x16x32_bf16 v[104:107], v[164:167], v[196:199], v[104:107]
	v_mfma_f32_16x16x32_bf16 v[92:95], v[156:159], v[204:207], v[92:95]
	v_mfma_f32_16x16x32_bf16 v[88:91], v[164:167], v[204:207], v[88:91]
	v_mfma_f32_16x16x32_bf16 v[76:79], v[156:159], v[212:215], v[76:79]
	v_mfma_f32_16x16x32_bf16 v[72:75], v[164:167], v[212:215], v[72:75]
	v_mfma_f32_16x16x32_bf16 v[116:119], v[168:171], v[184:187], v[116:119]
	v_mfma_f32_16x16x32_bf16 v[112:115], v[176:179], v[184:187], v[112:115]
	v_mfma_f32_16x16x32_bf16 v[100:103], v[168:171], v[192:195], v[100:103]
	v_mfma_f32_16x16x32_bf16 v[96:99], v[176:179], v[192:195], v[96:99]
	v_mfma_f32_16x16x32_bf16 v[84:87], v[168:171], v[200:203], v[84:87]
	v_mfma_f32_16x16x32_bf16 v[80:83], v[176:179], v[200:203], v[80:83]
	v_mfma_f32_16x16x32_bf16 v[68:71], v[168:171], v[208:211], v[68:71]
	v_mfma_f32_16x16x32_bf16 v[64:67], v[176:179], v[208:211], v[64:67]
	v_mfma_f32_16x16x32_bf16 v[116:119], v[172:175], v[188:191], v[116:119]
	v_mfma_f32_16x16x32_bf16 v[112:115], v[180:183], v[188:191], v[112:115]
	v_mfma_f32_16x16x32_bf16 v[100:103], v[172:175], v[196:199], v[100:103]
	v_mfma_f32_16x16x32_bf16 v[96:99], v[180:183], v[196:199], v[96:99]
	v_mfma_f32_16x16x32_bf16 v[84:87], v[172:175], v[204:207], v[84:87]
	v_mfma_f32_16x16x32_bf16 v[80:83], v[180:183], v[204:207], v[80:83]
	v_mfma_f32_16x16x32_bf16 v[68:71], v[172:175], v[212:215], v[68:71]
	v_mfma_f32_16x16x32_bf16 v[64:67], v[180:183], v[212:215], v[64:67]
	s_setprio 0
	s_barrier
	s_add_i32 s71, s62, s50
	v_lshl_add_u64 v[216:217], s[44:45], 0, v[130:131]
	s_mov_b32 m0, s71
	ds_read_b128 v[184:187], v155 offset:16384
	ds_read_b128 v[188:191], v155 offset:17408
	ds_read_b128 v[192:195], v155 offset:18432
	ds_read_b128 v[196:199], v155 offset:19456
	ds_read_b128 v[200:203], v155 offset:20480
	ds_read_b128 v[204:207], v155 offset:21504
	ds_read_b128 v[208:211], v155 offset:22528
	ds_read_b128 v[212:215], v155 offset:23552
	global_load_lds_dwordx4 v[216:217], off
	s_add_i32 m0, s71, 0x2000
	s_add_u32 s72, s44, 0x40000
	v_lshl_add_u64 v[218:219], s[44:45], 0, v[134:135]
	s_addc_u32 s73, s45, 0
	s_add_i32 s71, s63, s50
	global_load_lds_dwordx4 v[218:219], off
	v_lshl_add_u64 v[220:221], s[72:73], 0, v[130:131]
	s_mov_b32 m0, s71
	v_lshl_add_u64 v[222:223], s[46:47], 0, v[132:133]
	global_load_lds_dwordx4 v[220:221], off
	v_lshl_add_u64 v[220:221], s[72:73], 0, v[134:135]
	s_add_i32 m0, s71, 0x2000
	s_nop 0
	global_load_lds_dwordx4 v[220:221], off
	v_lshl_add_u64 v[220:221], s[46:47], 0, v[128:129]
	s_mov_b32 m0, s41
	s_nop 0
	global_load_lds_dwordx4 v[220:221], off
	s_mov_b32 m0, s52
	s_nop 0
	global_load_lds_dwordx4 v[222:223], off
	s_waitcnt vmcnt(8)
	s_waitcnt lgkmcnt(0)
	s_barrier
; #define PG8_STAGE(bufoff, gbase, voff) do { _Pragma("unroll") for (int _i = 0; _i < 2; ++_i) \
;         __builtin_amdgcn_global_load_lds((const unsigned*)((const char*)(gbase) + (voff)[_i]), (PG8_LAS unsigned*)(lds + (bufoff) + ldsw + _i * 8192), 16, 0, 0); } while (0)
; #define PG8_LDA(dst, b, h) do { _Pragma("unroll") for (int m = 0; m < 4; ++m) _Pragma("unroll") for (int k = 0; k < 2; ++k) dst[m][k] = *(const PG8_LAS bf16x8*)(lds + PG8_SA(b, h) + aoff + m * 2048 + k * 1024); } while (0)
; #define PG8_LDB(dst, b, h) do { _Pragma("unroll") for (int n = 0; n < 2; ++n) _Pragma("unroll") for (int k = 0; k < 2; ++k) dst[n][k] = *(const PG8_LAS bf16x8*)(lds + PG8_SB(b, h) + boff + n * 2048 + k * 1024); } while (0)
; #define PG8_MMA(ai, bj, At, Bt) do { __builtin_amdgcn_s_setprio(1); _Pragma("unroll") for (int m = 0; m < 4; ++m) _Pragma("unroll") for (int n = 0; n < 2; ++n) _Pragma("unroll") for (int k = 0; k < 2; ++k) \
;         acc[ai][bj][m][n] = __builtin_amdgcn_mfma_f32_16x16x32_bf16(Bt[n][k], At[m][k], acc[ai][bj][m][n], 0, 0, 0); __builtin_amdgcn_s_setprio(0); } while (0)
; #define PG8_WAIT_V(n) asm volatile("s_waitcnt vmcnt(" #n ")" ::: "memory")
; #define PG8_WAIT_L(n) asm volatile("s_waitcnt lgkmcnt(" #n ")" ::: "memory")
; #define PG8_BAR __builtin_amdgcn_s_barrier()
; #define PG8_SCHED __builtin_amdgcn_sched_barrier(0)
; template <class Epi, class Sched, bool ALIGN_EPI = false, bool SP2 = false>
; __device__ __forceinline__ void gemm_phase(PG8_LAS unsigned char* lds, const Gemm g, const Sched& S, const Epi& E) {
;     ...
;             PG8_WAIT_V(8); PG8_WAIT_L(0); PG8_BAR; PG8_MMA(1, 0, At, B0); PG8_MMA(1, 1, At, B1); PG8_BAR; PG8_SCHED;
;             PG8_LDB(B0, 1, 0); PG8_LDB(B1, 1, 1); PG8_SCHED; PG8_LDA(At, 1, 0); PG8_STAGE(PG8_SA(0, 1), a2 + hstep, voffA);
;             PG8_WAIT_V(8); PG8_WAIT_L(0); PG8_BAR; PG8_MMA(0, 0, At, B0); PG8_MMA(0, 1, At, B1); PG8_BAR; PG8_SCHED;
	s_setprio 1
	s_waitcnt lgkmcnt(0)
	v_mfma_f32_16x16x32_bf16 v[60:63], v[146:149], v[184:187], v[60:63]
	v_mfma_f32_16x16x32_bf16 v[56:59], v[160:163], v[184:187], v[56:59]
	v_mfma_f32_16x16x32_bf16 v[44:47], v[146:149], v[192:195], v[44:47]
	v_mfma_f32_16x16x32_bf16 v[40:43], v[160:163], v[192:195], v[40:43]
	v_mfma_f32_16x16x32_bf16 v[28:31], v[146:149], v[200:203], v[28:31]
	v_mfma_f32_16x16x32_bf16 v[24:27], v[160:163], v[200:203], v[24:27]
	v_mfma_f32_16x16x32_bf16 v[12:15], v[146:149], v[208:211], v[12:15]
	v_mfma_f32_16x16x32_bf16 v[8:11], v[160:163], v[208:211], v[8:11]
	v_mfma_f32_16x16x32_bf16 v[60:63], v[156:159], v[188:191], v[60:63]
	v_mfma_f32_16x16x32_bf16 v[56:59], v[164:167], v[188:191], v[56:59]
	v_mfma_f32_16x16x32_bf16 v[44:47], v[156:159], v[196:199], v[44:47]
	v_mfma_f32_16x16x32_bf16 v[40:43], v[164:167], v[196:199], v[40:43]
	v_mfma_f32_16x16x32_bf16 v[28:31], v[156:159], v[204:207], v[28:31]
	v_mfma_f32_16x16x32_bf16 v[24:27], v[164:167], v[204:207], v[24:27]
	v_mfma_f32_16x16x32_bf16 v[12:15], v[156:159], v[212:215], v[12:15]
	v_mfma_f32_16x16x32_bf16 v[8:11], v[164:167], v[212:215], v[8:11]
	v_mfma_f32_16x16x32_bf16 v[52:55], v[168:171], v[184:187], v[52:55]
	v_mfma_f32_16x16x32_bf16 v[48:51], v[176:179], v[184:187], v[48:51]
	v_mfma_f32_16x16x32_bf16 v[36:39], v[168:171], v[192:195], v[36:39]
	v_mfma_f32_16x16x32_bf16 v[32:35], v[176:179], v[192:195], v[32:35]
	v_mfma_f32_16x16x32_bf16 v[20:23], v[168:171], v[200:203], v[20:23]
	v_mfma_f32_16x16x32_bf16 v[16:19], v[176:179], v[200:203], v[16:19]
	v_mfma_f32_16x16x32_bf16 v[4:7], v[168:171], v[208:211], v[4:7]
	v_mfma_f32_16x16x32_bf16 v[0:3], v[176:179], v[208:211], v[0:3]
	v_mfma_f32_16x16x32_bf16 v[52:55], v[172:175], v[188:191], v[52:55]
	v_mfma_f32_16x16x32_bf16 v[48:51], v[180:183], v[188:191], v[48:51]
	v_mfma_f32_16x16x32_bf16 v[36:39], v[172:175], v[196:199], v[36:39]
	v_mfma_f32_16x16x32_bf16 v[32:35], v[180:183], v[196:199], v[32:35]
	v_mfma_f32_16x16x32_bf16 v[20:23], v[172:175], v[204:207], v[20:23]
	v_mfma_f32_16x16x32_bf16 v[16:19], v[180:183], v[204:207], v[16:19]
	v_mfma_f32_16x16x32_bf16 v[4:7], v[172:175], v[212:215], v[4:7]
	v_mfma_f32_16x16x32_bf16 v[0:3], v[180:183], v[212:215], v[0:3]
	s_setprio 0
	s_barrier
	s_add_i32 s71, 0, 0x18000
	s_add_i32 s72, 0, 0x1c000
	v_add_u32_e32 v164, s71, v152
	v_add_u32_e32 v180, s72, v152
	ds_read_b128 v[146:149], v164
	ds_read_b128 v[156:159], v164 offset:1024
	ds_read_b128 v[160:163], v164 offset:2048
	ds_read_b128 v[164:167], v164 offset:3072
	ds_read_b128 v[168:171], v180
	ds_read_b128 v[172:175], v180 offset:1024
	ds_read_b128 v[176:179], v180 offset:2048
	ds_read_b128 v[180:183], v180 offset:3072
	s_add_u32 s46, s46, 0x40000
	s_addc_u32 s47, s47, 0
	s_mov_b32 m0, s53
	v_lshl_add_u64 v[224:225], s[46:47], 0, v[128:129]
	ds_read_b128 v[184:187], v155 offset:32768
	ds_read_b128 v[188:191], v155 offset:33792
	ds_read_b128 v[192:195], v155 offset:34816
	ds_read_b128 v[196:199], v155 offset:35840
	ds_read_b128 v[200:203], v155 offset:36864
	ds_read_b128 v[204:207], v155 offset:37888
	ds_read_b128 v[208:211], v155 offset:38912
	ds_read_b128 v[212:215], v155 offset:39936
	global_load_lds_dwordx4 v[224:225], off
	v_lshl_add_u64 v[224:225], s[46:47], 0, v[132:133]
	s_mov_b32 m0, s54
	s_nop 0
	global_load_lds_dwordx4 v[224:225], off
	s_waitcnt vmcnt(8)
	s_waitcnt lgkmcnt(0)
	s_barrier
	s_setprio 1
	s_waitcnt lgkmcnt(0)
	v_mfma_f32_16x16x32_bf16 v[124:127], v[146:149], v[184:187], v[124:127]
	v_mfma_f32_16x16x32_bf16 v[120:123], v[160:163], v[184:187], v[120:123]
	v_mfma_f32_16x16x32_bf16 v[108:111], v[146:149], v[192:195], v[108:111]
	v_mfma_f32_16x16x32_bf16 v[104:107], v[160:163], v[192:195], v[104:107]
	v_mfma_f32_16x16x32_bf16 v[92:95], v[146:149], v[200:203], v[92:95]
	v_mfma_f32_16x16x32_bf16 v[88:91], v[160:163], v[200:203], v[88:91]
	v_mfma_f32_16x16x32_bf16 v[76:79], v[146:149], v[208:211], v[76:79]
	v_mfma_f32_16x16x32_bf16 v[72:75], v[160:163], v[208:211], v[72:75]
	v_mfma_f32_16x16x32_bf16 v[124:127], v[156:159], v[188:191], v[124:127]
	v_mfma_f32_16x16x32_bf16 v[120:123], v[164:167], v[188:191], v[120:123]
	v_mfma_f32_16x16x32_bf16 v[108:111], v[156:159], v[196:199], v[108:111]
	v_mfma_f32_16x16x32_bf16 v[104:107], v[164:167], v[196:199], v[104:107]
	v_mfma_f32_16x16x32_bf16 v[92:95], v[156:159], v[204:207], v[92:95]
	v_mfma_f32_16x16x32_bf16 v[88:91], v[164:167], v[204:207], v[88:91]
	v_mfma_f32_16x16x32_bf16 v[76:79], v[156:159], v[212:215], v[76:79]
	v_mfma_f32_16x16x32_bf16 v[72:75], v[164:167], v[212:215], v[72:75]
	v_mfma_f32_16x16x32_bf16 v[116:119], v[168:171], v[184:187], v[116:119]
	v_mfma_f32_16x16x32_bf16 v[112:115], v[176:179], v[184:187], v[112:115]
	v_mfma_f32_16x16x32_bf16 v[100:103], v[168:171], v[192:195], v[100:103]
	v_mfma_f32_16x16x32_bf16 v[96:99], v[176:179], v[192:195], v[96:99]
	v_mfma_f32_16x16x32_bf16 v[84:87], v[168:171], v[200:203], v[84:87]
	v_mfma_f32_16x16x32_bf16 v[80:83], v[176:179], v[200:203], v[80:83]
	v_mfma_f32_16x16x32_bf16 v[68:71], v[168:171], v[208:211], v[68:71]
	v_mfma_f32_16x16x32_bf16 v[64:67], v[176:179], v[208:211], v[64:67]
	v_mfma_f32_16x16x32_bf16 v[116:119], v[172:175], v[188:191], v[116:119]
	v_mfma_f32_16x16x32_bf16 v[112:115], v[180:183], v[188:191], v[112:115]
	v_mfma_f32_16x16x32_bf16 v[100:103], v[172:175], v[196:199], v[100:103]
	v_mfma_f32_16x16x32_bf16 v[96:99], v[180:183], v[196:199], v[96:99]
	v_mfma_f32_16x16x32_bf16 v[84:87], v[172:175], v[204:207], v[84:87]
	v_mfma_f32_16x16x32_bf16 v[80:83], v[180:183], v[204:207], v[80:83]
	v_mfma_f32_16x16x32_bf16 v[68:71], v[172:175], v[212:215], v[68:71]
	v_mfma_f32_16x16x32_bf16 v[64:67], v[180:183], v[212:215], v[64:67]
	s_setprio 0
	s_barrier
; #define PG8_STAGE(bufoff, gbase, voff) do { _Pragma("unroll") for (int _i = 0; _i < 2; ++_i) \
;         __builtin_amdgcn_global_load_lds((const unsigned*)((const char*)(gbase) + (voff)[_i]), (PG8_LAS unsigned*)(lds + (bufoff) + ldsw + _i * 8192), 16, 0, 0); } while (0)
; #define PG8_LDA(dst, b, h) do { _Pragma("unroll") for (int m = 0; m < 4; ++m) _Pragma("unroll") for (int k = 0; k < 2; ++k) dst[m][k] = *(const PG8_LAS bf16x8*)(lds + PG8_SA(b, h) + aoff + m * 2048 + k * 1024); } while (0)
; #define PG8_MMA(ai, bj, At, Bt) do { __builtin_amdgcn_s_setprio(1); _Pragma("unroll") for (int m = 0; m < 4; ++m) _Pragma("unroll") for (int n = 0; n < 2; ++n) _Pragma("unroll") for (int k = 0; k < 2; ++k) \
;         acc[ai][bj][m][n] = __builtin_amdgcn_mfma_f32_16x16x32_bf16(Bt[n][k], At[m][k], acc[ai][bj][m][n], 0, 0, 0); __builtin_amdgcn_s_setprio(0); } while (0)
; #define PG8_WAIT_V(n) asm volatile("s_waitcnt vmcnt(" #n ")" ::: "memory")
; #define PG8_WAIT_L(n) asm volatile("s_waitcnt lgkmcnt(" #n ")" ::: "memory")
; #define PG8_BAR __builtin_amdgcn_s_barrier()
; #define PG8_SCHED __builtin_amdgcn_sched_barrier(0)
; template <class Epi, class Sched, bool ALIGN_EPI = false, bool SP2 = false>
; __device__ __forceinline__ void gemm_phase(PG8_LAS unsigned char* lds, const Gemm g, const Sched& S, const Epi& E) {
;     ...
;             PG8_LDA(At, 1, 1); PG8_STAGE(PG8_SB(1, 0), b3, voffB); PG8_STAGE(PG8_SB(1, 1), b3 + hstep, voffB); PG8_STAGE(PG8_SA(1, 0), a3, voffA);
;             PG8_WAIT_V(8); PG8_WAIT_L(0); PG8_BAR; PG8_MMA(1, 0, At, B0); PG8_MMA(1, 1, At, B1); PG8_BAR; PG8_SCHED;
;     ...
;         if constexpr (ALIGN_EPI) { if (wr == 0) PG8_BAR; }
	s_add_i32 s46, s71, s50
	v_lshl_add_u64 v[216:217], v[216:217], 0, s[12:13]
	s_mov_b32 m0, s46
	ds_read_b128 v[184:187], v155 offset:49152
	ds_read_b128 v[188:191], v155 offset:50176
	ds_read_b128 v[192:195], v155 offset:51200
	ds_read_b128 v[196:199], v155 offset:52224
	ds_read_b128 v[200:203], v155 offset:53248
	ds_read_b128 v[204:207], v155 offset:54272
	ds_read_b128 v[208:211], v155 offset:55296
	ds_read_b128 v[212:215], v155 offset:56320
	global_load_lds_dwordx4 v[216:217], off
	s_add_i32 m0, s46, 0x2000
	s_add_u32 s44, s44, 0x40080
	v_lshl_add_u64 v[216:217], v[218:219], 0, s[12:13]
	s_addc_u32 s45, s45, 0
	s_add_i32 s46, s72, s50
	global_load_lds_dwordx4 v[216:217], off
	v_lshl_add_u64 v[216:217], s[44:45], 0, v[130:131]
	s_mov_b32 m0, s46
	s_nop 0
	global_load_lds_dwordx4 v[216:217], off
	v_lshl_add_u64 v[216:217], s[44:45], 0, v[134:135]
	s_add_i32 m0, s46, 0x2000
	s_nop 0
	global_load_lds_dwordx4 v[216:217], off
	v_lshl_add_u64 v[216:217], v[220:221], 0, s[12:13]
	s_mov_b32 m0, s59
	s_nop 0
	global_load_lds_dwordx4 v[216:217], off
	v_lshl_add_u64 v[216:217], v[222:223], 0, s[12:13]
	s_mov_b32 m0, s60
	s_nop 0
	global_load_lds_dwordx4 v[216:217], off
	s_waitcnt vmcnt(8)
	s_waitcnt lgkmcnt(0)
	s_barrier
	s_setprio 1
	s_waitcnt lgkmcnt(0)
	v_mfma_f32_16x16x32_bf16 v[60:63], v[146:149], v[184:187], v[60:63]
	v_mfma_f32_16x16x32_bf16 v[56:59], v[160:163], v[184:187], v[56:59]
	v_mfma_f32_16x16x32_bf16 v[44:47], v[146:149], v[192:195], v[44:47]
	v_mfma_f32_16x16x32_bf16 v[40:43], v[160:163], v[192:195], v[40:43]
	v_mfma_f32_16x16x32_bf16 v[28:31], v[146:149], v[200:203], v[28:31]
	v_mfma_f32_16x16x32_bf16 v[24:27], v[160:163], v[200:203], v[24:27]
	v_mfma_f32_16x16x32_bf16 v[12:15], v[146:149], v[208:211], v[12:15]
	v_mfma_f32_16x16x32_bf16 v[8:11], v[160:163], v[208:211], v[8:11]
	v_mfma_f32_16x16x32_bf16 v[60:63], v[156:159], v[188:191], v[60:63]
	v_mfma_f32_16x16x32_bf16 v[56:59], v[164:167], v[188:191], v[56:59]
	v_mfma_f32_16x16x32_bf16 v[44:47], v[156:159], v[196:199], v[44:47]
	v_mfma_f32_16x16x32_bf16 v[40:43], v[164:167], v[196:199], v[40:43]
	v_mfma_f32_16x16x32_bf16 v[28:31], v[156:159], v[204:207], v[28:31]
	v_mfma_f32_16x16x32_bf16 v[24:27], v[164:167], v[204:207], v[24:27]
	v_mfma_f32_16x16x32_bf16 v[12:15], v[156:159], v[212:215], v[12:15]
	v_mfma_f32_16x16x32_bf16 v[8:11], v[164:167], v[212:215], v[8:11]
	v_mfma_f32_16x16x32_bf16 v[52:55], v[168:171], v[184:187], v[52:55]
	v_mfma_f32_16x16x32_bf16 v[48:51], v[176:179], v[184:187], v[48:51]
	v_mfma_f32_16x16x32_bf16 v[36:39], v[168:171], v[192:195], v[36:39]
	v_mfma_f32_16x16x32_bf16 v[32:35], v[176:179], v[192:195], v[32:35]
	v_mfma_f32_16x16x32_bf16 v[20:23], v[168:171], v[200:203], v[20:23]
	v_mfma_f32_16x16x32_bf16 v[16:19], v[176:179], v[200:203], v[16:19]
	v_mfma_f32_16x16x32_bf16 v[4:7], v[168:171], v[208:211], v[4:7]
	v_mfma_f32_16x16x32_bf16 v[0:3], v[176:179], v[208:211], v[0:3]
	v_mfma_f32_16x16x32_bf16 v[52:55], v[172:175], v[188:191], v[52:55]
	v_mfma_f32_16x16x32_bf16 v[48:51], v[180:183], v[188:191], v[48:51]
	v_mfma_f32_16x16x32_bf16 v[36:39], v[172:175], v[196:199], v[36:39]
	v_mfma_f32_16x16x32_bf16 v[32:35], v[180:183], v[196:199], v[32:35]
	v_mfma_f32_16x16x32_bf16 v[20:23], v[172:175], v[204:207], v[20:23]
	v_mfma_f32_16x16x32_bf16 v[16:19], v[180:183], v[204:207], v[16:19]
	v_mfma_f32_16x16x32_bf16 v[4:7], v[172:175], v[212:215], v[4:7]
	v_mfma_f32_16x16x32_bf16 v[0:3], v[180:183], v[212:215], v[0:3]
	s_setprio 0
	s_barrier
	s_add_i32 s70, s70, 2
	s_add_u32 s42, s42, 0x100
	s_addc_u32 s43, s43, 0
	s_add_u32 s68, s68, 0x100
	s_addc_u32 s69, s69, 0
	s_cmp_gt_u32 s70, 13
	s_cbranch_scc0 .LBB0_1535
	s_and_b64 vcc, exec, s[14:15]
	s_cbranch_vccz .LBB0_1538
	s_barrier

; #define PG8_STAGE(bufoff, gbase, voff) do { _Pragma("unroll") for (int _i = 0; _i < 2; ++_i) \
;         __builtin_amdgcn_global_load_lds((const unsigned*)((const char*)(gbase) + (voff)[_i]), (PG8_LAS unsigned*)(lds + (bufoff) + ldsw + _i * 8192), 16, 0, 0); } while (0)
; #define PG8_LDA(dst, b, h) do { _Pragma("unroll") for (int m = 0; m < 4; ++m) _Pragma("unroll") for (int k = 0; k < 2; ++k) dst[m][k] = *(const PG8_LAS bf16x8*)(lds + PG8_SA(b, h) + aoff + m * 2048 + k * 1024); } while (0)
; #define PG8_LDB(dst, b, h) do { _Pragma("unroll") for (int n = 0; n < 2; ++n) _Pragma("unroll") for (int k = 0; k < 2; ++k) dst[n][k] = *(const PG8_LAS bf16x8*)(lds + PG8_SB(b, h) + boff + n * 2048 + k * 1024); } while (0)
; #define PG8_MMA(ai, bj, At, Bt) do { __builtin_amdgcn_s_setprio(1); _Pragma("unroll") for (int m = 0; m < 4; ++m) _Pragma("unroll") for (int n = 0; n < 2; ++n) _Pragma("unroll") for (int k = 0; k < 2; ++k) \
;         acc[ai][bj][m][n] = __builtin_amdgcn_mfma_f32_16x16x32_bf16(Bt[n][k], At[m][k], acc[ai][bj][m][n], 0, 0, 0); __builtin_amdgcn_s_setprio(0); } while (0)
; #define PG8_WAIT_V(n) asm volatile("s_waitcnt vmcnt(" #n ")" ::: "memory")
; #define PG8_WAIT_L(n) asm volatile("s_waitcnt lgkmcnt(" #n ")" ::: "memory")
; template <class Epi, class Sched, bool ALIGN_EPI = false, bool SP2 = false>
; __device__ __forceinline__ void gemm_phase(PG8_LAS unsigned char* lds, const Gemm g, const Sched& S, const Epi& E) {
;     ...
;             const bool last = (t == nt - 2);
;             const char* a1 = cA + (size_t)(t + 1) * kstep;
;             const char* a2 = last ? nA : cA + (size_t)(t + 2) * kstep; const char* b2 = last ? nB : cB + (size_t)(t + 2) * kstep;
;             const char* a3 = a2 + kstep; const char* b3 = b2 + kstep;
;             if (last && has_next) S.a_ready(nxt);
;             if constexpr (SP2) {
;             PG8_LDB(B0, 0, 0); PG8_LDB(B1, 0, 1); PG8_SCHED; PG8_LDA(At, 0, 0); PG8_STAGE(PG8_SA(1, 1), a1 + hstep, voffA);
;             PG8_WAIT_V(8); PG8_WAIT_L(0); PG8_BAR; PG8_MMA(0, 0, At, B0); PG8_MMA(0, 1, At, B1); PG8_BAR; PG8_SCHED;
;             PG8_LDA(At, 0, 1); PG8_STAGE(PG8_SB(0, 0), b2, voffB); PG8_STAGE(PG8_SB(0, 1), b2 + hstep, voffB); PG8_STAGE(PG8_SA(0, 0), a2, voffA);
;             PG8_WAIT_V(8); PG8_WAIT_L(0); PG8_BAR; PG8_MMA(1, 0, At, B0); PG8_MMA(1, 1, At, B1); PG8_BAR; PG8_SCHED;
.LBB0_1612:
	ds_read_b128 v[146:149], v153
	ds_read_b128 v[158:161], v153 offset:1024
	ds_read_b128 v[162:165], v153 offset:2048
	ds_read_b128 v[166:169], v153 offset:3072
	ds_read_b128 v[170:173], v154
	ds_read_b128 v[174:177], v154 offset:1024
	ds_read_b128 v[178:181], v154 offset:2048
	ds_read_b128 v[182:185], v154 offset:3072
	s_add_u32 s44, s42, 0xfff80080
	s_addc_u32 s45, s43, -1
	s_cmp_eq_u32 s69, 28
	s_cselect_b32 s47, s23, s45
	s_cselect_b32 s46, s41, s44
	s_cselect_b32 s45, s19, s68
	s_cselect_b32 s44, s66, s67
	v_lshl_add_u64 v[218:219], s[42:43], 0, v[136:137]
	s_add_i32 m0, s51, 0xc000
	ds_read_b128 v[186:189], v155
	ds_read_b128 v[190:193], v155 offset:1024
	ds_read_b128 v[194:197], v155 offset:2048
	ds_read_b128 v[198:201], v155 offset:3072
	ds_read_b128 v[202:205], v155 offset:4096
	ds_read_b128 v[206:209], v155 offset:5120
	ds_read_b128 v[210:213], v155 offset:6144
	ds_read_b128 v[214:217], v155 offset:7168
	global_load_lds_dwordx4 v[218:219], off
	v_lshl_add_u64 v[218:219], s[42:43], 0, v[138:139]
	s_add_i32 m0, s51, 0xe000
	s_nop 0
	global_load_lds_dwordx4 v[218:219], off
	s_waitcnt vmcnt(8)
	s_waitcnt lgkmcnt(0)
	s_barrier
	s_setprio 1
	s_waitcnt lgkmcnt(0)
	v_mfma_f32_16x16x32_bf16 v[124:127], v[146:149], v[186:189], v[124:127]
	v_mfma_f32_16x16x32_bf16 v[120:123], v[162:165], v[186:189], v[120:123]
	v_mfma_f32_16x16x32_bf16 v[108:111], v[146:149], v[194:197], v[108:111]
	v_mfma_f32_16x16x32_bf16 v[104:107], v[162:165], v[194:197], v[104:107]
	v_mfma_f32_16x16x32_bf16 v[92:95], v[146:149], v[202:205], v[92:95]
	v_mfma_f32_16x16x32_bf16 v[88:91], v[162:165], v[202:205], v[88:91]
	v_mfma_f32_16x16x32_bf16 v[76:79], v[146:149], v[210:213], v[76:79]
	v_mfma_f32_16x16x32_bf16 v[72:75], v[162:165], v[210:213], v[72:75]
	v_mfma_f32_16x16x32_bf16 v[124:127], v[158:161], v[190:193], v[124:127]
	v_mfma_f32_16x16x32_bf16 v[120:123], v[166:169], v[190:193], v[120:123]
	v_mfma_f32_16x16x32_bf16 v[108:111], v[158:161], v[198:201], v[108:111]
	v_mfma_f32_16x16x32_bf16 v[104:107], v[166:169], v[198:201], v[104:107]
	v_mfma_f32_16x16x32_bf16 v[92:95], v[158:161], v[206:209], v[92:95]
	v_mfma_f32_16x16x32_bf16 v[88:91], v[166:169], v[206:209], v[88:91]
	v_mfma_f32_16x16x32_bf16 v[76:79], v[158:161], v[214:217], v[76:79]
	v_mfma_f32_16x16x32_bf16 v[72:75], v[166:169], v[214:217], v[72:75]
	v_mfma_f32_16x16x32_bf16 v[116:119], v[170:173], v[186:189], v[116:119]
	v_mfma_f32_16x16x32_bf16 v[112:115], v[178:181], v[186:189], v[112:115]
	v_mfma_f32_16x16x32_bf16 v[100:103], v[170:173], v[194:197], v[100:103]
	v_mfma_f32_16x16x32_bf16 v[96:99], v[178:181], v[194:197], v[96:99]
	v_mfma_f32_16x16x32_bf16 v[84:87], v[170:173], v[202:205], v[84:87]
	v_mfma_f32_16x16x32_bf16 v[80:83], v[178:181], v[202:205], v[80:83]
	v_mfma_f32_16x16x32_bf16 v[68:71], v[170:173], v[210:213], v[68:71]
	v_mfma_f32_16x16x32_bf16 v[64:67], v[178:181], v[210:213], v[64:67]
	v_mfma_f32_16x16x32_bf16 v[116:119], v[174:177], v[190:193], v[116:119]
	v_mfma_f32_16x16x32_bf16 v[112:115], v[182:185], v[190:193], v[112:115]
	v_mfma_f32_16x16x32_bf16 v[100:103], v[174:177], v[198:201], v[100:103]
	v_mfma_f32_16x16x32_bf16 v[96:99], v[182:185], v[198:201], v[96:99]
	v_mfma_f32_16x16x32_bf16 v[84:87], v[174:177], v[206:209], v[84:87]
	v_mfma_f32_16x16x32_bf16 v[80:83], v[182:185], v[206:209], v[80:83]
	v_mfma_f32_16x16x32_bf16 v[68:71], v[174:177], v[214:217], v[68:71]
	v_mfma_f32_16x16x32_bf16 v[64:67], v[182:185], v[214:217], v[64:67]
	s_setprio 0
	s_barrier
	s_add_i32 s70, s63, s50
	v_lshl_add_u64 v[218:219], s[44:45], 0, v[130:131]
	s_mov_b32 m0, s70
	ds_read_b128 v[186:189], v155 offset:16384
	ds_read_b128 v[190:193], v155 offset:17408
	ds_read_b128 v[194:197], v155 offset:18432
	ds_read_b128 v[198:201], v155 offset:19456
	ds_read_b128 v[202:205], v155 offset:20480
	ds_read_b128 v[206:209], v155 offset:21504
	ds_read_b128 v[210:213], v155 offset:22528
	ds_read_b128 v[214:217], v155 offset:23552
	global_load_lds_dwordx4 v[218:219], off
	s_add_i32 m0, s70, 0x2000
	s_add_u32 s70, s44, 0x80000
	v_lshl_add_u64 v[220:221], s[44:45], 0, v[134:135]
	s_addc_u32 s71, s45, 0
	s_add_i32 s72, s64, s50
	global_load_lds_dwordx4 v[220:221], off
	v_lshl_add_u64 v[222:223], s[70:71], 0, v[130:131]
	s_mov_b32 m0, s72
	v_lshl_add_u64 v[224:225], s[46:47], 0, v[132:133]
	global_load_lds_dwordx4 v[222:223], off
	v_lshl_add_u64 v[222:223], s[70:71], 0, v[134:135]
	s_add_i32 m0, s72, 0x2000
	s_nop 0
	global_load_lds_dwordx4 v[222:223], off
	v_lshl_add_u64 v[222:223], s[46:47], 0, v[128:129]
	s_mov_b32 m0, s51
	s_nop 0
	global_load_lds_dwordx4 v[222:223], off
	s_mov_b32 m0, s52
	s_nop 0
	global_load_lds_dwordx4 v[224:225], off
	s_waitcnt vmcnt(8)
	s_waitcnt lgkmcnt(0)
	s_barrier
; #define PG8_STAGE(bufoff, gbase, voff) do { _Pragma("unroll") for (int _i = 0; _i < 2; ++_i) \
;         __builtin_amdgcn_global_load_lds((const unsigned*)((const char*)(gbase) + (voff)[_i]), (PG8_LAS unsigned*)(lds + (bufoff) + ldsw + _i * 8192), 16, 0, 0); } while (0)
; #define PG8_LDA(dst, b, h) do { _Pragma("unroll") for (int m = 0; m < 4; ++m) _Pragma("unroll") for (int k = 0; k < 2; ++k) dst[m][k] = *(const PG8_LAS bf16x8*)(lds + PG8_SA(b, h) + aoff + m * 2048 + k * 1024); } while (0)
; #define PG8_LDB(dst, b, h) do { _Pragma("unroll") for (int n = 0; n < 2; ++n) _Pragma("unroll") for (int k = 0; k < 2; ++k) dst[n][k] = *(const PG8_LAS bf16x8*)(lds + PG8_SB(b, h) + boff + n * 2048 + k * 1024); } while (0)
; #define PG8_MMA(ai, bj, At, Bt) do { __builtin_amdgcn_s_setprio(1); _Pragma("unroll") for (int m = 0; m < 4; ++m) _Pragma("unroll") for (int n = 0; n < 2; ++n) _Pragma("unroll") for (int k = 0; k < 2; ++k) \
;         acc[ai][bj][m][n] = __builtin_amdgcn_mfma_f32_16x16x32_bf16(Bt[n][k], At[m][k], acc[ai][bj][m][n], 0, 0, 0); __builtin_amdgcn_s_setprio(0); } while (0)
; #define PG8_WAIT_V(n) asm volatile("s_waitcnt vmcnt(" #n ")" ::: "memory")
; #define PG8_WAIT_L(n) asm volatile("s_waitcnt lgkmcnt(" #n ")" ::: "memory")
; #define PG8_BAR __builtin_amdgcn_s_barrier()
; #define PG8_SCHED __builtin_amdgcn_sched_barrier(0)
; template <class Epi, class Sched, bool ALIGN_EPI = false, bool SP2 = false>
; __device__ __forceinline__ void gemm_phase(PG8_LAS unsigned char* lds, const Gemm g, const Sched& S, const Epi& E) {
;     ...
;             PG8_WAIT_V(8); PG8_WAIT_L(0); PG8_BAR; PG8_MMA(1, 0, At, B0); PG8_MMA(1, 1, At, B1); PG8_BAR; PG8_SCHED;
;             PG8_LDB(B0, 1, 0); PG8_LDB(B1, 1, 1); PG8_SCHED; PG8_LDA(At, 1, 0); PG8_STAGE(PG8_SA(0, 1), a2 + hstep, voffA);
;             PG8_WAIT_V(8); PG8_WAIT_L(0); PG8_BAR; PG8_MMA(0, 0, At, B0); PG8_MMA(0, 1, At, B1); PG8_BAR; PG8_SCHED;
	s_setprio 1
	s_waitcnt lgkmcnt(0)
	v_mfma_f32_16x16x32_bf16 v[60:63], v[146:149], v[186:189], v[60:63]
	v_mfma_f32_16x16x32_bf16 v[56:59], v[162:165], v[186:189], v[56:59]
	v_mfma_f32_16x16x32_bf16 v[44:47], v[146:149], v[194:197], v[44:47]
	v_mfma_f32_16x16x32_bf16 v[40:43], v[162:165], v[194:197], v[40:43]
	v_mfma_f32_16x16x32_bf16 v[28:31], v[146:149], v[202:205], v[28:31]
	v_mfma_f32_16x16x32_bf16 v[24:27], v[162:165], v[202:205], v[24:27]
	v_mfma_f32_16x16x32_bf16 v[12:15], v[146:149], v[210:213], v[12:15]
	v_mfma_f32_16x16x32_bf16 v[8:11], v[162:165], v[210:213], v[8:11]
	v_mfma_f32_16x16x32_bf16 v[60:63], v[158:161], v[190:193], v[60:63]
	v_mfma_f32_16x16x32_bf16 v[56:59], v[166:169], v[190:193], v[56:59]
	v_mfma_f32_16x16x32_bf16 v[44:47], v[158:161], v[198:201], v[44:47]
	v_mfma_f32_16x16x32_bf16 v[40:43], v[166:169], v[198:201], v[40:43]
	v_mfma_f32_16x16x32_bf16 v[28:31], v[158:161], v[206:209], v[28:31]
	v_mfma_f32_16x16x32_bf16 v[24:27], v[166:169], v[206:209], v[24:27]
	v_mfma_f32_16x16x32_bf16 v[12:15], v[158:161], v[214:217], v[12:15]
	v_mfma_f32_16x16x32_bf16 v[8:11], v[166:169], v[214:217], v[8:11]
	v_mfma_f32_16x16x32_bf16 v[52:55], v[170:173], v[186:189], v[52:55]
	v_mfma_f32_16x16x32_bf16 v[48:51], v[178:181], v[186:189], v[48:51]
	v_mfma_f32_16x16x32_bf16 v[36:39], v[170:173], v[194:197], v[36:39]
	v_mfma_f32_16x16x32_bf16 v[32:35], v[178:181], v[194:197], v[32:35]
	v_mfma_f32_16x16x32_bf16 v[20:23], v[170:173], v[202:205], v[20:23]
	v_mfma_f32_16x16x32_bf16 v[16:19], v[178:181], v[202:205], v[16:19]
	v_mfma_f32_16x16x32_bf16 v[4:7], v[170:173], v[210:213], v[4:7]
	v_mfma_f32_16x16x32_bf16 v[0:3], v[178:181], v[210:213], v[0:3]
	v_mfma_f32_16x16x32_bf16 v[52:55], v[174:177], v[190:193], v[52:55]
	v_mfma_f32_16x16x32_bf16 v[48:51], v[182:185], v[190:193], v[48:51]
	v_mfma_f32_16x16x32_bf16 v[36:39], v[174:177], v[198:201], v[36:39]
	v_mfma_f32_16x16x32_bf16 v[32:35], v[182:185], v[198:201], v[32:35]
	v_mfma_f32_16x16x32_bf16 v[20:23], v[174:177], v[206:209], v[20:23]
	v_mfma_f32_16x16x32_bf16 v[16:19], v[182:185], v[206:209], v[16:19]
	v_mfma_f32_16x16x32_bf16 v[4:7], v[174:177], v[214:217], v[4:7]
	v_mfma_f32_16x16x32_bf16 v[0:3], v[182:185], v[214:217], v[0:3]
	s_setprio 0
	s_barrier
	s_add_i32 s70, 0, 0x18000
	v_add_u32_e32 v157, s70, v152
	s_add_i32 s71, 0, 0x1c000
	ds_read_b128 v[146:149], v157
	ds_read_b128 v[158:161], v157 offset:1024
	ds_read_b128 v[162:165], v157 offset:2048
	ds_read_b128 v[166:169], v157 offset:3072
	v_add_u32_e32 v157, s71, v152
	ds_read_b128 v[170:173], v157
	ds_read_b128 v[174:177], v157 offset:1024
	ds_read_b128 v[178:181], v157 offset:2048
	ds_read_b128 v[182:185], v157 offset:3072
	s_add_u32 s46, s46, 0x80000
	s_addc_u32 s47, s47, 0
	s_mov_b32 m0, s53
	v_lshl_add_u64 v[226:227], s[46:47], 0, v[128:129]
	ds_read_b128 v[186:189], v155 offset:32768
	ds_read_b128 v[190:193], v155 offset:33792
	ds_read_b128 v[194:197], v155 offset:34816
	ds_read_b128 v[198:201], v155 offset:35840
	ds_read_b128 v[202:205], v155 offset:36864
	ds_read_b128 v[206:209], v155 offset:37888
	ds_read_b128 v[210:213], v155 offset:38912
	ds_read_b128 v[214:217], v155 offset:39936
	global_load_lds_dwordx4 v[226:227], off
	v_lshl_add_u64 v[226:227], s[46:47], 0, v[132:133]
	s_mov_b32 m0, s54
	s_nop 0
	global_load_lds_dwordx4 v[226:227], off
	s_waitcnt vmcnt(8)
	s_waitcnt lgkmcnt(0)
	s_barrier
	s_setprio 1
	s_waitcnt lgkmcnt(0)
	v_mfma_f32_16x16x32_bf16 v[124:127], v[146:149], v[186:189], v[124:127]
	v_mfma_f32_16x16x32_bf16 v[120:123], v[162:165], v[186:189], v[120:123]
	v_mfma_f32_16x16x32_bf16 v[108:111], v[146:149], v[194:197], v[108:111]
	v_mfma_f32_16x16x32_bf16 v[104:107], v[162:165], v[194:197], v[104:107]
	v_mfma_f32_16x16x32_bf16 v[92:95], v[146:149], v[202:205], v[92:95]
	v_mfma_f32_16x16x32_bf16 v[88:91], v[162:165], v[202:205], v[88:91]
	v_mfma_f32_16x16x32_bf16 v[76:79], v[146:149], v[210:213], v[76:79]
	v_mfma_f32_16x16x32_bf16 v[72:75], v[162:165], v[210:213], v[72:75]
	v_mfma_f32_16x16x32_bf16 v[124:127], v[158:161], v[190:193], v[124:127]
	v_mfma_f32_16x16x32_bf16 v[120:123], v[166:169], v[190:193], v[120:123]
	v_mfma_f32_16x16x32_bf16 v[108:111], v[158:161], v[198:201], v[108:111]
	v_mfma_f32_16x16x32_bf16 v[104:107], v[166:169], v[198:201], v[104:107]
	v_mfma_f32_16x16x32_bf16 v[92:95], v[158:161], v[206:209], v[92:95]
	v_mfma_f32_16x16x32_bf16 v[88:91], v[166:169], v[206:209], v[88:91]
	v_mfma_f32_16x16x32_bf16 v[76:79], v[158:161], v[214:217], v[76:79]
	v_mfma_f32_16x16x32_bf16 v[72:75], v[166:169], v[214:217], v[72:75]
	v_mfma_f32_16x16x32_bf16 v[116:119], v[170:173], v[186:189], v[116:119]
	v_mfma_f32_16x16x32_bf16 v[112:115], v[178:181], v[186:189], v[112:115]
	v_mfma_f32_16x16x32_bf16 v[100:103], v[170:173], v[194:197], v[100:103]
	v_mfma_f32_16x16x32_bf16 v[96:99], v[178:181], v[194:197], v[96:99]
	v_mfma_f32_16x16x32_bf16 v[84:87], v[170:173], v[202:205], v[84:87]
	v_mfma_f32_16x16x32_bf16 v[80:83], v[178:181], v[202:205], v[80:83]
	v_mfma_f32_16x16x32_bf16 v[68:71], v[170:173], v[210:213], v[68:71]
	v_mfma_f32_16x16x32_bf16 v[64:67], v[178:181], v[210:213], v[64:67]
	v_mfma_f32_16x16x32_bf16 v[116:119], v[174:177], v[190:193], v[116:119]
	v_mfma_f32_16x16x32_bf16 v[112:115], v[182:185], v[190:193], v[112:115]
	v_mfma_f32_16x16x32_bf16 v[100:103], v[174:177], v[198:201], v[100:103]
	v_mfma_f32_16x16x32_bf16 v[96:99], v[182:185], v[198:201], v[96:99]
	v_mfma_f32_16x16x32_bf16 v[84:87], v[174:177], v[206:209], v[84:87]
	v_mfma_f32_16x16x32_bf16 v[80:83], v[182:185], v[206:209], v[80:83]
	v_mfma_f32_16x16x32_bf16 v[68:71], v[174:177], v[214:217], v[68:71]
	v_mfma_f32_16x16x32_bf16 v[64:67], v[182:185], v[214:217], v[64:67]
	s_setprio 0
	s_barrier
; #define PG8_STAGE(bufoff, gbase, voff) do { _Pragma("unroll") for (int _i = 0; _i < 2; ++_i) \
;         __builtin_amdgcn_global_load_lds((const unsigned*)((const char*)(gbase) + (voff)[_i]), (PG8_LAS unsigned*)(lds + (bufoff) + ldsw + _i * 8192), 16, 0, 0); } while (0)
; #define PG8_LDA(dst, b, h) do { _Pragma("unroll") for (int m = 0; m < 4; ++m) _Pragma("unroll") for (int k = 0; k < 2; ++k) dst[m][k] = *(const PG8_LAS bf16x8*)(lds + PG8_SA(b, h) + aoff + m * 2048 + k * 1024); } while (0)
; #define PG8_MMA(ai, bj, At, Bt) do { __builtin_amdgcn_s_setprio(1); _Pragma("unroll") for (int m = 0; m < 4; ++m) _Pragma("unroll") for (int n = 0; n < 2; ++n) _Pragma("unroll") for (int k = 0; k < 2; ++k) \
;         acc[ai][bj][m][n] = __builtin_amdgcn_mfma_f32_16x16x32_bf16(Bt[n][k], At[m][k], acc[ai][bj][m][n], 0, 0, 0); __builtin_amdgcn_s_setprio(0); } while (0)
; #define PG8_WAIT_V(n) asm volatile("s_waitcnt vmcnt(" #n ")" ::: "memory")
; #define PG8_WAIT_L(n) asm volatile("s_waitcnt lgkmcnt(" #n ")" ::: "memory")
; #define PG8_BAR __builtin_amdgcn_s_barrier()
; #define PG8_SCHED __builtin_amdgcn_sched_barrier(0)
; template <class Epi, class Sched, bool ALIGN_EPI = false, bool SP2 = false>
; __device__ __forceinline__ void gemm_phase(PG8_LAS unsigned char* lds, const Gemm g, const Sched& S, const Epi& E) {
;     ...
;             PG8_LDA(At, 1, 1); PG8_STAGE(PG8_SB(1, 0), b3, voffB); PG8_STAGE(PG8_SB(1, 1), b3 + hstep, voffB); PG8_STAGE(PG8_SA(1, 0), a3, voffA);
;             PG8_WAIT_V(8); PG8_WAIT_L(0); PG8_BAR; PG8_MMA(1, 0, At, B0); PG8_MMA(1, 1, At, B1); PG8_BAR; PG8_SCHED;
;     ...
;         if constexpr (ALIGN_EPI) { if (wr == 0) PG8_BAR; }
	s_add_i32 s46, s70, s50
	v_lshl_add_u64 v[218:219], v[218:219], 0, s[14:15]
	s_mov_b32 m0, s46
	ds_read_b128 v[186:189], v155 offset:49152
	ds_read_b128 v[190:193], v155 offset:50176
	ds_read_b128 v[194:197], v155 offset:51200
	ds_read_b128 v[198:201], v155 offset:52224
	ds_read_b128 v[202:205], v155 offset:53248
	ds_read_b128 v[206:209], v155 offset:54272
	ds_read_b128 v[210:213], v155 offset:55296
	ds_read_b128 v[214:217], v155 offset:56320
	global_load_lds_dwordx4 v[218:219], off
	s_add_i32 m0, s46, 0x2000
	s_add_u32 s44, s44, 0x80080
	v_lshl_add_u64 v[218:219], v[220:221], 0, s[14:15]
	s_addc_u32 s45, s45, 0
	s_add_i32 s46, s71, s50
	global_load_lds_dwordx4 v[218:219], off
	v_lshl_add_u64 v[218:219], s[44:45], 0, v[130:131]
	s_mov_b32 m0, s46
	s_nop 0
	global_load_lds_dwordx4 v[218:219], off
	v_lshl_add_u64 v[218:219], s[44:45], 0, v[134:135]
	s_add_i32 m0, s46, 0x2000
	s_nop 0
	global_load_lds_dwordx4 v[218:219], off
	v_lshl_add_u64 v[218:219], v[222:223], 0, s[14:15]
	s_mov_b32 m0, s60
	s_nop 0
	global_load_lds_dwordx4 v[218:219], off
	v_lshl_add_u64 v[218:219], v[224:225], 0, s[14:15]
	s_mov_b32 m0, s61
	s_nop 0
	global_load_lds_dwordx4 v[218:219], off
	s_waitcnt vmcnt(8)
	s_waitcnt lgkmcnt(0)
	s_barrier
	s_setprio 1
	s_waitcnt lgkmcnt(0)
	v_mfma_f32_16x16x32_bf16 v[60:63], v[146:149], v[186:189], v[60:63]
	v_mfma_f32_16x16x32_bf16 v[56:59], v[162:165], v[186:189], v[56:59]
	v_mfma_f32_16x16x32_bf16 v[44:47], v[146:149], v[194:197], v[44:47]
	v_mfma_f32_16x16x32_bf16 v[40:43], v[162:165], v[194:197], v[40:43]
	v_mfma_f32_16x16x32_bf16 v[28:31], v[146:149], v[202:205], v[28:31]
	v_mfma_f32_16x16x32_bf16 v[24:27], v[162:165], v[202:205], v[24:27]
	v_mfma_f32_16x16x32_bf16 v[12:15], v[146:149], v[210:213], v[12:15]
	v_mfma_f32_16x16x32_bf16 v[8:11], v[162:165], v[210:213], v[8:11]
	v_mfma_f32_16x16x32_bf16 v[60:63], v[158:161], v[190:193], v[60:63]
	v_mfma_f32_16x16x32_bf16 v[56:59], v[166:169], v[190:193], v[56:59]
	v_mfma_f32_16x16x32_bf16 v[44:47], v[158:161], v[198:201], v[44:47]
	v_mfma_f32_16x16x32_bf16 v[40:43], v[166:169], v[198:201], v[40:43]
	v_mfma_f32_16x16x32_bf16 v[28:31], v[158:161], v[206:209], v[28:31]
	v_mfma_f32_16x16x32_bf16 v[24:27], v[166:169], v[206:209], v[24:27]
	v_mfma_f32_16x16x32_bf16 v[12:15], v[158:161], v[214:217], v[12:15]
	v_mfma_f32_16x16x32_bf16 v[8:11], v[166:169], v[214:217], v[8:11]
	v_mfma_f32_16x16x32_bf16 v[52:55], v[170:173], v[186:189], v[52:55]
	v_mfma_f32_16x16x32_bf16 v[48:51], v[178:181], v[186:189], v[48:51]
	v_mfma_f32_16x16x32_bf16 v[36:39], v[170:173], v[194:197], v[36:39]
	v_mfma_f32_16x16x32_bf16 v[32:35], v[178:181], v[194:197], v[32:35]
	v_mfma_f32_16x16x32_bf16 v[20:23], v[170:173], v[202:205], v[20:23]
	v_mfma_f32_16x16x32_bf16 v[16:19], v[178:181], v[202:205], v[16:19]
	v_mfma_f32_16x16x32_bf16 v[4:7], v[170:173], v[210:213], v[4:7]
	v_mfma_f32_16x16x32_bf16 v[0:3], v[178:181], v[210:213], v[0:3]
	v_mfma_f32_16x16x32_bf16 v[52:55], v[174:177], v[190:193], v[52:55]
	v_mfma_f32_16x16x32_bf16 v[48:51], v[182:185], v[190:193], v[48:51]
	v_mfma_f32_16x16x32_bf16 v[36:39], v[174:177], v[198:201], v[36:39]
	v_mfma_f32_16x16x32_bf16 v[32:35], v[182:185], v[198:201], v[32:35]
	v_mfma_f32_16x16x32_bf16 v[20:23], v[174:177], v[206:209], v[20:23]
	v_mfma_f32_16x16x32_bf16 v[16:19], v[182:185], v[206:209], v[16:19]
	v_mfma_f32_16x16x32_bf16 v[4:7], v[174:177], v[214:217], v[4:7]
	v_mfma_f32_16x16x32_bf16 v[0:3], v[182:185], v[214:217], v[0:3]
	s_setprio 0
	s_barrier
	s_add_i32 s69, s69, 2
	s_add_u32 s42, s42, 0x100
	s_addc_u32 s43, s43, 0
	s_add_u32 s67, s67, 0x100
	s_addc_u32 s68, s68, 0
	s_cmp_gt_u32 s69, 29
	s_cbranch_scc0 .LBB0_1612
	s_and_b64 vcc, exec, s[16:17]
	s_cbranch_vccz .LBB0_1615
	s_barrier

; #define PG8_STAGE(bufoff, gbase, voff) do { _Pragma("unroll") for (int _i = 0; _i < 2; ++_i) \
;         __builtin_amdgcn_global_load_lds((const unsigned*)((const char*)(gbase) + (voff)[_i]), (PG8_LAS unsigned*)(lds + (bufoff) + ldsw + _i * 8192), 16, 0, 0); } while (0)
; #define PG8_LDA(dst, b, h) do { _Pragma("unroll") for (int m = 0; m < 4; ++m) _Pragma("unroll") for (int k = 0; k < 2; ++k) dst[m][k] = *(const PG8_LAS bf16x8*)(lds + PG8_SA(b, h) + aoff + m * 2048 + k * 1024); } while (0)
; #define PG8_LDB(dst, b, h) do { _Pragma("unroll") for (int n = 0; n < 2; ++n) _Pragma("unroll") for (int k = 0; k < 2; ++k) dst[n][k] = *(const PG8_LAS bf16x8*)(lds + PG8_SB(b, h) + boff + n * 2048 + k * 1024); } while (0)
; #define PG8_MMA(ai, bj, At, Bt) do { __builtin_amdgcn_s_setprio(1); _Pragma("unroll") for (int m = 0; m < 4; ++m) _Pragma("unroll") for (int n = 0; n < 2; ++n) _Pragma("unroll") for (int k = 0; k < 2; ++k) \
;         acc[ai][bj][m][n] = __builtin_amdgcn_mfma_f32_16x16x32_bf16(Bt[n][k], At[m][k], acc[ai][bj][m][n], 0, 0, 0); __builtin_amdgcn_s_setprio(0); } while (0)
; #define PG8_WAIT_V(n) asm volatile("s_waitcnt vmcnt(" #n ")" ::: "memory")
; #define PG8_WAIT_L(n) asm volatile("s_waitcnt lgkmcnt(" #n ")" ::: "memory")
; template <class Epi, class Sched, bool ALIGN_EPI = false, bool SP2 = false>
; __device__ __forceinline__ void gemm_phase(PG8_LAS unsigned char* lds, const Gemm g, const Sched& S, const Epi& E) {
;     ...
;             const bool last = (t == nt - 2);
;             const char* a1 = cA + (size_t)(t + 1) * kstep;
;             const char* a2 = last ? nA : cA + (size_t)(t + 2) * kstep; const char* b2 = last ? nB : cB + (size_t)(t + 2) * kstep;
;             const char* a3 = a2 + kstep; const char* b3 = b2 + kstep;
;             if (last && has_next) S.a_ready(nxt);
;             if constexpr (SP2) {
;             PG8_LDB(B0, 0, 0); PG8_LDB(B1, 0, 1); PG8_SCHED; PG8_LDA(At, 0, 0); PG8_STAGE(PG8_SA(1, 1), a1 + hstep, voffA);
;             PG8_WAIT_V(8); PG8_WAIT_L(0); PG8_BAR; PG8_MMA(0, 0, At, B0); PG8_MMA(0, 1, At, B1); PG8_BAR; PG8_SCHED;
;             PG8_LDA(At, 0, 1); PG8_STAGE(PG8_SB(0, 0), b2, voffB); PG8_STAGE(PG8_SB(0, 1), b2 + hstep, voffB); PG8_STAGE(PG8_SA(0, 0), a2, voffA);
;             PG8_WAIT_V(8); PG8_WAIT_L(0); PG8_BAR; PG8_MMA(1, 0, At, B0); PG8_MMA(1, 1, At, B1); PG8_BAR; PG8_SCHED;
.LBB0_1701:
	ds_read_b128 v[128:131], v220
	ds_read_b128 v[132:135], v220 offset:1024
	ds_read_b128 v[136:139], v220 offset:2048
	ds_read_b128 v[140:143], v220 offset:3072
	ds_read_b128 v[164:167], v221
	ds_read_b128 v[168:171], v221 offset:1024
	ds_read_b128 v[172:175], v221 offset:2048
	ds_read_b128 v[176:179], v221 offset:3072
	s_add_u32 s8, s0, 0xfff80080
	s_addc_u32 s9, s1, -1
	s_cmp_eq_u32 s73, 28
	s_cselect_b32 s11, s7, s9
	s_cselect_b32 s10, s12, s8
	s_cselect_b32 s9, s13, s71
	s_cselect_b32 s8, s16, s37
	v_lshl_add_u64 v[212:213], s[0:1], 0, v[156:157]
	s_add_i32 m0, s61, 0xc000
	ds_read_b128 v[180:183], v222
	ds_read_b128 v[184:187], v222 offset:1024
	ds_read_b128 v[188:191], v222 offset:2048
	ds_read_b128 v[192:195], v222 offset:3072
	ds_read_b128 v[196:199], v222 offset:4096
	ds_read_b128 v[200:203], v222 offset:5120
	ds_read_b128 v[204:207], v222 offset:6144
	ds_read_b128 v[208:211], v222 offset:7168
	global_load_lds_dwordx4 v[212:213], off
	v_lshl_add_u64 v[212:213], s[0:1], 0, v[158:159]
	s_add_i32 m0, s61, 0xe000
	s_nop 0
	global_load_lds_dwordx4 v[212:213], off
	s_waitcnt vmcnt(8)
	s_waitcnt lgkmcnt(0)
	s_barrier
	s_setprio 1
	s_waitcnt lgkmcnt(0)
	v_mfma_f32_16x16x32_bf16 v[124:127], v[128:131], v[180:183], v[124:127]
	v_mfma_f32_16x16x32_bf16 v[116:119], v[136:139], v[180:183], v[116:119]
	v_mfma_f32_16x16x32_bf16 v[120:123], v[128:131], v[188:191], v[120:123]
	v_mfma_f32_16x16x32_bf16 v[112:115], v[136:139], v[188:191], v[112:115]
	v_mfma_f32_16x16x32_bf16 v[104:107], v[128:131], v[196:199], v[104:107]
	v_mfma_f32_16x16x32_bf16 v[108:111], v[136:139], v[196:199], v[108:111]
	v_mfma_f32_16x16x32_bf16 v[80:83], v[128:131], v[204:207], v[80:83]
	v_mfma_f32_16x16x32_bf16 v[92:95], v[136:139], v[204:207], v[92:95]
	v_mfma_f32_16x16x32_bf16 v[124:127], v[132:135], v[184:187], v[124:127]
	v_mfma_f32_16x16x32_bf16 v[116:119], v[140:143], v[184:187], v[116:119]
	v_mfma_f32_16x16x32_bf16 v[120:123], v[132:135], v[192:195], v[120:123]
	v_mfma_f32_16x16x32_bf16 v[112:115], v[140:143], v[192:195], v[112:115]
	v_mfma_f32_16x16x32_bf16 v[104:107], v[132:135], v[200:203], v[104:107]
	v_mfma_f32_16x16x32_bf16 v[108:111], v[140:143], v[200:203], v[108:111]
	v_mfma_f32_16x16x32_bf16 v[80:83], v[132:135], v[208:211], v[80:83]
	v_mfma_f32_16x16x32_bf16 v[92:95], v[140:143], v[208:211], v[92:95]
	v_mfma_f32_16x16x32_bf16 v[100:103], v[164:167], v[180:183], v[100:103]
	v_mfma_f32_16x16x32_bf16 v[76:79], v[172:175], v[180:183], v[76:79]
	v_mfma_f32_16x16x32_bf16 v[96:99], v[164:167], v[188:191], v[96:99]
	v_mfma_f32_16x16x32_bf16 v[72:75], v[172:175], v[188:191], v[72:75]
	v_mfma_f32_16x16x32_bf16 v[88:91], v[164:167], v[196:199], v[88:91]
	v_mfma_f32_16x16x32_bf16 v[68:71], v[172:175], v[196:199], v[68:71]
	v_mfma_f32_16x16x32_bf16 v[84:87], v[164:167], v[204:207], v[84:87]
	v_mfma_f32_16x16x32_bf16 v[64:67], v[172:175], v[204:207], v[64:67]
	v_mfma_f32_16x16x32_bf16 v[100:103], v[168:171], v[184:187], v[100:103]
	v_mfma_f32_16x16x32_bf16 v[76:79], v[176:179], v[184:187], v[76:79]
	v_mfma_f32_16x16x32_bf16 v[96:99], v[168:171], v[192:195], v[96:99]
	v_mfma_f32_16x16x32_bf16 v[72:75], v[176:179], v[192:195], v[72:75]
	v_mfma_f32_16x16x32_bf16 v[88:91], v[168:171], v[200:203], v[88:91]
	v_mfma_f32_16x16x32_bf16 v[68:71], v[176:179], v[200:203], v[68:71]
	v_mfma_f32_16x16x32_bf16 v[84:87], v[168:171], v[208:211], v[84:87]
	v_mfma_f32_16x16x32_bf16 v[64:67], v[176:179], v[208:211], v[64:67]
	s_setprio 0
	s_barrier
	s_add_i32 s79, s15, s59
	v_lshl_add_u64 v[212:213], s[8:9], 0, v[148:149]
	s_mov_b32 m0, s79
	ds_read_b128 v[180:183], v222 offset:16384
	ds_read_b128 v[184:187], v222 offset:17408
	ds_read_b128 v[188:191], v222 offset:18432
	ds_read_b128 v[192:195], v222 offset:19456
	ds_read_b128 v[196:199], v222 offset:20480
	ds_read_b128 v[200:203], v222 offset:21504
	ds_read_b128 v[204:207], v222 offset:22528
	ds_read_b128 v[208:211], v222 offset:23552
	global_load_lds_dwordx4 v[212:213], off
	s_add_i32 m0, s79, 0x2000
	s_add_u32 vcc_lo, s8, 0x80000
	v_lshl_add_u64 v[214:215], s[8:9], 0, v[152:153]
	s_addc_u32 vcc_hi, s9, 0
	s_add_i32 s79, s87, s59
	global_load_lds_dwordx4 v[214:215], off
	v_lshl_add_u64 v[226:227], vcc, 0, v[148:149]
	s_mov_b32 m0, s79
	v_lshl_add_u64 v[228:229], s[10:11], 0, v[150:151]
	global_load_lds_dwordx4 v[226:227], off
	v_lshl_add_u64 v[226:227], vcc, 0, v[152:153]
	s_add_i32 m0, s79, 0x2000
	s_nop 0
	global_load_lds_dwordx4 v[226:227], off
	v_lshl_add_u64 v[226:227], s[10:11], 0, v[146:147]
	s_mov_b32 m0, s61
	s_nop 0
	global_load_lds_dwordx4 v[226:227], off
	s_mov_b32 m0, s63
	s_nop 0
	global_load_lds_dwordx4 v[228:229], off
	s_waitcnt vmcnt(8)
	s_waitcnt lgkmcnt(0)
	s_barrier
; #define PG8_STAGE(bufoff, gbase, voff) do { _Pragma("unroll") for (int _i = 0; _i < 2; ++_i) \
;         __builtin_amdgcn_global_load_lds((const unsigned*)((const char*)(gbase) + (voff)[_i]), (PG8_LAS unsigned*)(lds + (bufoff) + ldsw + _i * 8192), 16, 0, 0); } while (0)
; #define PG8_LDA(dst, b, h) do { _Pragma("unroll") for (int m = 0; m < 4; ++m) _Pragma("unroll") for (int k = 0; k < 2; ++k) dst[m][k] = *(const PG8_LAS bf16x8*)(lds + PG8_SA(b, h) + aoff + m * 2048 + k * 1024); } while (0)
; #define PG8_LDB(dst, b, h) do { _Pragma("unroll") for (int n = 0; n < 2; ++n) _Pragma("unroll") for (int k = 0; k < 2; ++k) dst[n][k] = *(const PG8_LAS bf16x8*)(lds + PG8_SB(b, h) + boff + n * 2048 + k * 1024); } while (0)
; #define PG8_MMA(ai, bj, At, Bt) do { __builtin_amdgcn_s_setprio(1); _Pragma("unroll") for (int m = 0; m < 4; ++m) _Pragma("unroll") for (int n = 0; n < 2; ++n) _Pragma("unroll") for (int k = 0; k < 2; ++k) \
;         acc[ai][bj][m][n] = __builtin_amdgcn_mfma_f32_16x16x32_bf16(Bt[n][k], At[m][k], acc[ai][bj][m][n], 0, 0, 0); __builtin_amdgcn_s_setprio(0); } while (0)
; #define PG8_WAIT_V(n) asm volatile("s_waitcnt vmcnt(" #n ")" ::: "memory")
; #define PG8_WAIT_L(n) asm volatile("s_waitcnt lgkmcnt(" #n ")" ::: "memory")
; #define PG8_BAR __builtin_amdgcn_s_barrier()
; #define PG8_SCHED __builtin_amdgcn_sched_barrier(0)
; template <class Epi, class Sched, bool ALIGN_EPI = false, bool SP2 = false>
; __device__ __forceinline__ void gemm_phase(PG8_LAS unsigned char* lds, const Gemm g, const Sched& S, const Epi& E) {
;     ...
;             PG8_WAIT_V(8); PG8_WAIT_L(0); PG8_BAR; PG8_MMA(1, 0, At, B0); PG8_MMA(1, 1, At, B1); PG8_BAR; PG8_SCHED;
;             PG8_LDB(B0, 1, 0); PG8_LDB(B1, 1, 1); PG8_SCHED; PG8_LDA(At, 1, 0); PG8_STAGE(PG8_SA(0, 1), a2 + hstep, voffA);
;             PG8_WAIT_V(8); PG8_WAIT_L(0); PG8_BAR; PG8_MMA(0, 0, At, B0); PG8_MMA(0, 1, At, B1); PG8_BAR; PG8_SCHED;
	s_setprio 1
	s_waitcnt lgkmcnt(0)
	v_mfma_f32_16x16x32_bf16 v[60:63], v[128:131], v[180:183], v[60:63]
	v_mfma_f32_16x16x32_bf16 v[44:47], v[136:139], v[180:183], v[44:47]
	v_mfma_f32_16x16x32_bf16 v[56:59], v[128:131], v[188:191], v[56:59]
	v_mfma_f32_16x16x32_bf16 v[40:43], v[136:139], v[188:191], v[40:43]
	v_mfma_f32_16x16x32_bf16 v[52:55], v[128:131], v[196:199], v[52:55]
	v_mfma_f32_16x16x32_bf16 v[36:39], v[136:139], v[196:199], v[36:39]
	v_mfma_f32_16x16x32_bf16 v[48:51], v[128:131], v[204:207], v[48:51]
	v_mfma_f32_16x16x32_bf16 v[32:35], v[136:139], v[204:207], v[32:35]
	v_mfma_f32_16x16x32_bf16 v[60:63], v[132:135], v[184:187], v[60:63]
	v_mfma_f32_16x16x32_bf16 v[44:47], v[140:143], v[184:187], v[44:47]
	v_mfma_f32_16x16x32_bf16 v[56:59], v[132:135], v[192:195], v[56:59]
	v_mfma_f32_16x16x32_bf16 v[40:43], v[140:143], v[192:195], v[40:43]
	v_mfma_f32_16x16x32_bf16 v[52:55], v[132:135], v[200:203], v[52:55]
	v_mfma_f32_16x16x32_bf16 v[36:39], v[140:143], v[200:203], v[36:39]
	v_mfma_f32_16x16x32_bf16 v[48:51], v[132:135], v[208:211], v[48:51]
	v_mfma_f32_16x16x32_bf16 v[32:35], v[140:143], v[208:211], v[32:35]
	v_mfma_f32_16x16x32_bf16 v[28:31], v[164:167], v[180:183], v[28:31]
	v_mfma_f32_16x16x32_bf16 v[12:15], v[172:175], v[180:183], v[12:15]
	v_mfma_f32_16x16x32_bf16 v[24:27], v[164:167], v[188:191], v[24:27]
	v_mfma_f32_16x16x32_bf16 v[8:11], v[172:175], v[188:191], v[8:11]
	v_mfma_f32_16x16x32_bf16 v[20:23], v[164:167], v[196:199], v[20:23]
	v_mfma_f32_16x16x32_bf16 v[4:7], v[172:175], v[196:199], v[4:7]
	v_mfma_f32_16x16x32_bf16 v[16:19], v[164:167], v[204:207], v[16:19]
	v_mfma_f32_16x16x32_bf16 v[0:3], v[172:175], v[204:207], v[0:3]
	v_mfma_f32_16x16x32_bf16 v[28:31], v[168:171], v[184:187], v[28:31]
	v_mfma_f32_16x16x32_bf16 v[12:15], v[176:179], v[184:187], v[12:15]
	v_mfma_f32_16x16x32_bf16 v[24:27], v[168:171], v[192:195], v[24:27]
	v_mfma_f32_16x16x32_bf16 v[8:11], v[176:179], v[192:195], v[8:11]
	v_mfma_f32_16x16x32_bf16 v[20:23], v[168:171], v[200:203], v[20:23]
	v_mfma_f32_16x16x32_bf16 v[4:7], v[176:179], v[200:203], v[4:7]
	v_mfma_f32_16x16x32_bf16 v[16:19], v[168:171], v[208:211], v[16:19]
	v_mfma_f32_16x16x32_bf16 v[0:3], v[176:179], v[208:211], v[0:3]
	s_setprio 0
	s_barrier
	s_add_i32 s79, 0, 0x18000
	s_add_i32 vcc_lo, 0, 0x1c000
	v_add_u32_e32 v140, s79, v219
	v_add_u32_e32 v154, vcc_lo, v219
	ds_read_b128 v[128:131], v140
	ds_read_b128 v[132:135], v140 offset:1024
	ds_read_b128 v[136:139], v140 offset:2048
	ds_read_b128 v[140:143], v140 offset:3072
	ds_read_b128 v[164:167], v154
	ds_read_b128 v[168:171], v154 offset:1024
	ds_read_b128 v[172:175], v154 offset:2048
	ds_read_b128 v[176:179], v154 offset:3072
	s_add_u32 s10, s10, 0x80000
	s_addc_u32 s11, s11, 0
	s_mov_b32 m0, s65
	v_lshl_add_u64 v[230:231], s[10:11], 0, v[146:147]
	ds_read_b128 v[180:183], v222 offset:32768
	ds_read_b128 v[184:187], v222 offset:33792
	ds_read_b128 v[188:191], v222 offset:34816
	ds_read_b128 v[192:195], v222 offset:35840
	ds_read_b128 v[196:199], v222 offset:36864
	ds_read_b128 v[200:203], v222 offset:37888
	ds_read_b128 v[204:207], v222 offset:38912
	ds_read_b128 v[208:211], v222 offset:39936
	global_load_lds_dwordx4 v[230:231], off
	v_lshl_add_u64 v[230:231], s[10:11], 0, v[150:151]
	s_mov_b32 m0, s67
	s_nop 0
	global_load_lds_dwordx4 v[230:231], off
	s_waitcnt vmcnt(8)
	s_waitcnt lgkmcnt(0)
	s_barrier
	s_setprio 1
	s_waitcnt lgkmcnt(0)
	v_mfma_f32_16x16x32_bf16 v[124:127], v[128:131], v[180:183], v[124:127]
	v_mfma_f32_16x16x32_bf16 v[116:119], v[136:139], v[180:183], v[116:119]
	v_mfma_f32_16x16x32_bf16 v[120:123], v[128:131], v[188:191], v[120:123]
	v_mfma_f32_16x16x32_bf16 v[112:115], v[136:139], v[188:191], v[112:115]
	v_mfma_f32_16x16x32_bf16 v[104:107], v[128:131], v[196:199], v[104:107]
	v_mfma_f32_16x16x32_bf16 v[108:111], v[136:139], v[196:199], v[108:111]
	v_mfma_f32_16x16x32_bf16 v[80:83], v[128:131], v[204:207], v[80:83]
	v_mfma_f32_16x16x32_bf16 v[92:95], v[136:139], v[204:207], v[92:95]
	v_mfma_f32_16x16x32_bf16 v[124:127], v[132:135], v[184:187], v[124:127]
	v_mfma_f32_16x16x32_bf16 v[116:119], v[140:143], v[184:187], v[116:119]
	v_mfma_f32_16x16x32_bf16 v[120:123], v[132:135], v[192:195], v[120:123]
	v_mfma_f32_16x16x32_bf16 v[112:115], v[140:143], v[192:195], v[112:115]
	v_mfma_f32_16x16x32_bf16 v[104:107], v[132:135], v[200:203], v[104:107]
	v_mfma_f32_16x16x32_bf16 v[108:111], v[140:143], v[200:203], v[108:111]
	v_mfma_f32_16x16x32_bf16 v[80:83], v[132:135], v[208:211], v[80:83]
	v_mfma_f32_16x16x32_bf16 v[92:95], v[140:143], v[208:211], v[92:95]
	v_mfma_f32_16x16x32_bf16 v[100:103], v[164:167], v[180:183], v[100:103]
	v_mfma_f32_16x16x32_bf16 v[76:79], v[172:175], v[180:183], v[76:79]
	v_mfma_f32_16x16x32_bf16 v[96:99], v[164:167], v[188:191], v[96:99]
	v_mfma_f32_16x16x32_bf16 v[72:75], v[172:175], v[188:191], v[72:75]
	v_mfma_f32_16x16x32_bf16 v[88:91], v[164:167], v[196:199], v[88:91]
	v_mfma_f32_16x16x32_bf16 v[68:71], v[172:175], v[196:199], v[68:71]
	v_mfma_f32_16x16x32_bf16 v[84:87], v[164:167], v[204:207], v[84:87]
	v_mfma_f32_16x16x32_bf16 v[64:67], v[172:175], v[204:207], v[64:67]
	v_mfma_f32_16x16x32_bf16 v[100:103], v[168:171], v[184:187], v[100:103]
	v_mfma_f32_16x16x32_bf16 v[76:79], v[176:179], v[184:187], v[76:79]
	v_mfma_f32_16x16x32_bf16 v[96:99], v[168:171], v[192:195], v[96:99]
	v_mfma_f32_16x16x32_bf16 v[72:75], v[176:179], v[192:195], v[72:75]
	v_mfma_f32_16x16x32_bf16 v[88:91], v[168:171], v[200:203], v[88:91]
	v_mfma_f32_16x16x32_bf16 v[68:71], v[176:179], v[200:203], v[68:71]
	v_mfma_f32_16x16x32_bf16 v[84:87], v[168:171], v[208:211], v[84:87]
	v_mfma_f32_16x16x32_bf16 v[64:67], v[176:179], v[208:211], v[64:67]
	s_setprio 0
	s_barrier
; #define PG8_STAGE(bufoff, gbase, voff) do { _Pragma("unroll") for (int _i = 0; _i < 2; ++_i) \
;         __builtin_amdgcn_global_load_lds((const unsigned*)((const char*)(gbase) + (voff)[_i]), (PG8_LAS unsigned*)(lds + (bufoff) + ldsw + _i * 8192), 16, 0, 0); } while (0)
; #define PG8_LDA(dst, b, h) do { _Pragma("unroll") for (int m = 0; m < 4; ++m) _Pragma("unroll") for (int k = 0; k < 2; ++k) dst[m][k] = *(const PG8_LAS bf16x8*)(lds + PG8_SA(b, h) + aoff + m * 2048 + k * 1024); } while (0)
; #define PG8_MMA(ai, bj, At, Bt) do { __builtin_amdgcn_s_setprio(1); _Pragma("unroll") for (int m = 0; m < 4; ++m) _Pragma("unroll") for (int n = 0; n < 2; ++n) _Pragma("unroll") for (int k = 0; k < 2; ++k) \
;         acc[ai][bj][m][n] = __builtin_amdgcn_mfma_f32_16x16x32_bf16(Bt[n][k], At[m][k], acc[ai][bj][m][n], 0, 0, 0); __builtin_amdgcn_s_setprio(0); } while (0)
; #define PG8_WAIT_V(n) asm volatile("s_waitcnt vmcnt(" #n ")" ::: "memory")
; #define PG8_WAIT_L(n) asm volatile("s_waitcnt lgkmcnt(" #n ")" ::: "memory")
; #define PG8_BAR __builtin_amdgcn_s_barrier()
; #define PG8_SCHED __builtin_amdgcn_sched_barrier(0)
; template <class Epi, class Sched, bool ALIGN_EPI = false, bool SP2 = false>
; __device__ __forceinline__ void gemm_phase(PG8_LAS unsigned char* lds, const Gemm g, const Sched& S, const Epi& E) {
;     ...
;             PG8_LDA(At, 1, 1); PG8_STAGE(PG8_SB(1, 0), b3, voffB); PG8_STAGE(PG8_SB(1, 1), b3 + hstep, voffB); PG8_STAGE(PG8_SA(1, 0), a3, voffA);
;             PG8_WAIT_V(8); PG8_WAIT_L(0); PG8_BAR; PG8_MMA(1, 0, At, B0); PG8_MMA(1, 1, At, B1); PG8_BAR; PG8_SCHED;
;     ...
;         if constexpr (ALIGN_EPI) { if (wr == 0) PG8_BAR; }
	s_add_i32 s10, s79, s59
	v_lshl_add_u64 v[212:213], v[212:213], 0, s[46:47]
	s_mov_b32 m0, s10
	ds_read_b128 v[180:183], v222 offset:49152
	ds_read_b128 v[184:187], v222 offset:50176
	ds_read_b128 v[188:191], v222 offset:51200
	ds_read_b128 v[192:195], v222 offset:52224
	ds_read_b128 v[196:199], v222 offset:53248
	ds_read_b128 v[200:203], v222 offset:54272
	ds_read_b128 v[204:207], v222 offset:55296
	ds_read_b128 v[208:211], v222 offset:56320
	global_load_lds_dwordx4 v[212:213], off
	s_add_i32 m0, s10, 0x2000
	s_add_u32 s8, s8, 0x80080
	v_lshl_add_u64 v[212:213], v[214:215], 0, s[46:47]
	s_addc_u32 s9, s9, 0
	s_add_i32 s10, vcc_lo, s59
	global_load_lds_dwordx4 v[212:213], off
	v_lshl_add_u64 v[212:213], s[8:9], 0, v[148:149]
	s_mov_b32 m0, s10
	s_nop 0
	global_load_lds_dwordx4 v[212:213], off
	v_lshl_add_u64 v[212:213], s[8:9], 0, v[152:153]
	s_add_i32 m0, s10, 0x2000
	s_nop 0
	global_load_lds_dwordx4 v[212:213], off
	v_lshl_add_u64 v[212:213], v[226:227], 0, s[46:47]
	s_mov_b32 m0, s84
	s_nop 0
	global_load_lds_dwordx4 v[212:213], off
	v_lshl_add_u64 v[212:213], v[228:229], 0, s[46:47]
	s_mov_b32 m0, s85
	s_nop 0
	global_load_lds_dwordx4 v[212:213], off
	s_waitcnt vmcnt(8)
	s_waitcnt lgkmcnt(0)
	s_barrier
	s_setprio 1
	s_waitcnt lgkmcnt(0)
	v_mfma_f32_16x16x32_bf16 v[60:63], v[128:131], v[180:183], v[60:63]
	v_mfma_f32_16x16x32_bf16 v[44:47], v[136:139], v[180:183], v[44:47]
	v_mfma_f32_16x16x32_bf16 v[56:59], v[128:131], v[188:191], v[56:59]
	v_mfma_f32_16x16x32_bf16 v[40:43], v[136:139], v[188:191], v[40:43]
	v_mfma_f32_16x16x32_bf16 v[52:55], v[128:131], v[196:199], v[52:55]
	v_mfma_f32_16x16x32_bf16 v[36:39], v[136:139], v[196:199], v[36:39]
	v_mfma_f32_16x16x32_bf16 v[48:51], v[128:131], v[204:207], v[48:51]
	v_mfma_f32_16x16x32_bf16 v[32:35], v[136:139], v[204:207], v[32:35]
	v_mfma_f32_16x16x32_bf16 v[60:63], v[132:135], v[184:187], v[60:63]
	v_mfma_f32_16x16x32_bf16 v[44:47], v[140:143], v[184:187], v[44:47]
	v_mfma_f32_16x16x32_bf16 v[56:59], v[132:135], v[192:195], v[56:59]
	v_mfma_f32_16x16x32_bf16 v[40:43], v[140:143], v[192:195], v[40:43]
	v_mfma_f32_16x16x32_bf16 v[52:55], v[132:135], v[200:203], v[52:55]
	v_mfma_f32_16x16x32_bf16 v[36:39], v[140:143], v[200:203], v[36:39]
	v_mfma_f32_16x16x32_bf16 v[48:51], v[132:135], v[208:211], v[48:51]
	v_mfma_f32_16x16x32_bf16 v[32:35], v[140:143], v[208:211], v[32:35]
	v_mfma_f32_16x16x32_bf16 v[28:31], v[164:167], v[180:183], v[28:31]
	v_mfma_f32_16x16x32_bf16 v[12:15], v[172:175], v[180:183], v[12:15]
	v_mfma_f32_16x16x32_bf16 v[24:27], v[164:167], v[188:191], v[24:27]
	v_mfma_f32_16x16x32_bf16 v[8:11], v[172:175], v[188:191], v[8:11]
	v_mfma_f32_16x16x32_bf16 v[20:23], v[164:167], v[196:199], v[20:23]
	v_mfma_f32_16x16x32_bf16 v[4:7], v[172:175], v[196:199], v[4:7]
	v_mfma_f32_16x16x32_bf16 v[16:19], v[164:167], v[204:207], v[16:19]
	v_mfma_f32_16x16x32_bf16 v[0:3], v[172:175], v[204:207], v[0:3]
	v_mfma_f32_16x16x32_bf16 v[28:31], v[168:171], v[184:187], v[28:31]
	v_mfma_f32_16x16x32_bf16 v[12:15], v[176:179], v[184:187], v[12:15]
	v_mfma_f32_16x16x32_bf16 v[24:27], v[168:171], v[192:195], v[24:27]
	v_mfma_f32_16x16x32_bf16 v[8:11], v[176:179], v[192:195], v[8:11]
	v_mfma_f32_16x16x32_bf16 v[20:23], v[168:171], v[200:203], v[20:23]
	v_mfma_f32_16x16x32_bf16 v[4:7], v[176:179], v[200:203], v[4:7]
	v_mfma_f32_16x16x32_bf16 v[16:19], v[168:171], v[208:211], v[16:19]
	v_mfma_f32_16x16x32_bf16 v[0:3], v[176:179], v[208:211], v[0:3]
	s_setprio 0
	s_barrier
	s_add_i32 s73, s73, 2
	s_add_u32 s0, s0, 0x100
	s_addc_u32 s1, s1, 0
	s_add_u32 s37, s37, 0x100
	s_addc_u32 s71, s71, 0
	s_cmp_gt_u32 s73, 29
	s_cbranch_scc0 .LBB0_1701
	v_readlane_b32 s0, v244, 56
	v_readlane_b32 s1, v244, 57
	s_and_b64 vcc, exec, s[0:1]
	s_cbranch_vccz .LBB0_1704
	s_barrier

; #define PG8_STAGE(bufoff, gbase, voff) do { _Pragma("unroll") for (int _i = 0; _i < 2; ++_i) \
;         __builtin_amdgcn_global_load_lds((const unsigned*)((const char*)(gbase) + (voff)[_i]), (PG8_LAS unsigned*)(lds + (bufoff) + ldsw + _i * 8192), 16, 0, 0); } while (0)
; #define PG8_LDA(dst, b, h) do { _Pragma("unroll") for (int m = 0; m < 4; ++m) _Pragma("unroll") for (int k = 0; k < 2; ++k) dst[m][k] = *(const PG8_LAS bf16x8*)(lds + PG8_SA(b, h) + aoff + m * 2048 + k * 1024); } while (0)
; #define PG8_LDB(dst, b, h) do { _Pragma("unroll") for (int n = 0; n < 2; ++n) _Pragma("unroll") for (int k = 0; k < 2; ++k) dst[n][k] = *(const PG8_LAS bf16x8*)(lds + PG8_SB(b, h) + boff + n * 2048 + k * 1024); } while (0)
; #define PG8_MMA(ai, bj, At, Bt) do { __builtin_amdgcn_s_setprio(1); _Pragma("unroll") for (int m = 0; m < 4; ++m) _Pragma("unroll") for (int n = 0; n < 2; ++n) _Pragma("unroll") for (int k = 0; k < 2; ++k) \
;         acc[ai][bj][m][n] = __builtin_amdgcn_mfma_f32_16x16x32_bf16(Bt[n][k], At[m][k], acc[ai][bj][m][n], 0, 0, 0); __builtin_amdgcn_s_setprio(0); } while (0)
; #define PG8_WAIT_V(n) asm volatile("s_waitcnt vmcnt(" #n ")" ::: "memory")
; #define PG8_WAIT_L(n) asm volatile("s_waitcnt lgkmcnt(" #n ")" ::: "memory")
; template <class Epi, class Sched, bool ALIGN_EPI = false, bool SP2 = false>
; __device__ __forceinline__ void gemm_phase(PG8_LAS unsigned char* lds, const Gemm g, const Sched& S, const Epi& E) {
;     ...
;             const bool last = (t == nt - 2);
;             const char* a1 = cA + (size_t)(t + 1) * kstep;
;             const char* a2 = last ? nA : cA + (size_t)(t + 2) * kstep; const char* b2 = last ? nB : cB + (size_t)(t + 2) * kstep;
;             const char* a3 = a2 + kstep; const char* b3 = b2 + kstep;
;             if (last && has_next) S.a_ready(nxt);
;             if constexpr (SP2) {
;             PG8_LDB(B0, 0, 0); PG8_LDB(B1, 0, 1); PG8_SCHED; PG8_LDA(At, 0, 0); PG8_STAGE(PG8_SA(1, 1), a1 + hstep, voffA);
;             PG8_WAIT_V(8); PG8_WAIT_L(0); PG8_BAR; PG8_MMA(0, 0, At, B0); PG8_MMA(0, 1, At, B1); PG8_BAR; PG8_SCHED;
;             PG8_LDA(At, 0, 1); PG8_STAGE(PG8_SB(0, 0), b2, voffB); PG8_STAGE(PG8_SB(0, 1), b2 + hstep, voffB); PG8_STAGE(PG8_SA(0, 0), a2, voffA);
;             PG8_WAIT_V(8); PG8_WAIT_L(0); PG8_BAR; PG8_MMA(1, 0, At, B0); PG8_MMA(1, 1, At, B1); PG8_BAR; PG8_SCHED;
.LBB0_1924:
	ds_read_b128 v[146:149], v153
	ds_read_b128 v[158:161], v153 offset:1024
	ds_read_b128 v[162:165], v153 offset:2048
	ds_read_b128 v[166:169], v153 offset:3072
	ds_read_b128 v[170:173], v154
	ds_read_b128 v[174:177], v154 offset:1024
	ds_read_b128 v[178:181], v154 offset:2048
	ds_read_b128 v[182:185], v154 offset:3072
	s_add_u32 s36, s22, 0xffea0080
	s_addc_u32 s37, s23, -1
	s_cmpk_eq_i32 s63, 0x54
	s_cselect_b32 s39, s5, s37
	s_cselect_b32 s38, s4, s36
	s_cselect_b32 s37, s21, s62
	s_cselect_b32 s36, s20, s61
	v_lshl_add_u64 v[218:219], s[22:23], 0, v[136:137]
	s_add_i32 m0, s43, 0xc000
	ds_read_b128 v[186:189], v155
	ds_read_b128 v[190:193], v155 offset:1024
	ds_read_b128 v[194:197], v155 offset:2048
	ds_read_b128 v[198:201], v155 offset:3072
	ds_read_b128 v[202:205], v155 offset:4096
	ds_read_b128 v[206:209], v155 offset:5120
	ds_read_b128 v[210:213], v155 offset:6144
	ds_read_b128 v[214:217], v155 offset:7168
	global_load_lds_dwordx4 v[218:219], off
	v_lshl_add_u64 v[218:219], s[22:23], 0, v[138:139]
	s_add_i32 m0, s43, 0xe000
	s_nop 0
	global_load_lds_dwordx4 v[218:219], off
	s_waitcnt vmcnt(8)
	s_waitcnt lgkmcnt(0)
	s_barrier
	s_setprio 1
	s_waitcnt lgkmcnt(0)
	v_mfma_f32_16x16x32_bf16 v[124:127], v[146:149], v[186:189], v[124:127]
	v_mfma_f32_16x16x32_bf16 v[120:123], v[162:165], v[186:189], v[120:123]
	v_mfma_f32_16x16x32_bf16 v[108:111], v[146:149], v[194:197], v[108:111]
	v_mfma_f32_16x16x32_bf16 v[104:107], v[162:165], v[194:197], v[104:107]
	v_mfma_f32_16x16x32_bf16 v[92:95], v[146:149], v[202:205], v[92:95]
	v_mfma_f32_16x16x32_bf16 v[88:91], v[162:165], v[202:205], v[88:91]
	v_mfma_f32_16x16x32_bf16 v[76:79], v[146:149], v[210:213], v[76:79]
	v_mfma_f32_16x16x32_bf16 v[72:75], v[162:165], v[210:213], v[72:75]
	v_mfma_f32_16x16x32_bf16 v[124:127], v[158:161], v[190:193], v[124:127]
	v_mfma_f32_16x16x32_bf16 v[120:123], v[166:169], v[190:193], v[120:123]
	v_mfma_f32_16x16x32_bf16 v[108:111], v[158:161], v[198:201], v[108:111]
	v_mfma_f32_16x16x32_bf16 v[104:107], v[166:169], v[198:201], v[104:107]
	v_mfma_f32_16x16x32_bf16 v[92:95], v[158:161], v[206:209], v[92:95]
	v_mfma_f32_16x16x32_bf16 v[88:91], v[166:169], v[206:209], v[88:91]
	v_mfma_f32_16x16x32_bf16 v[76:79], v[158:161], v[214:217], v[76:79]
	v_mfma_f32_16x16x32_bf16 v[72:75], v[166:169], v[214:217], v[72:75]
	v_mfma_f32_16x16x32_bf16 v[116:119], v[170:173], v[186:189], v[116:119]
	v_mfma_f32_16x16x32_bf16 v[112:115], v[178:181], v[186:189], v[112:115]
	v_mfma_f32_16x16x32_bf16 v[100:103], v[170:173], v[194:197], v[100:103]
	v_mfma_f32_16x16x32_bf16 v[96:99], v[178:181], v[194:197], v[96:99]
	v_mfma_f32_16x16x32_bf16 v[84:87], v[170:173], v[202:205], v[84:87]
	v_mfma_f32_16x16x32_bf16 v[80:83], v[178:181], v[202:205], v[80:83]
	v_mfma_f32_16x16x32_bf16 v[68:71], v[170:173], v[210:213], v[68:71]
	v_mfma_f32_16x16x32_bf16 v[64:67], v[178:181], v[210:213], v[64:67]
	v_mfma_f32_16x16x32_bf16 v[116:119], v[174:177], v[190:193], v[116:119]
	v_mfma_f32_16x16x32_bf16 v[112:115], v[182:185], v[190:193], v[112:115]
	v_mfma_f32_16x16x32_bf16 v[100:103], v[174:177], v[198:201], v[100:103]
	v_mfma_f32_16x16x32_bf16 v[96:99], v[182:185], v[198:201], v[96:99]
	v_mfma_f32_16x16x32_bf16 v[84:87], v[174:177], v[206:209], v[84:87]
	v_mfma_f32_16x16x32_bf16 v[80:83], v[182:185], v[206:209], v[80:83]
	v_mfma_f32_16x16x32_bf16 v[68:71], v[174:177], v[214:217], v[68:71]
	v_mfma_f32_16x16x32_bf16 v[64:67], v[182:185], v[214:217], v[64:67]
	s_setprio 0
	s_barrier
	s_add_i32 s64, s55, s42
	v_lshl_add_u64 v[218:219], s[36:37], 0, v[130:131]
	s_mov_b32 m0, s64
	ds_read_b128 v[186:189], v155 offset:16384
	ds_read_b128 v[190:193], v155 offset:17408
	ds_read_b128 v[194:197], v155 offset:18432
	ds_read_b128 v[198:201], v155 offset:19456
	ds_read_b128 v[202:205], v155 offset:20480
	ds_read_b128 v[206:209], v155 offset:21504
	ds_read_b128 v[210:213], v155 offset:22528
	ds_read_b128 v[214:217], v155 offset:23552
	global_load_lds_dwordx4 v[218:219], off
	s_add_i32 m0, s64, 0x2000
	s_add_u32 s64, s36, 0x160000
	v_lshl_add_u64 v[220:221], s[36:37], 0, v[134:135]
	s_addc_u32 s65, s37, 0
	s_add_i32 s66, s56, s42
	global_load_lds_dwordx4 v[220:221], off
	v_lshl_add_u64 v[222:223], s[64:65], 0, v[130:131]
	s_mov_b32 m0, s66
	v_lshl_add_u64 v[224:225], s[38:39], 0, v[132:133]
	global_load_lds_dwordx4 v[222:223], off
	v_lshl_add_u64 v[222:223], s[64:65], 0, v[134:135]
	s_add_i32 m0, s66, 0x2000
	s_nop 0
	global_load_lds_dwordx4 v[222:223], off
	v_lshl_add_u64 v[222:223], s[38:39], 0, v[128:129]
	s_mov_b32 m0, s43
	s_nop 0
	global_load_lds_dwordx4 v[222:223], off
	s_mov_b32 m0, s44
	s_nop 0
	global_load_lds_dwordx4 v[224:225], off
	s_waitcnt vmcnt(8)
	s_waitcnt lgkmcnt(0)
	s_barrier
; #define PG8_STAGE(bufoff, gbase, voff) do { _Pragma("unroll") for (int _i = 0; _i < 2; ++_i) \
;         __builtin_amdgcn_global_load_lds((const unsigned*)((const char*)(gbase) + (voff)[_i]), (PG8_LAS unsigned*)(lds + (bufoff) + ldsw + _i * 8192), 16, 0, 0); } while (0)
; #define PG8_LDA(dst, b, h) do { _Pragma("unroll") for (int m = 0; m < 4; ++m) _Pragma("unroll") for (int k = 0; k < 2; ++k) dst[m][k] = *(const PG8_LAS bf16x8*)(lds + PG8_SA(b, h) + aoff + m * 2048 + k * 1024); } while (0)
; #define PG8_LDB(dst, b, h) do { _Pragma("unroll") for (int n = 0; n < 2; ++n) _Pragma("unroll") for (int k = 0; k < 2; ++k) dst[n][k] = *(const PG8_LAS bf16x8*)(lds + PG8_SB(b, h) + boff + n * 2048 + k * 1024); } while (0)
; #define PG8_MMA(ai, bj, At, Bt) do { __builtin_amdgcn_s_setprio(1); _Pragma("unroll") for (int m = 0; m < 4; ++m) _Pragma("unroll") for (int n = 0; n < 2; ++n) _Pragma("unroll") for (int k = 0; k < 2; ++k) \
;         acc[ai][bj][m][n] = __builtin_amdgcn_mfma_f32_16x16x32_bf16(Bt[n][k], At[m][k], acc[ai][bj][m][n], 0, 0, 0); __builtin_amdgcn_s_setprio(0); } while (0)
; #define PG8_WAIT_V(n) asm volatile("s_waitcnt vmcnt(" #n ")" ::: "memory")
; #define PG8_WAIT_L(n) asm volatile("s_waitcnt lgkmcnt(" #n ")" ::: "memory")
; #define PG8_BAR __builtin_amdgcn_s_barrier()
; #define PG8_SCHED __builtin_amdgcn_sched_barrier(0)
; template <class Epi, class Sched, bool ALIGN_EPI = false, bool SP2 = false>
; __device__ __forceinline__ void gemm_phase(PG8_LAS unsigned char* lds, const Gemm g, const Sched& S, const Epi& E) {
;     ...
;             PG8_WAIT_V(8); PG8_WAIT_L(0); PG8_BAR; PG8_MMA(1, 0, At, B0); PG8_MMA(1, 1, At, B1); PG8_BAR; PG8_SCHED;
;             PG8_LDB(B0, 1, 0); PG8_LDB(B1, 1, 1); PG8_SCHED; PG8_LDA(At, 1, 0); PG8_STAGE(PG8_SA(0, 1), a2 + hstep, voffA);
;             PG8_WAIT_V(8); PG8_WAIT_L(0); PG8_BAR; PG8_MMA(0, 0, At, B0); PG8_MMA(0, 1, At, B1); PG8_BAR; PG8_SCHED;
	s_setprio 1
	s_waitcnt lgkmcnt(0)
	v_mfma_f32_16x16x32_bf16 v[60:63], v[146:149], v[186:189], v[60:63]
	v_mfma_f32_16x16x32_bf16 v[56:59], v[162:165], v[186:189], v[56:59]
	v_mfma_f32_16x16x32_bf16 v[44:47], v[146:149], v[194:197], v[44:47]
	v_mfma_f32_16x16x32_bf16 v[40:43], v[162:165], v[194:197], v[40:43]
	v_mfma_f32_16x16x32_bf16 v[28:31], v[146:149], v[202:205], v[28:31]
	v_mfma_f32_16x16x32_bf16 v[24:27], v[162:165], v[202:205], v[24:27]
	v_mfma_f32_16x16x32_bf16 v[12:15], v[146:149], v[210:213], v[12:15]
	v_mfma_f32_16x16x32_bf16 v[8:11], v[162:165], v[210:213], v[8:11]
	v_mfma_f32_16x16x32_bf16 v[60:63], v[158:161], v[190:193], v[60:63]
	v_mfma_f32_16x16x32_bf16 v[56:59], v[166:169], v[190:193], v[56:59]
	v_mfma_f32_16x16x32_bf16 v[44:47], v[158:161], v[198:201], v[44:47]
	v_mfma_f32_16x16x32_bf16 v[40:43], v[166:169], v[198:201], v[40:43]
	v_mfma_f32_16x16x32_bf16 v[28:31], v[158:161], v[206:209], v[28:31]
	v_mfma_f32_16x16x32_bf16 v[24:27], v[166:169], v[206:209], v[24:27]
	v_mfma_f32_16x16x32_bf16 v[12:15], v[158:161], v[214:217], v[12:15]
	v_mfma_f32_16x16x32_bf16 v[8:11], v[166:169], v[214:217], v[8:11]
	v_mfma_f32_16x16x32_bf16 v[52:55], v[170:173], v[186:189], v[52:55]
	v_mfma_f32_16x16x32_bf16 v[48:51], v[178:181], v[186:189], v[48:51]
	v_mfma_f32_16x16x32_bf16 v[36:39], v[170:173], v[194:197], v[36:39]
	v_mfma_f32_16x16x32_bf16 v[32:35], v[178:181], v[194:197], v[32:35]
	v_mfma_f32_16x16x32_bf16 v[20:23], v[170:173], v[202:205], v[20:23]
	v_mfma_f32_16x16x32_bf16 v[16:19], v[178:181], v[202:205], v[16:19]
	v_mfma_f32_16x16x32_bf16 v[4:7], v[170:173], v[210:213], v[4:7]
	v_mfma_f32_16x16x32_bf16 v[0:3], v[178:181], v[210:213], v[0:3]
	v_mfma_f32_16x16x32_bf16 v[52:55], v[174:177], v[190:193], v[52:55]
	v_mfma_f32_16x16x32_bf16 v[48:51], v[182:185], v[190:193], v[48:51]
	v_mfma_f32_16x16x32_bf16 v[36:39], v[174:177], v[198:201], v[36:39]
	v_mfma_f32_16x16x32_bf16 v[32:35], v[182:185], v[198:201], v[32:35]
	v_mfma_f32_16x16x32_bf16 v[20:23], v[174:177], v[206:209], v[20:23]
	v_mfma_f32_16x16x32_bf16 v[16:19], v[182:185], v[206:209], v[16:19]
	v_mfma_f32_16x16x32_bf16 v[4:7], v[174:177], v[214:217], v[4:7]
	v_mfma_f32_16x16x32_bf16 v[0:3], v[182:185], v[214:217], v[0:3]
	s_setprio 0
	s_barrier
	s_add_i32 s64, 0, 0x18000
	v_add_u32_e32 v157, s64, v152
	s_add_i32 s65, 0, 0x1c000
	ds_read_b128 v[146:149], v157
	ds_read_b128 v[158:161], v157 offset:1024
	ds_read_b128 v[162:165], v157 offset:2048
	ds_read_b128 v[166:169], v157 offset:3072
	v_add_u32_e32 v157, s65, v152
	ds_read_b128 v[170:173], v157
	ds_read_b128 v[174:177], v157 offset:1024
	ds_read_b128 v[178:181], v157 offset:2048
	ds_read_b128 v[182:185], v157 offset:3072
	s_add_u32 s38, s38, 0x160000
	s_addc_u32 s39, s39, 0
	s_mov_b32 m0, s45
	v_lshl_add_u64 v[226:227], s[38:39], 0, v[128:129]
	ds_read_b128 v[186:189], v155 offset:32768
	ds_read_b128 v[190:193], v155 offset:33792
	ds_read_b128 v[194:197], v155 offset:34816
	ds_read_b128 v[198:201], v155 offset:35840
	ds_read_b128 v[202:205], v155 offset:36864
	ds_read_b128 v[206:209], v155 offset:37888
	ds_read_b128 v[210:213], v155 offset:38912
	ds_read_b128 v[214:217], v155 offset:39936
	global_load_lds_dwordx4 v[226:227], off
	v_lshl_add_u64 v[226:227], s[38:39], 0, v[132:133]
	s_mov_b32 m0, s46
	s_nop 0
	global_load_lds_dwordx4 v[226:227], off
	s_waitcnt vmcnt(8)
	s_waitcnt lgkmcnt(0)
	s_barrier
	s_setprio 1
	s_waitcnt lgkmcnt(0)
	v_mfma_f32_16x16x32_bf16 v[124:127], v[146:149], v[186:189], v[124:127]
	v_mfma_f32_16x16x32_bf16 v[120:123], v[162:165], v[186:189], v[120:123]
	v_mfma_f32_16x16x32_bf16 v[108:111], v[146:149], v[194:197], v[108:111]
	v_mfma_f32_16x16x32_bf16 v[104:107], v[162:165], v[194:197], v[104:107]
	v_mfma_f32_16x16x32_bf16 v[92:95], v[146:149], v[202:205], v[92:95]
	v_mfma_f32_16x16x32_bf16 v[88:91], v[162:165], v[202:205], v[88:91]
	v_mfma_f32_16x16x32_bf16 v[76:79], v[146:149], v[210:213], v[76:79]
	v_mfma_f32_16x16x32_bf16 v[72:75], v[162:165], v[210:213], v[72:75]
	v_mfma_f32_16x16x32_bf16 v[124:127], v[158:161], v[190:193], v[124:127]
	v_mfma_f32_16x16x32_bf16 v[120:123], v[166:169], v[190:193], v[120:123]
	v_mfma_f32_16x16x32_bf16 v[108:111], v[158:161], v[198:201], v[108:111]
	v_mfma_f32_16x16x32_bf16 v[104:107], v[166:169], v[198:201], v[104:107]
	v_mfma_f32_16x16x32_bf16 v[92:95], v[158:161], v[206:209], v[92:95]
	v_mfma_f32_16x16x32_bf16 v[88:91], v[166:169], v[206:209], v[88:91]
	v_mfma_f32_16x16x32_bf16 v[76:79], v[158:161], v[214:217], v[76:79]
	v_mfma_f32_16x16x32_bf16 v[72:75], v[166:169], v[214:217], v[72:75]
	v_mfma_f32_16x16x32_bf16 v[116:119], v[170:173], v[186:189], v[116:119]
	v_mfma_f32_16x16x32_bf16 v[112:115], v[178:181], v[186:189], v[112:115]
	v_mfma_f32_16x16x32_bf16 v[100:103], v[170:173], v[194:197], v[100:103]
	v_mfma_f32_16x16x32_bf16 v[96:99], v[178:181], v[194:197], v[96:99]
	v_mfma_f32_16x16x32_bf16 v[84:87], v[170:173], v[202:205], v[84:87]
	v_mfma_f32_16x16x32_bf16 v[80:83], v[178:181], v[202:205], v[80:83]
	v_mfma_f32_16x16x32_bf16 v[68:71], v[170:173], v[210:213], v[68:71]
	v_mfma_f32_16x16x32_bf16 v[64:67], v[178:181], v[210:213], v[64:67]
	v_mfma_f32_16x16x32_bf16 v[116:119], v[174:177], v[190:193], v[116:119]
	v_mfma_f32_16x16x32_bf16 v[112:115], v[182:185], v[190:193], v[112:115]
	v_mfma_f32_16x16x32_bf16 v[100:103], v[174:177], v[198:201], v[100:103]
	v_mfma_f32_16x16x32_bf16 v[96:99], v[182:185], v[198:201], v[96:99]
	v_mfma_f32_16x16x32_bf16 v[84:87], v[174:177], v[206:209], v[84:87]
	v_mfma_f32_16x16x32_bf16 v[80:83], v[182:185], v[206:209], v[80:83]
	v_mfma_f32_16x16x32_bf16 v[68:71], v[174:177], v[214:217], v[68:71]
	v_mfma_f32_16x16x32_bf16 v[64:67], v[182:185], v[214:217], v[64:67]
	s_setprio 0
	s_barrier
; #define PG8_STAGE(bufoff, gbase, voff) do { _Pragma("unroll") for (int _i = 0; _i < 2; ++_i) \
;         __builtin_amdgcn_global_load_lds((const unsigned*)((const char*)(gbase) + (voff)[_i]), (PG8_LAS unsigned*)(lds + (bufoff) + ldsw + _i * 8192), 16, 0, 0); } while (0)
; #define PG8_LDA(dst, b, h) do { _Pragma("unroll") for (int m = 0; m < 4; ++m) _Pragma("unroll") for (int k = 0; k < 2; ++k) dst[m][k] = *(const PG8_LAS bf16x8*)(lds + PG8_SA(b, h) + aoff + m * 2048 + k * 1024); } while (0)
; #define PG8_MMA(ai, bj, At, Bt) do { __builtin_amdgcn_s_setprio(1); _Pragma("unroll") for (int m = 0; m < 4; ++m) _Pragma("unroll") for (int n = 0; n < 2; ++n) _Pragma("unroll") for (int k = 0; k < 2; ++k) \
;         acc[ai][bj][m][n] = __builtin_amdgcn_mfma_f32_16x16x32_bf16(Bt[n][k], At[m][k], acc[ai][bj][m][n], 0, 0, 0); __builtin_amdgcn_s_setprio(0); } while (0)
; #define PG8_WAIT_V(n) asm volatile("s_waitcnt vmcnt(" #n ")" ::: "memory")
; #define PG8_WAIT_L(n) asm volatile("s_waitcnt lgkmcnt(" #n ")" ::: "memory")
; #define PG8_BAR __builtin_amdgcn_s_barrier()
; #define PG8_SCHED __builtin_amdgcn_sched_barrier(0)
; template <class Epi, class Sched, bool ALIGN_EPI = false, bool SP2 = false>
; __device__ __forceinline__ void gemm_phase(PG8_LAS unsigned char* lds, const Gemm g, const Sched& S, const Epi& E) {
;     ...
;             PG8_LDA(At, 1, 1); PG8_STAGE(PG8_SB(1, 0), b3, voffB); PG8_STAGE(PG8_SB(1, 1), b3 + hstep, voffB); PG8_STAGE(PG8_SA(1, 0), a3, voffA);
;             PG8_WAIT_V(8); PG8_WAIT_L(0); PG8_BAR; PG8_MMA(1, 0, At, B0); PG8_MMA(1, 1, At, B1); PG8_BAR; PG8_SCHED;
;     ...
;         if constexpr (ALIGN_EPI) { if (wr == 0) PG8_BAR; }
	s_add_i32 s38, s64, s42
	v_lshl_add_u64 v[218:219], v[218:219], 0, s[16:17]
	s_mov_b32 m0, s38
	ds_read_b128 v[186:189], v155 offset:49152
	ds_read_b128 v[190:193], v155 offset:50176
	ds_read_b128 v[194:197], v155 offset:51200
	ds_read_b128 v[198:201], v155 offset:52224
	ds_read_b128 v[202:205], v155 offset:53248
	ds_read_b128 v[206:209], v155 offset:54272
	ds_read_b128 v[210:213], v155 offset:55296
	ds_read_b128 v[214:217], v155 offset:56320
	global_load_lds_dwordx4 v[218:219], off
	s_add_i32 m0, s38, 0x2000
	s_add_u32 s36, s36, 0x160080
	v_lshl_add_u64 v[218:219], v[220:221], 0, s[16:17]
	s_addc_u32 s37, s37, 0
	s_add_i32 s38, s65, s42
	global_load_lds_dwordx4 v[218:219], off
	v_lshl_add_u64 v[218:219], s[36:37], 0, v[130:131]
	s_mov_b32 m0, s38
	s_nop 0
	global_load_lds_dwordx4 v[218:219], off
	v_lshl_add_u64 v[218:219], s[36:37], 0, v[134:135]
	s_add_i32 m0, s38, 0x2000
	s_nop 0
	global_load_lds_dwordx4 v[218:219], off
	v_lshl_add_u64 v[218:219], v[222:223], 0, s[16:17]
	s_mov_b32 m0, s52
	s_nop 0
	global_load_lds_dwordx4 v[218:219], off
	v_lshl_add_u64 v[218:219], v[224:225], 0, s[16:17]
	s_mov_b32 m0, s53
	s_nop 0
	global_load_lds_dwordx4 v[218:219], off
	s_waitcnt vmcnt(8)
	s_waitcnt lgkmcnt(0)
	s_barrier
	s_setprio 1
	s_waitcnt lgkmcnt(0)
	v_mfma_f32_16x16x32_bf16 v[60:63], v[146:149], v[186:189], v[60:63]
	v_mfma_f32_16x16x32_bf16 v[56:59], v[162:165], v[186:189], v[56:59]
	v_mfma_f32_16x16x32_bf16 v[44:47], v[146:149], v[194:197], v[44:47]
	v_mfma_f32_16x16x32_bf16 v[40:43], v[162:165], v[194:197], v[40:43]
	v_mfma_f32_16x16x32_bf16 v[28:31], v[146:149], v[202:205], v[28:31]
	v_mfma_f32_16x16x32_bf16 v[24:27], v[162:165], v[202:205], v[24:27]
	v_mfma_f32_16x16x32_bf16 v[12:15], v[146:149], v[210:213], v[12:15]
	v_mfma_f32_16x16x32_bf16 v[8:11], v[162:165], v[210:213], v[8:11]
	v_mfma_f32_16x16x32_bf16 v[60:63], v[158:161], v[190:193], v[60:63]
	v_mfma_f32_16x16x32_bf16 v[56:59], v[166:169], v[190:193], v[56:59]
	v_mfma_f32_16x16x32_bf16 v[44:47], v[158:161], v[198:201], v[44:47]
	v_mfma_f32_16x16x32_bf16 v[40:43], v[166:169], v[198:201], v[40:43]
	v_mfma_f32_16x16x32_bf16 v[28:31], v[158:161], v[206:209], v[28:31]
	v_mfma_f32_16x16x32_bf16 v[24:27], v[166:169], v[206:209], v[24:27]
	v_mfma_f32_16x16x32_bf16 v[12:15], v[158:161], v[214:217], v[12:15]
	v_mfma_f32_16x16x32_bf16 v[8:11], v[166:169], v[214:217], v[8:11]
	v_mfma_f32_16x16x32_bf16 v[52:55], v[170:173], v[186:189], v[52:55]
	v_mfma_f32_16x16x32_bf16 v[48:51], v[178:181], v[186:189], v[48:51]
	v_mfma_f32_16x16x32_bf16 v[36:39], v[170:173], v[194:197], v[36:39]
	v_mfma_f32_16x16x32_bf16 v[32:35], v[178:181], v[194:197], v[32:35]
	v_mfma_f32_16x16x32_bf16 v[20:23], v[170:173], v[202:205], v[20:23]
	v_mfma_f32_16x16x32_bf16 v[16:19], v[178:181], v[202:205], v[16:19]
	v_mfma_f32_16x16x32_bf16 v[4:7], v[170:173], v[210:213], v[4:7]
	v_mfma_f32_16x16x32_bf16 v[0:3], v[178:181], v[210:213], v[0:3]
	v_mfma_f32_16x16x32_bf16 v[52:55], v[174:177], v[190:193], v[52:55]
	v_mfma_f32_16x16x32_bf16 v[48:51], v[182:185], v[190:193], v[48:51]
	v_mfma_f32_16x16x32_bf16 v[36:39], v[174:177], v[198:201], v[36:39]
	v_mfma_f32_16x16x32_bf16 v[32:35], v[182:185], v[198:201], v[32:35]
	v_mfma_f32_16x16x32_bf16 v[20:23], v[174:177], v[206:209], v[20:23]
	v_mfma_f32_16x16x32_bf16 v[16:19], v[182:185], v[206:209], v[16:19]
	v_mfma_f32_16x16x32_bf16 v[4:7], v[174:177], v[214:217], v[4:7]
	v_mfma_f32_16x16x32_bf16 v[0:3], v[182:185], v[214:217], v[0:3]
	s_setprio 0
	s_barrier
	s_add_i32 s63, s63, 2
	s_add_u32 s22, s22, 0x100
	s_addc_u32 s23, s23, 0
	s_add_u32 s61, s61, 0x100
	s_addc_u32 s62, s62, 0
	s_cmpk_gt_u32 s63, 0x55
	s_cbranch_scc0 .LBB0_1924
	s_and_b64 vcc, exec, s[18:19]
	s_cbranch_vccz .LBB0_1927
	s_barrier
